# v34 plus ksc scale loads of the weight-conversion loop issued as one batch instead of four serialized round trips
# speedup vs baseline: 1.0034x; 1.0034x over previous
; __device__ __forceinline__ void transpose_item(const float* __restrict__ W, int K, int N, bf16* __restrict__ WT, const float* __restrict__ ksc, int mode, int row_off, int item, int lane) {
;     const int nblk = N / 64, kb = item / nblk, nb = item % nblk, k0 = 64 * kb, n = 64 * nb + lane;
;     const float* src = W + (size_t)k0 * N + n;
;     float v[64];
; #pragma unroll
;     for (int i = 0; i < 64; ++i) v[i] = __builtin_nontemporal_load(src + (size_t)i * N);
; __device__ __forceinline__ void convert_layer(ArgsP a, int L, int first, int stride, int lane) {
;     ...
;         else if (r < I_IN + I_OUT + I_GU) transpose_item(a->in[18] + (size_t)L * D * GU, D, GU, WGU + (size_t)L * GU * D, a->in[17] + L * D, 2, 0, r - I_IN - I_OUT, lane);
.LBB0_93:
	s_andn2_b64 vcc, exec, s[4:5]
	s_cbranch_vccnz .LBB0_101
	s_add_i32 s24, s1, 0xfc80
	s_and_b32 s91, s24, 0xffff
	s_mul_i32 s91, s91, 0xba2f
	s_load_dwordx4 s[4:7], s[12:13], 0x88
	s_lshr_b32 s93, s91, 16
	s_lshr_b32 s91, s91, 22
	s_mulk_i32 s91, 0x58
	s_sub_i32 s24, s24, s91
	s_and_b32 s92, s24, 0xffff
	s_and_b32 s24, s93, 0xffc0
	s_lshl_b32 s91, s92, 6
	s_mul_i32 s93, s24, 0x5800
	v_or_b32_e32 v78, s91, v80
	s_waitcnt lgkmcnt(0)
	s_add_u32 s6, s6, s93
	s_addc_u32 s7, s7, 0
	v_lshlrev_b32_e32 v12, 2, v78
	v_lshl_add_u64 v[0:1], s[6:7], 0, v[12:13]
	s_mov_b32 s6, 0x1600000
	v_add_co_u32_e32 v2, vcc, s6, v0
	s_mov_b32 s6, 0x1605000
	s_nop 0
	v_addc_co_u32_e32 v3, vcc, 0, v1, vcc
	global_load_dword v16, v[2:3], off nt
	v_add_co_u32_e32 v2, vcc, s6, v0
	s_mov_b32 s6, 0x160b000
	s_nop 0
	v_addc_co_u32_e32 v3, vcc, 0, v1, vcc
	global_load_dword v14, v[2:3], off offset:2048 nt
	v_add_co_u32_e32 v2, vcc, s6, v0
	s_mov_b32 s6, 0x1610000
	s_nop 0
	v_addc_co_u32_e32 v3, vcc, 0, v1, vcc
	global_load_dword v17, v[2:3], off nt
	v_add_co_u32_e32 v2, vcc, s6, v0
	s_mov_b32 s6, 0x1616000
	s_nop 0
	v_addc_co_u32_e32 v3, vcc, 0, v1, vcc
	global_load_dword v15, v[2:3], off offset:2048 nt
	v_add_co_u32_e32 v2, vcc, s6, v0
	s_mov_b32 s6, 0x161b000
	s_nop 0
	v_addc_co_u32_e32 v3, vcc, 0, v1, vcc
	global_load_dword v20, v[2:3], off nt
	v_add_co_u32_e32 v2, vcc, s6, v0
	s_mov_b32 s6, 0x1621000
	s_nop 0
	v_addc_co_u32_e32 v3, vcc, 0, v1, vcc
	global_load_dword v18, v[2:3], off offset:2048 nt
	v_add_co_u32_e32 v2, vcc, s6, v0
	s_mov_b32 s6, 0x1626000
	s_nop 0
	v_addc_co_u32_e32 v3, vcc, 0, v1, vcc
	global_load_dword v21, v[2:3], off nt
	v_add_co_u32_e32 v2, vcc, s6, v0
	s_mov_b32 s6, 0x162c000
	s_nop 0
	v_addc_co_u32_e32 v3, vcc, 0, v1, vcc
	global_load_dword v19, v[2:3], off offset:2048 nt
	v_add_co_u32_e32 v2, vcc, s6, v0
	s_mov_b32 s6, 0x1631000
	s_nop 0
	v_addc_co_u32_e32 v3, vcc, 0, v1, vcc
	global_load_dword v24, v[2:3], off nt
	v_add_co_u32_e32 v2, vcc, s6, v0
	s_mov_b32 s6, 0x1637000
	s_nop 0
	v_addc_co_u32_e32 v3, vcc, 0, v1, vcc
	global_load_dword v22, v[2:3], off offset:2048 nt
	v_add_co_u32_e32 v2, vcc, s6, v0
	s_mov_b32 s6, 0x163c000
	s_nop 0
	v_addc_co_u32_e32 v3, vcc, 0, v1, vcc
	global_load_dword v25, v[2:3], off nt
	v_add_co_u32_e32 v2, vcc, s6, v0
	s_mov_b32 s6, 0x1642000
	s_nop 0
	v_addc_co_u32_e32 v3, vcc, 0, v1, vcc
	global_load_dword v23, v[2:3], off offset:2048 nt
	v_add_co_u32_e32 v2, vcc, s6, v0
	s_mov_b32 s6, 0x1647000
	s_nop 0
	v_addc_co_u32_e32 v3, vcc, 0, v1, vcc
	global_load_dword v28, v[2:3], off nt
	v_add_co_u32_e32 v2, vcc, s6, v0
	s_mov_b32 s6, 0x164d000
	s_nop 0
	v_addc_co_u32_e32 v3, vcc, 0, v1, vcc
	global_load_dword v26, v[2:3], off offset:2048 nt
	v_add_co_u32_e32 v2, vcc, s6, v0
	s_mov_b32 s6, 0x1652000
	s_nop 0
	v_addc_co_u32_e32 v3, vcc, 0, v1, vcc
	global_load_dword v29, v[2:3], off nt
	v_add_co_u32_e32 v2, vcc, s6, v0
	s_mov_b32 s6, 0x1658000
	s_nop 0
	v_addc_co_u32_e32 v3, vcc, 0, v1, vcc
	global_load_dword v27, v[2:3], off offset:2048 nt
	v_add_co_u32_e32 v2, vcc, s6, v0
	s_mov_b32 s6, 0x165d000
	s_nop 0
	v_addc_co_u32_e32 v3, vcc, 0, v1, vcc
	global_load_dword v32, v[2:3], off nt
	v_add_co_u32_e32 v2, vcc, s6, v0
	s_mov_b32 s6, 0x1663000
	s_nop 0
	v_addc_co_u32_e32 v3, vcc, 0, v1, vcc
	global_load_dword v30, v[2:3], off offset:2048 nt
	v_add_co_u32_e32 v2, vcc, s6, v0
	s_mov_b32 s6, 0x1668000
	s_nop 0
	v_addc_co_u32_e32 v3, vcc, 0, v1, vcc
	global_load_dword v33, v[2:3], off nt
	v_add_co_u32_e32 v2, vcc, s6, v0
	s_mov_b32 s6, 0x166e000
	s_nop 0
	v_addc_co_u32_e32 v3, vcc, 0, v1, vcc
	global_load_dword v31, v[2:3], off offset:2048 nt
	v_add_co_u32_e32 v2, vcc, s6, v0
	s_mov_b32 s6, 0x1673000
	s_nop 0
	v_addc_co_u32_e32 v3, vcc, 0, v1, vcc
	global_load_dword v36, v[2:3], off nt
	v_add_co_u32_e32 v2, vcc, s6, v0
	s_mov_b32 s6, 0x1679000
	s_nop 0
	v_addc_co_u32_e32 v3, vcc, 0, v1, vcc
	global_load_dword v34, v[2:3], off offset:2048 nt
	v_add_co_u32_e32 v2, vcc, s6, v0
	s_mov_b32 s6, 0x167e000
	s_nop 0
	v_addc_co_u32_e32 v3, vcc, 0, v1, vcc
	global_load_dword v37, v[2:3], off nt
	v_add_co_u32_e32 v2, vcc, s6, v0
	s_mov_b32 s6, 0x1684000
	s_nop 0
	v_addc_co_u32_e32 v3, vcc, 0, v1, vcc
	global_load_dword v35, v[2:3], off offset:2048 nt
	v_add_co_u32_e32 v2, vcc, s6, v0
	s_mov_b32 s6, 0x1689000
	s_nop 0
	v_addc_co_u32_e32 v3, vcc, 0, v1, vcc
	global_load_dword v40, v[2:3], off nt
	v_add_co_u32_e32 v2, vcc, s6, v0
	s_mov_b32 s6, 0x168f000
	s_nop 0
	v_addc_co_u32_e32 v3, vcc, 0, v1, vcc
	global_load_dword v38, v[2:3], off offset:2048 nt
	v_add_co_u32_e32 v2, vcc, s6, v0
	s_mov_b32 s6, 0x1694000
	s_nop 0
	v_addc_co_u32_e32 v3, vcc, 0, v1, vcc
	global_load_dword v41, v[2:3], off nt
	v_add_co_u32_e32 v2, vcc, s6, v0
	s_mov_b32 s6, 0x169a000
	s_nop 0
	v_addc_co_u32_e32 v3, vcc, 0, v1, vcc
	global_load_dword v39, v[2:3], off offset:2048 nt
	v_add_co_u32_e32 v2, vcc, s6, v0
	s_mov_b32 s6, 0x169f000
	s_nop 0
	v_addc_co_u32_e32 v3, vcc, 0, v1, vcc
	global_load_dword v44, v[2:3], off nt
	v_add_co_u32_e32 v2, vcc, s6, v0
	s_mov_b32 s6, 0x16a5000
	s_nop 0
	v_addc_co_u32_e32 v3, vcc, 0, v1, vcc
	global_load_dword v42, v[2:3], off offset:2048 nt
	v_add_co_u32_e32 v2, vcc, s6, v0
	s_mov_b32 s6, 0x16aa000
	s_nop 0
	v_addc_co_u32_e32 v3, vcc, 0, v1, vcc
	global_load_dword v45, v[2:3], off nt
	v_add_co_u32_e32 v2, vcc, s6, v0
	s_mov_b32 s6, 0x16b0000
	s_nop 0
	v_addc_co_u32_e32 v3, vcc, 0, v1, vcc
	global_load_dword v43, v[2:3], off offset:2048 nt
	v_add_co_u32_e32 v2, vcc, s6, v0
	s_mov_b32 s6, 0x16b5000
	s_nop 0
	v_addc_co_u32_e32 v3, vcc, 0, v1, vcc
	global_load_dword v48, v[2:3], off nt
	v_add_co_u32_e32 v2, vcc, s6, v0
; __device__ __forceinline__ void transpose_item(const float* __restrict__ W, int K, int N, bf16* __restrict__ WT, const float* __restrict__ ksc, int mode, int row_off, int item, int lane) {
;     ...
;     for (int i = 0; i < 64; ++i) v[i] = __builtin_nontemporal_load(src + (size_t)i * N);
;     if (ksc) {
	s_mov_b32 s6, 0x16bb000
	s_nop 0
	v_addc_co_u32_e32 v3, vcc, 0, v1, vcc
	global_load_dword v46, v[2:3], off offset:2048 nt
	v_add_co_u32_e32 v2, vcc, s6, v0
	s_mov_b32 s6, 0x16c0000
	s_nop 0
	v_addc_co_u32_e32 v3, vcc, 0, v1, vcc
	global_load_dword v49, v[2:3], off nt
	v_add_co_u32_e32 v2, vcc, s6, v0
	s_mov_b32 s6, 0x16c6000
	s_nop 0
	v_addc_co_u32_e32 v3, vcc, 0, v1, vcc
	global_load_dword v47, v[2:3], off offset:2048 nt
	v_add_co_u32_e32 v2, vcc, s6, v0
	s_mov_b32 s6, 0x16cb000
	s_nop 0
	v_addc_co_u32_e32 v3, vcc, 0, v1, vcc
	global_load_dword v52, v[2:3], off nt
	v_add_co_u32_e32 v2, vcc, s6, v0
	s_mov_b32 s6, 0x16d1000
	s_nop 0
	v_addc_co_u32_e32 v3, vcc, 0, v1, vcc
	global_load_dword v50, v[2:3], off offset:2048 nt
	v_add_co_u32_e32 v2, vcc, s6, v0
	s_mov_b32 s6, 0x16d6000
	s_nop 0
	v_addc_co_u32_e32 v3, vcc, 0, v1, vcc
	global_load_dword v53, v[2:3], off nt
	v_add_co_u32_e32 v2, vcc, s6, v0
	s_mov_b32 s6, 0x16dc000
	s_nop 0
	v_addc_co_u32_e32 v3, vcc, 0, v1, vcc
	global_load_dword v51, v[2:3], off offset:2048 nt
	v_add_co_u32_e32 v2, vcc, s6, v0
	s_mov_b32 s6, 0x16e1000
	s_nop 0
	v_addc_co_u32_e32 v3, vcc, 0, v1, vcc
	global_load_dword v56, v[2:3], off nt
	v_add_co_u32_e32 v2, vcc, s6, v0
	s_mov_b32 s6, 0x16e7000
	s_nop 0
	v_addc_co_u32_e32 v3, vcc, 0, v1, vcc
	global_load_dword v54, v[2:3], off offset:2048 nt
	v_add_co_u32_e32 v2, vcc, s6, v0
	s_mov_b32 s6, 0x16ec000
	s_nop 0
	v_addc_co_u32_e32 v3, vcc, 0, v1, vcc
	global_load_dword v57, v[2:3], off nt
	v_add_co_u32_e32 v2, vcc, s6, v0
	s_mov_b32 s6, 0x16f2000
	s_nop 0
	v_addc_co_u32_e32 v3, vcc, 0, v1, vcc
	global_load_dword v55, v[2:3], off offset:2048 nt
	v_add_co_u32_e32 v2, vcc, s6, v0
	s_mov_b32 s6, 0x16f7000
	s_nop 0
	v_addc_co_u32_e32 v3, vcc, 0, v1, vcc
	global_load_dword v60, v[2:3], off nt
	v_add_co_u32_e32 v2, vcc, s6, v0
	s_mov_b32 s6, 0x16fd000
	s_nop 0
	v_addc_co_u32_e32 v3, vcc, 0, v1, vcc
	global_load_dword v58, v[2:3], off offset:2048 nt
	v_add_co_u32_e32 v2, vcc, s6, v0
	s_mov_b32 s6, 0x1702000
	s_nop 0
	v_addc_co_u32_e32 v3, vcc, 0, v1, vcc
	global_load_dword v61, v[2:3], off nt
	v_add_co_u32_e32 v2, vcc, s6, v0
	s_mov_b32 s6, 0x1708000
	s_nop 0
	v_addc_co_u32_e32 v3, vcc, 0, v1, vcc
	global_load_dword v59, v[2:3], off offset:2048 nt
	v_add_co_u32_e32 v2, vcc, s6, v0
	s_mov_b32 s6, 0x170d000
	s_nop 0
	v_addc_co_u32_e32 v3, vcc, 0, v1, vcc
	global_load_dword v64, v[2:3], off nt
	v_add_co_u32_e32 v2, vcc, s6, v0
	s_mov_b32 s6, 0x1713000
	s_nop 0
	v_addc_co_u32_e32 v3, vcc, 0, v1, vcc
	global_load_dword v62, v[2:3], off offset:2048 nt
	v_add_co_u32_e32 v2, vcc, s6, v0
	s_mov_b32 s6, 0x1718000
	s_nop 0
	v_addc_co_u32_e32 v3, vcc, 0, v1, vcc
	global_load_dword v65, v[2:3], off nt
	v_add_co_u32_e32 v2, vcc, s6, v0
	s_mov_b32 s6, 0x171e000
	s_nop 0
	v_addc_co_u32_e32 v3, vcc, 0, v1, vcc
	global_load_dword v63, v[2:3], off offset:2048 nt
	v_add_co_u32_e32 v2, vcc, s6, v0
	s_mov_b32 s6, 0x1723000
	s_nop 0
	v_addc_co_u32_e32 v3, vcc, 0, v1, vcc
	global_load_dword v68, v[2:3], off nt
	v_add_co_u32_e32 v2, vcc, s6, v0
	s_mov_b32 s6, 0x1729000
	s_nop 0
	v_addc_co_u32_e32 v3, vcc, 0, v1, vcc
	global_load_dword v66, v[2:3], off offset:2048 nt
	v_add_co_u32_e32 v2, vcc, s6, v0
	s_mov_b32 s6, 0x172e000
	s_nop 0
	v_addc_co_u32_e32 v3, vcc, 0, v1, vcc
	global_load_dword v69, v[2:3], off nt
	v_add_co_u32_e32 v2, vcc, s6, v0
	s_mov_b32 s6, 0x1734000
	s_nop 0
	v_addc_co_u32_e32 v3, vcc, 0, v1, vcc
	global_load_dword v67, v[2:3], off offset:2048 nt
	v_add_co_u32_e32 v2, vcc, s6, v0
	s_mov_b32 s6, 0x1739000
	s_nop 0
	v_addc_co_u32_e32 v3, vcc, 0, v1, vcc
	global_load_dword v70, v[2:3], off nt
	v_add_co_u32_e32 v2, vcc, s6, v0
	s_mov_b32 s6, 0x173f000
	s_nop 0
	v_addc_co_u32_e32 v3, vcc, 0, v1, vcc
	global_load_dword v72, v[2:3], off offset:2048 nt
	v_add_co_u32_e32 v2, vcc, s6, v0
	s_mov_b32 s6, 0x1744000
	s_nop 0
	v_addc_co_u32_e32 v3, vcc, 0, v1, vcc
	global_load_dword v71, v[2:3], off nt
	v_add_co_u32_e32 v2, vcc, s6, v0
	s_mov_b32 s6, 0x174a000
	s_nop 0
	v_addc_co_u32_e32 v3, vcc, 0, v1, vcc
	global_load_dword v73, v[2:3], off offset:2048 nt
	v_add_co_u32_e32 v2, vcc, s6, v0
	s_mov_b32 s6, 0x174f000
	s_nop 0
	v_addc_co_u32_e32 v3, vcc, 0, v1, vcc
	global_load_dword v74, v[2:3], off nt
	v_add_co_u32_e32 v2, vcc, s6, v0
	s_mov_b32 s6, 0x1755000
	s_nop 0
	v_addc_co_u32_e32 v3, vcc, 0, v1, vcc
	global_load_dword v75, v[2:3], off offset:2048 nt
	v_add_co_u32_e32 v2, vcc, s6, v0
	s_mov_b32 s6, 0x175a000
	s_nop 0
	v_addc_co_u32_e32 v3, vcc, 0, v1, vcc
	v_add_co_u32_e32 v0, vcc, s6, v0
	global_load_dword v76, v[2:3], off nt
	s_nop 0
	v_addc_co_u32_e32 v1, vcc, 0, v1, vcc
	global_load_dword v77, v[0:1], off offset:2048 nt
	s_cmp_eq_u64 s[4:5], 0
	s_cbranch_scc1 .LBB0_96
; __device__ __forceinline__ void transpose_item(const float* __restrict__ W, int K, int N, bf16* __restrict__ WT, const float* __restrict__ ksc, int mode, int row_off, int item, int lane) {
;     ...
;     if (ksc) {
; #pragma unroll
;         for (int i = 0; i < 64; ++i) v[i] *= ksc[k0 + i];
;     }
	s_lshl_b32 s6, s24, 2
	s_add_u32 s6, s4, s6
	s_addc_u32 s7, s5, 0
	s_add_u32 s4, s6, 0x1000
	s_addc_u32 s5, s7, 0
	global_load_dwordx4 v[0:3], v13, s[4:5] offset:48
	global_load_dwordx4 v[4:7], v13, s[4:5] offset:32
	global_load_dwordx4 v[8:11], v13, s[4:5] offset:16
	global_load_dwordx4 v[86:89], v83, s[6:7]
	global_load_dwordx4 v[160:163], v13, s[4:5] offset:112
	global_load_dwordx4 v[164:167], v13, s[4:5] offset:96
	global_load_dwordx4 v[168:171], v13, s[4:5] offset:80
	global_load_dwordx4 v[172:175], v13, s[4:5] offset:64
	global_load_dwordx4 v[176:179], v13, s[4:5] offset:176
	global_load_dwordx4 v[180:183], v13, s[4:5] offset:160
	global_load_dwordx4 v[184:187], v13, s[4:5] offset:144
	global_load_dwordx4 v[188:191], v13, s[4:5] offset:128
	global_load_dwordx4 v[208:211], v13, s[4:5] offset:224
	global_load_dwordx4 v[212:215], v13, s[4:5] offset:208
	global_load_dwordx4 v[216:219], v13, s[4:5] offset:192
	global_load_dwordx4 v[220:223], v13, s[4:5] offset:240
	s_waitcnt vmcnt(0)
	v_mov_b32_e32 v90, v86
	v_mov_b32_e32 v91, v88
	v_mov_b32_e32 v88, v87
	v_mov_b32_e32 v86, v8
	v_mov_b32_e32 v87, v10
	v_mov_b32_e32 v10, v9
	v_mov_b32_e32 v8, v4
	v_mov_b32_e32 v9, v6
	v_mov_b32_e32 v6, v5
	v_mov_b32_e32 v4, v0
	v_mov_b32_e32 v5, v2
	v_mov_b32_e32 v2, v1
	v_pk_mul_f32 v[14:15], v[14:15], v[88:89]
	v_pk_mul_f32 v[20:21], v[20:21], v[86:87]
	v_pk_mul_f32 v[18:19], v[18:19], v[10:11]
	v_pk_mul_f32 v[24:25], v[24:25], v[8:9]
	v_pk_mul_f32 v[22:23], v[22:23], v[6:7]
	v_pk_mul_f32 v[28:29], v[28:29], v[4:5]
	v_pk_mul_f32 v[26:27], v[26:27], v[2:3]
	v_mov_b32_e32 v0, v160
	v_mov_b32_e32 v1, v161
	v_mov_b32_e32 v2, v162
	v_mov_b32_e32 v3, v163
	v_mov_b32_e32 v4, v164
	v_mov_b32_e32 v5, v165
	v_mov_b32_e32 v6, v166
	v_mov_b32_e32 v7, v167
	v_mov_b32_e32 v8, v168
	v_mov_b32_e32 v9, v169
	v_mov_b32_e32 v10, v170
	v_mov_b32_e32 v11, v171
	v_mov_b32_e32 v86, v172
	v_mov_b32_e32 v87, v173
	v_mov_b32_e32 v88, v174
	v_mov_b32_e32 v89, v175
	v_pk_mul_f32 v[16:17], v[16:17], v[90:91]
	s_waitcnt vmcnt(0)
	v_mov_b32_e32 v90, v86
	v_mov_b32_e32 v91, v88
	v_mov_b32_e32 v88, v87
	v_mov_b32_e32 v86, v8
	v_mov_b32_e32 v87, v10
	v_mov_b32_e32 v10, v9
	v_mov_b32_e32 v8, v4
	v_mov_b32_e32 v9, v6
	v_mov_b32_e32 v6, v5
	v_mov_b32_e32 v4, v0
	v_mov_b32_e32 v5, v2
	v_mov_b32_e32 v2, v1
	v_pk_mul_f32 v[30:31], v[30:31], v[88:89]
	v_pk_mul_f32 v[36:37], v[36:37], v[86:87]
	v_pk_mul_f32 v[34:35], v[34:35], v[10:11]
	v_pk_mul_f32 v[40:41], v[40:41], v[8:9]
	v_pk_mul_f32 v[38:39], v[38:39], v[6:7]
	v_pk_mul_f32 v[44:45], v[44:45], v[4:5]
	v_pk_mul_f32 v[42:43], v[42:43], v[2:3]
	v_mov_b32_e32 v0, v176
	v_mov_b32_e32 v1, v177
	v_mov_b32_e32 v2, v178
	v_mov_b32_e32 v3, v179
	v_mov_b32_e32 v4, v180
	v_mov_b32_e32 v5, v181
	v_mov_b32_e32 v6, v182
	v_mov_b32_e32 v7, v183
	v_mov_b32_e32 v8, v184
	v_mov_b32_e32 v9, v185
	v_mov_b32_e32 v10, v186
	v_mov_b32_e32 v11, v187
	v_mov_b32_e32 v86, v188
	v_mov_b32_e32 v87, v189
	v_mov_b32_e32 v88, v190
	v_mov_b32_e32 v89, v191
	v_pk_mul_f32 v[32:33], v[32:33], v[90:91]
	s_waitcnt vmcnt(0)
	v_mov_b32_e32 v90, v86
	v_mov_b32_e32 v91, v88
	v_mov_b32_e32 v88, v87
	v_mov_b32_e32 v86, v8
	v_mov_b32_e32 v87, v10
	v_mov_b32_e32 v10, v9
	v_mov_b32_e32 v8, v4
	v_mov_b32_e32 v9, v6
	v_mov_b32_e32 v6, v5
	v_mov_b32_e32 v4, v0
	v_mov_b32_e32 v5, v2
	v_mov_b32_e32 v2, v1
	v_pk_mul_f32 v[46:47], v[46:47], v[88:89]
	v_pk_mul_f32 v[52:53], v[52:53], v[86:87]
	v_pk_mul_f32 v[50:51], v[50:51], v[10:11]
	v_pk_mul_f32 v[56:57], v[56:57], v[8:9]
	v_pk_mul_f32 v[54:55], v[54:55], v[6:7]
	v_pk_mul_f32 v[60:61], v[60:61], v[4:5]
	v_pk_mul_f32 v[58:59], v[58:59], v[2:3]
	v_mov_b32_e32 v0, v208
	v_mov_b32_e32 v1, v209
	v_mov_b32_e32 v2, v210
	v_mov_b32_e32 v3, v211
	v_mov_b32_e32 v4, v212
	v_mov_b32_e32 v5, v213
	v_mov_b32_e32 v6, v214
	v_mov_b32_e32 v7, v215
	v_mov_b32_e32 v86, v216
	v_mov_b32_e32 v87, v217
	v_mov_b32_e32 v88, v218
	v_mov_b32_e32 v89, v219
	v_mov_b32_e32 v8, v220
	v_mov_b32_e32 v9, v221
	v_mov_b32_e32 v10, v222
	v_mov_b32_e32 v11, v223
	v_pk_mul_f32 v[48:49], v[48:49], v[90:91]
	s_waitcnt vmcnt(1)
	v_mov_b32_e32 v90, v86
	v_mov_b32_e32 v91, v88
	v_mov_b32_e32 v88, v87
	v_mov_b32_e32 v86, v4
	v_mov_b32_e32 v87, v6
	v_mov_b32_e32 v6, v5
	v_mov_b32_e32 v4, v0
	v_mov_b32_e32 v5, v2
	v_mov_b32_e32 v2, v1
	v_pk_mul_f32 v[64:65], v[64:65], v[90:91]
	v_pk_mul_f32 v[62:63], v[62:63], v[88:89]
	v_pk_mul_f32 v[68:69], v[68:69], v[86:87]
	v_pk_mul_f32 v[66:67], v[66:67], v[6:7]
	v_pk_mul_f32 v[70:71], v[70:71], v[4:5]
	v_pk_mul_f32 v[72:73], v[72:73], v[2:3]
	s_waitcnt vmcnt(0)
	v_pk_mul_f32 v[74:75], v[74:75], v[8:9]
	v_pk_mul_f32 v[76:77], v[76:77], v[10:11]

; __device__ __forceinline__ void transpose_item(const float* __restrict__ W, int K, int N, bf16* __restrict__ WT, const float* __restrict__ ksc, int mode, int row_off, int item, int lane) {
;     const int nblk = N / 64, kb = item / nblk, nb = item % nblk, k0 = 64 * kb, n = 64 * nb + lane;
;     const float* src = W + (size_t)k0 * N + n;
;     float v[64];
; #pragma unroll
;     for (int i = 0; i < 64; ++i) v[i] = __builtin_nontemporal_load(src + (size_t)i * N);
; __device__ __forceinline__ void convert_layer(ArgsP a, int L, int first, int stride, int lane) {
;     ...
;         if (r < I_IN) transpose_item(a->in[3] + (size_t)L * D * INW, D, INW, WIN + (size_t)L * INW * D, a->in[2] + L * D, 1, 0, r, lane);
.LBB0_105:
	s_andn2_b64 vcc, exec, s[4:5]
	s_cbranch_vccnz .LBB0_88
	s_mul_hi_u32 s4, s1, 0xcccccccd
	s_lshr_b32 s91, s4, 5
	s_mul_i32 s4, s91, 0xa00
	v_subrev_u32_e32 v12, s4, v82
	s_load_dwordx4 s[4:7], s[12:13], 0x10
	s_lshl_b32 s24, s91, 6
	s_mul_i32 s91, s91, 0xa0000
	s_mul_hi_u32 s92, s24, 0x2800
	s_waitcnt lgkmcnt(0)
	s_add_u32 s6, s6, s91
	s_addc_u32 s7, s7, s92
	v_lshl_add_u64 v[66:67], v[12:13], 2, s[6:7]
	s_mov_b32 s6, 0xa00000
	v_add_co_u32_e32 v0, vcc, s6, v66
	s_mov_b32 s6, 0xa02000
	s_nop 0
	v_addc_co_u32_e32 v1, vcc, 0, v67, vcc
	v_add_co_u32_e32 v2, vcc, s6, v66
	s_mov_b32 s6, 0xa05000
	s_nop 0
	v_addc_co_u32_e32 v3, vcc, 0, v67, vcc
	global_load_dword v0, v[0:1], off nt
	s_cmp_eq_u64 s[4:5], 0
	global_load_dword v1, v[2:3], off offset:2048 nt
	v_add_co_u32_e32 v2, vcc, s6, v66
	s_mov_b32 s6, 0xa07000
	s_nop 0
	v_addc_co_u32_e32 v3, vcc, 0, v67, vcc
	v_add_co_u32_e32 v4, vcc, s6, v66
	s_mov_b32 s6, 0xa0a000
	s_nop 0
	v_addc_co_u32_e32 v5, vcc, 0, v67, vcc
	global_load_dword v2, v[2:3], off nt
	s_nop 0
	global_load_dword v3, v[4:5], off offset:2048 nt
	v_add_co_u32_e32 v4, vcc, s6, v66
	s_mov_b32 s6, 0xa0c000
	s_nop 0
	v_addc_co_u32_e32 v5, vcc, 0, v67, vcc
	v_add_co_u32_e32 v6, vcc, s6, v66
	global_load_dword v4, v[4:5], off nt
	s_nop 0
	v_addc_co_u32_e32 v7, vcc, 0, v67, vcc
	global_load_dword v5, v[6:7], off offset:2048 nt
	v_add_co_u32_e32 v6, vcc, s33, v66
	s_nop 1
	v_addc_co_u32_e32 v7, vcc, 0, v67, vcc
	v_add_co_u32_e32 v8, vcc, s34, v66
	global_load_dword v6, v[6:7], off nt
	s_nop 0
	v_addc_co_u32_e32 v9, vcc, 0, v67, vcc
	global_load_dword v7, v[8:9], off offset:2048 nt
	v_add_co_u32_e32 v8, vcc, s35, v66
	s_nop 1
	v_addc_co_u32_e32 v9, vcc, 0, v67, vcc
	v_add_co_u32_e32 v10, vcc, s36, v66
	global_load_dword v8, v[8:9], off nt
	s_nop 0
	v_addc_co_u32_e32 v11, vcc, 0, v67, vcc
	global_load_dword v9, v[10:11], off offset:2048 nt
	v_add_co_u32_e32 v10, vcc, s37, v66
	s_nop 1
	v_addc_co_u32_e32 v11, vcc, 0, v67, vcc
	v_add_co_u32_e32 v14, vcc, s38, v66
	global_load_dword v10, v[10:11], off nt
	s_nop 0
	v_addc_co_u32_e32 v15, vcc, 0, v67, vcc
	global_load_dword v11, v[14:15], off offset:2048 nt
	v_add_co_u32_e32 v14, vcc, s39, v66
	s_nop 1
	v_addc_co_u32_e32 v15, vcc, 0, v67, vcc
	v_add_co_u32_e32 v16, vcc, s40, v66
	global_load_dword v14, v[14:15], off nt
	s_nop 0
	v_addc_co_u32_e32 v17, vcc, 0, v67, vcc
	global_load_dword v15, v[16:17], off offset:2048 nt
	v_add_co_u32_e32 v16, vcc, s41, v66
	s_nop 1
	v_addc_co_u32_e32 v17, vcc, 0, v67, vcc
	v_add_co_u32_e32 v18, vcc, s42, v66
	global_load_dword v16, v[16:17], off nt
	s_nop 0
	v_addc_co_u32_e32 v19, vcc, 0, v67, vcc
	global_load_dword v17, v[18:19], off offset:2048 nt
	v_add_co_u32_e32 v18, vcc, s43, v66
	s_nop 1
	v_addc_co_u32_e32 v19, vcc, 0, v67, vcc
	v_add_co_u32_e32 v20, vcc, s44, v66
	global_load_dword v18, v[18:19], off nt
	s_nop 0
	v_addc_co_u32_e32 v21, vcc, 0, v67, vcc
	global_load_dword v19, v[20:21], off offset:2048 nt
	v_add_co_u32_e32 v20, vcc, s45, v66
	s_nop 1
	v_addc_co_u32_e32 v21, vcc, 0, v67, vcc
	v_add_co_u32_e32 v22, vcc, s46, v66
	global_load_dword v20, v[20:21], off nt
	s_nop 0
	v_addc_co_u32_e32 v23, vcc, 0, v67, vcc
	global_load_dword v21, v[22:23], off offset:2048 nt
	v_add_co_u32_e32 v22, vcc, s47, v66
	s_nop 1
	v_addc_co_u32_e32 v23, vcc, 0, v67, vcc
	v_add_co_u32_e32 v24, vcc, s48, v66
	global_load_dword v22, v[22:23], off nt
	s_nop 0
	v_addc_co_u32_e32 v25, vcc, 0, v67, vcc
	global_load_dword v23, v[24:25], off offset:2048 nt
	v_add_co_u32_e32 v24, vcc, s49, v66
	s_nop 1
	v_addc_co_u32_e32 v25, vcc, 0, v67, vcc
	v_add_co_u32_e32 v26, vcc, s50, v66
	global_load_dword v24, v[24:25], off nt
	s_nop 0
	v_addc_co_u32_e32 v27, vcc, 0, v67, vcc
	global_load_dword v25, v[26:27], off offset:2048 nt
	v_add_co_u32_e32 v26, vcc, s51, v66
	s_nop 1
	v_addc_co_u32_e32 v27, vcc, 0, v67, vcc
	v_add_co_u32_e32 v28, vcc, s52, v66
	global_load_dword v26, v[26:27], off nt
	s_nop 0
	v_addc_co_u32_e32 v29, vcc, 0, v67, vcc
	global_load_dword v27, v[28:29], off offset:2048 nt
	v_add_co_u32_e32 v28, vcc, s53, v66
	s_nop 1
	v_addc_co_u32_e32 v29, vcc, 0, v67, vcc
	v_add_co_u32_e32 v30, vcc, s54, v66
	global_load_dword v28, v[28:29], off nt
	s_nop 0
	v_addc_co_u32_e32 v31, vcc, 0, v67, vcc
	global_load_dword v29, v[30:31], off offset:2048 nt
	v_add_co_u32_e32 v30, vcc, s55, v66
	s_nop 1
	v_addc_co_u32_e32 v31, vcc, 0, v67, vcc
	v_add_co_u32_e32 v32, vcc, s56, v66
	global_load_dword v30, v[30:31], off nt
	s_nop 0
	v_addc_co_u32_e32 v33, vcc, 0, v67, vcc
	global_load_dword v31, v[32:33], off offset:2048 nt
	v_add_co_u32_e32 v32, vcc, s57, v66
	s_nop 1
	v_addc_co_u32_e32 v33, vcc, 0, v67, vcc
	v_add_co_u32_e32 v34, vcc, s58, v66
	global_load_dword v32, v[32:33], off nt
	s_nop 0
	v_addc_co_u32_e32 v35, vcc, 0, v67, vcc
	global_load_dword v33, v[34:35], off offset:2048 nt
	v_add_co_u32_e32 v34, vcc, s59, v66
	s_nop 1
	v_addc_co_u32_e32 v35, vcc, 0, v67, vcc
	v_add_co_u32_e32 v36, vcc, s60, v66
	global_load_dword v34, v[34:35], off nt
	s_nop 0
	v_addc_co_u32_e32 v37, vcc, 0, v67, vcc
	global_load_dword v35, v[36:37], off offset:2048 nt
	v_add_co_u32_e32 v36, vcc, s61, v66
	s_nop 1
	v_addc_co_u32_e32 v37, vcc, 0, v67, vcc
	v_add_co_u32_e32 v38, vcc, s62, v66
	global_load_dword v36, v[36:37], off nt
	s_nop 0
	v_addc_co_u32_e32 v39, vcc, 0, v67, vcc
	global_load_dword v37, v[38:39], off offset:2048 nt
	v_add_co_u32_e32 v38, vcc, s63, v66
	s_nop 1
	v_addc_co_u32_e32 v39, vcc, 0, v67, vcc
	v_add_co_u32_e32 v40, vcc, s64, v66
	global_load_dword v38, v[38:39], off nt
	s_nop 0
	v_addc_co_u32_e32 v41, vcc, 0, v67, vcc
	global_load_dword v39, v[40:41], off offset:2048 nt
; __device__ __forceinline__ void transpose_item(const float* __restrict__ W, int K, int N, bf16* __restrict__ WT, const float* __restrict__ ksc, int mode, int row_off, int item, int lane) {
;     ...
;     for (int i = 0; i < 64; ++i) v[i] = __builtin_nontemporal_load(src + (size_t)i * N);
;     if (ksc) {
	v_add_co_u32_e32 v40, vcc, s65, v66
	s_nop 1
	v_addc_co_u32_e32 v41, vcc, 0, v67, vcc
	v_add_co_u32_e32 v42, vcc, s66, v66
	global_load_dword v40, v[40:41], off nt
	s_nop 0
	v_addc_co_u32_e32 v43, vcc, 0, v67, vcc
	global_load_dword v41, v[42:43], off offset:2048 nt
	v_add_co_u32_e32 v42, vcc, s67, v66
	s_nop 1
	v_addc_co_u32_e32 v43, vcc, 0, v67, vcc
	v_add_co_u32_e32 v44, vcc, s68, v66
	global_load_dword v42, v[42:43], off nt
	s_nop 0
	v_addc_co_u32_e32 v45, vcc, 0, v67, vcc
	global_load_dword v43, v[44:45], off offset:2048 nt
	v_add_co_u32_e32 v44, vcc, s69, v66
	s_nop 1
	v_addc_co_u32_e32 v45, vcc, 0, v67, vcc
	v_add_co_u32_e32 v46, vcc, s70, v66
	global_load_dword v44, v[44:45], off nt
	s_nop 0
	v_addc_co_u32_e32 v47, vcc, 0, v67, vcc
	global_load_dword v45, v[46:47], off offset:2048 nt
	v_add_co_u32_e32 v46, vcc, s71, v66
	s_nop 1
	v_addc_co_u32_e32 v47, vcc, 0, v67, vcc
	v_add_co_u32_e32 v48, vcc, s72, v66
	global_load_dword v46, v[46:47], off nt
	s_nop 0
	v_addc_co_u32_e32 v49, vcc, 0, v67, vcc
	global_load_dword v47, v[48:49], off offset:2048 nt
	v_add_co_u32_e32 v48, vcc, s73, v66
	s_nop 1
	v_addc_co_u32_e32 v49, vcc, 0, v67, vcc
	v_add_co_u32_e32 v50, vcc, s74, v66
	global_load_dword v48, v[48:49], off nt
	s_nop 0
	v_addc_co_u32_e32 v51, vcc, 0, v67, vcc
	global_load_dword v49, v[50:51], off offset:2048 nt
	v_add_co_u32_e32 v50, vcc, s75, v66
	s_nop 1
	v_addc_co_u32_e32 v51, vcc, 0, v67, vcc
	v_add_co_u32_e32 v52, vcc, s76, v66
	global_load_dword v50, v[50:51], off nt
	s_nop 0
	v_addc_co_u32_e32 v53, vcc, 0, v67, vcc
	global_load_dword v51, v[52:53], off offset:2048 nt
	v_add_co_u32_e32 v52, vcc, s77, v66
	s_nop 1
	v_addc_co_u32_e32 v53, vcc, 0, v67, vcc
	v_add_co_u32_e32 v54, vcc, s78, v66
	global_load_dword v52, v[52:53], off nt
	s_nop 0
	v_addc_co_u32_e32 v55, vcc, 0, v67, vcc
	global_load_dword v53, v[54:55], off offset:2048 nt
	v_add_co_u32_e32 v54, vcc, s79, v66
	s_nop 1
	v_addc_co_u32_e32 v55, vcc, 0, v67, vcc
	v_add_co_u32_e32 v56, vcc, s80, v66
	global_load_dword v54, v[54:55], off nt
	s_nop 0
	v_addc_co_u32_e32 v57, vcc, 0, v67, vcc
	global_load_dword v55, v[56:57], off offset:2048 nt
	v_add_co_u32_e32 v56, vcc, s81, v66
	s_nop 1
	v_addc_co_u32_e32 v57, vcc, 0, v67, vcc
	v_add_co_u32_e32 v58, vcc, s82, v66
	global_load_dword v56, v[56:57], off nt
	s_nop 0
	v_addc_co_u32_e32 v59, vcc, 0, v67, vcc
	global_load_dword v57, v[58:59], off offset:2048 nt
	v_add_co_u32_e32 v58, vcc, s83, v66
	s_nop 1
	v_addc_co_u32_e32 v59, vcc, 0, v67, vcc
	v_add_co_u32_e32 v60, vcc, s84, v66
	global_load_dword v58, v[58:59], off nt
	s_nop 0
	v_addc_co_u32_e32 v61, vcc, 0, v67, vcc
	global_load_dword v59, v[60:61], off offset:2048 nt
	v_add_co_u32_e32 v60, vcc, s85, v66
	s_nop 1
	v_addc_co_u32_e32 v61, vcc, 0, v67, vcc
	v_add_co_u32_e32 v62, vcc, s86, v66
	global_load_dword v60, v[60:61], off nt
	s_nop 0
	v_addc_co_u32_e32 v63, vcc, 0, v67, vcc
	global_load_dword v61, v[62:63], off offset:2048 nt
	v_add_co_u32_e32 v62, vcc, s87, v66
	s_nop 1
	v_addc_co_u32_e32 v63, vcc, 0, v67, vcc
	v_add_co_u32_e32 v64, vcc, s88, v66
	global_load_dword v62, v[62:63], off nt
	s_nop 0
	v_addc_co_u32_e32 v65, vcc, 0, v67, vcc
	global_load_dword v63, v[64:65], off offset:2048 nt
	v_add_co_u32_e32 v64, vcc, s89, v66
	s_nop 1
	v_addc_co_u32_e32 v65, vcc, 0, v67, vcc
	v_add_co_u32_e32 v66, vcc, s90, v66
	global_load_dword v64, v[64:65], off nt
	s_nop 0
	v_addc_co_u32_e32 v67, vcc, 0, v67, vcc
	global_load_dword v65, v[66:67], off offset:2048 nt
	s_cbranch_scc1 .LBB0_87
; __device__ __forceinline__ void transpose_item(const float* __restrict__ W, int K, int N, bf16* __restrict__ WT, const float* __restrict__ ksc, int mode, int row_off, int item, int lane) {
;     ...
;     if (ksc) {
; #pragma unroll
;         for (int i = 0; i < 64; ++i) v[i] *= ksc[k0 + i];
;     }
	s_lshl_b64 s[6:7], s[24:25], 2
	s_add_u32 s6, s4, s6
	s_addc_u32 s7, s5, s7
	s_add_u32 s4, s6, 0x1000
	s_addc_u32 s5, s7, 0
	global_load_dwordx4 v[66:69], v13, s[4:5] offset:48
	global_load_dwordx4 v[70:73], v13, s[4:5] offset:32
	global_load_dwordx4 v[74:77], v13, s[4:5] offset:16
	global_load_dwordx4 v[86:89], v83, s[6:7]
	global_load_dwordx4 v[160:163], v13, s[4:5] offset:112
	global_load_dwordx4 v[164:167], v13, s[4:5] offset:96
	global_load_dwordx4 v[168:171], v13, s[4:5] offset:80
	global_load_dwordx4 v[172:175], v13, s[4:5] offset:64
	global_load_dwordx4 v[176:179], v13, s[4:5] offset:176
	global_load_dwordx4 v[180:183], v13, s[4:5] offset:160
	global_load_dwordx4 v[184:187], v13, s[4:5] offset:144
	global_load_dwordx4 v[188:191], v13, s[4:5] offset:128
	global_load_dwordx4 v[208:211], v13, s[4:5] offset:240
	global_load_dwordx4 v[212:215], v13, s[4:5] offset:224
	global_load_dwordx4 v[216:219], v13, s[4:5] offset:208
	global_load_dwordx4 v[220:223], v13, s[4:5] offset:192
	s_waitcnt vmcnt(0)
	v_pk_mul_f32 v[14:15], v[14:15], v[66:67]
	s_waitcnt vmcnt(2)
	v_pk_mul_f32 v[8:9], v[8:9], v[70:71]
	s_waitcnt vmcnt(1)
	v_pk_mul_f32 v[4:5], v[4:5], v[74:75]
	s_waitcnt vmcnt(0)
	v_pk_mul_f32 v[0:1], v[0:1], v[86:87]
	v_pk_mul_f32 v[2:3], v[2:3], v[88:89]
	v_pk_mul_f32 v[6:7], v[6:7], v[76:77]
	v_pk_mul_f32 v[10:11], v[10:11], v[72:73]
	v_pk_mul_f32 v[16:17], v[16:17], v[68:69]
	v_mov_b32_e32 v66, v160
	v_mov_b32_e32 v67, v161
	v_mov_b32_e32 v68, v162
	v_mov_b32_e32 v69, v163
	v_mov_b32_e32 v70, v164
	v_mov_b32_e32 v71, v165
	v_mov_b32_e32 v72, v166
	v_mov_b32_e32 v73, v167
	v_mov_b32_e32 v74, v168
	v_mov_b32_e32 v75, v169
	v_mov_b32_e32 v76, v170
	v_mov_b32_e32 v77, v171
	v_mov_b32_e32 v86, v172
	v_mov_b32_e32 v87, v173
	v_mov_b32_e32 v88, v174
	v_mov_b32_e32 v89, v175
	s_waitcnt vmcnt(3)
	v_pk_mul_f32 v[30:31], v[30:31], v[66:67]
	s_waitcnt vmcnt(2)
	v_pk_mul_f32 v[26:27], v[26:27], v[70:71]
	s_waitcnt vmcnt(1)
	v_pk_mul_f32 v[22:23], v[22:23], v[74:75]
	s_waitcnt vmcnt(0)
	v_pk_mul_f32 v[18:19], v[18:19], v[86:87]
	v_pk_mul_f32 v[20:21], v[20:21], v[88:89]
	v_pk_mul_f32 v[24:25], v[24:25], v[76:77]
	v_pk_mul_f32 v[28:29], v[28:29], v[72:73]
	v_pk_mul_f32 v[32:33], v[32:33], v[68:69]
	v_mov_b32_e32 v66, v176
	v_mov_b32_e32 v67, v177
	v_mov_b32_e32 v68, v178
	v_mov_b32_e32 v69, v179
	v_mov_b32_e32 v70, v180
	v_mov_b32_e32 v71, v181
	v_mov_b32_e32 v72, v182
	v_mov_b32_e32 v73, v183
	v_mov_b32_e32 v74, v184
	v_mov_b32_e32 v75, v185
	v_mov_b32_e32 v76, v186
	v_mov_b32_e32 v77, v187
	v_mov_b32_e32 v86, v188
	v_mov_b32_e32 v87, v189
	v_mov_b32_e32 v88, v190
	v_mov_b32_e32 v89, v191
	s_waitcnt vmcnt(3)
	v_pk_mul_f32 v[46:47], v[46:47], v[66:67]
	s_waitcnt vmcnt(2)
	v_pk_mul_f32 v[42:43], v[42:43], v[70:71]
	s_waitcnt vmcnt(1)
	v_pk_mul_f32 v[38:39], v[38:39], v[74:75]
	s_waitcnt vmcnt(0)
	v_pk_mul_f32 v[34:35], v[34:35], v[86:87]
	v_pk_mul_f32 v[36:37], v[36:37], v[88:89]
	v_pk_mul_f32 v[40:41], v[40:41], v[76:77]
	v_pk_mul_f32 v[44:45], v[44:45], v[72:73]
	v_pk_mul_f32 v[48:49], v[48:49], v[68:69]
	v_mov_b32_e32 v66, v208
	v_mov_b32_e32 v67, v209
	v_mov_b32_e32 v68, v210
	v_mov_b32_e32 v69, v211
	v_mov_b32_e32 v70, v212
	v_mov_b32_e32 v71, v213
	v_mov_b32_e32 v72, v214
	v_mov_b32_e32 v73, v215
	v_mov_b32_e32 v74, v216
	v_mov_b32_e32 v75, v217
	v_mov_b32_e32 v76, v218
	v_mov_b32_e32 v77, v219
	v_mov_b32_e32 v86, v220
	v_mov_b32_e32 v87, v221
	v_mov_b32_e32 v88, v222
	v_mov_b32_e32 v89, v223
	s_waitcnt vmcnt(3)
	v_pk_mul_f32 v[62:63], v[62:63], v[66:67]
	s_waitcnt vmcnt(2)
	v_pk_mul_f32 v[58:59], v[58:59], v[70:71]
	s_waitcnt vmcnt(1)
	v_pk_mul_f32 v[54:55], v[54:55], v[74:75]
	s_waitcnt vmcnt(0)
	v_pk_mul_f32 v[50:51], v[50:51], v[86:87]
	v_pk_mul_f32 v[52:53], v[52:53], v[88:89]
	v_pk_mul_f32 v[56:57], v[56:57], v[76:77]
	v_pk_mul_f32 v[60:61], v[60:61], v[72:73]
	v_pk_mul_f32 v[64:65], v[64:65], v[68:69]
	s_branch .LBB0_87

; __device__ __forceinline__ void transpose_item(const float* __restrict__ W, int K, int N, bf16* __restrict__ WT, const float* __restrict__ ksc, int mode, int row_off, int item, int lane) {
;     const int nblk = N / 64, kb = item / nblk, nb = item % nblk, k0 = 64 * kb, n = 64 * nb + lane;
;     const float* src = W + (size_t)k0 * N + n;
;     float v[64];
; #pragma unroll
;     for (int i = 0; i < 64; ++i) v[i] = __builtin_nontemporal_load(src + (size_t)i * N);
; __device__ __forceinline__ void convert_layer(ArgsP a, int L, int first, int stride, int lane) {
;     ...
;         else if (r < I_IN + I_OUT + I_GU) transpose_item(a->in[18] + (size_t)L * D * GU, D, GU, WGU + (size_t)L * GU * D, a->in[17] + L * D, 2, 0, r - I_IN - I_OUT, lane);
.Lcx1_93:
	s_andn2_b64 vcc, exec, s[4:5]
	s_cbranch_vccnz .Lcx1_101
	s_add_i32 s24, s1, 0xfc80
	s_and_b32 s91, s24, 0xffff
	s_mul_i32 s91, s91, 0xba2f
	s_load_dwordx4 s[4:7], s[12:13], 0x88
	s_lshr_b32 s93, s91, 16
	s_lshr_b32 s91, s91, 22
	s_mulk_i32 s91, 0x58
	s_sub_i32 s24, s24, s91
	s_and_b32 s92, s24, 0xffff
	s_and_b32 s24, s93, 0xffc0
	s_lshl_b32 s91, s92, 6
	s_mul_i32 s93, s24, 0x5800
	v_or_b32_e32 v78, s91, v80
	s_waitcnt lgkmcnt(0)
	s_add_u32 s6, s6, s93
	s_addc_u32 s7, s7, 0
	v_lshlrev_b32_e32 v12, 2, v78
	v_lshl_add_u64 v[0:1], s[6:7], 0, v[12:13]
	s_mov_b32 s6, 0x1600000
	v_add_co_u32_e32 v2, vcc, s6, v0
	s_mov_b32 s6, 0x1605000
	s_nop 0
	v_addc_co_u32_e32 v3, vcc, 0, v1, vcc
	global_load_dword v16, v[2:3], off nt
	v_add_co_u32_e32 v2, vcc, s6, v0
	s_mov_b32 s6, 0x160b000
	s_nop 0
	v_addc_co_u32_e32 v3, vcc, 0, v1, vcc
	global_load_dword v14, v[2:3], off offset:2048 nt
	v_add_co_u32_e32 v2, vcc, s6, v0
	s_mov_b32 s6, 0x1610000
	s_nop 0
	v_addc_co_u32_e32 v3, vcc, 0, v1, vcc
	global_load_dword v17, v[2:3], off nt
	v_add_co_u32_e32 v2, vcc, s6, v0
	s_mov_b32 s6, 0x1616000
	s_nop 0
	v_addc_co_u32_e32 v3, vcc, 0, v1, vcc
	global_load_dword v15, v[2:3], off offset:2048 nt
	v_add_co_u32_e32 v2, vcc, s6, v0
	s_mov_b32 s6, 0x161b000
	s_nop 0
	v_addc_co_u32_e32 v3, vcc, 0, v1, vcc
	global_load_dword v20, v[2:3], off nt
	v_add_co_u32_e32 v2, vcc, s6, v0
	s_mov_b32 s6, 0x1621000
	s_nop 0
	v_addc_co_u32_e32 v3, vcc, 0, v1, vcc
	global_load_dword v18, v[2:3], off offset:2048 nt
	v_add_co_u32_e32 v2, vcc, s6, v0
	s_mov_b32 s6, 0x1626000
	s_nop 0
	v_addc_co_u32_e32 v3, vcc, 0, v1, vcc
	global_load_dword v21, v[2:3], off nt
	v_add_co_u32_e32 v2, vcc, s6, v0
	s_mov_b32 s6, 0x162c000
	s_nop 0
	v_addc_co_u32_e32 v3, vcc, 0, v1, vcc
	global_load_dword v19, v[2:3], off offset:2048 nt
	v_add_co_u32_e32 v2, vcc, s6, v0
	s_mov_b32 s6, 0x1631000
	s_nop 0
	v_addc_co_u32_e32 v3, vcc, 0, v1, vcc
	global_load_dword v24, v[2:3], off nt
	v_add_co_u32_e32 v2, vcc, s6, v0
	s_mov_b32 s6, 0x1637000
	s_nop 0
	v_addc_co_u32_e32 v3, vcc, 0, v1, vcc
	global_load_dword v22, v[2:3], off offset:2048 nt
	v_add_co_u32_e32 v2, vcc, s6, v0
	s_mov_b32 s6, 0x163c000
	s_nop 0
	v_addc_co_u32_e32 v3, vcc, 0, v1, vcc
	global_load_dword v25, v[2:3], off nt
	v_add_co_u32_e32 v2, vcc, s6, v0
	s_mov_b32 s6, 0x1642000
	s_nop 0
	v_addc_co_u32_e32 v3, vcc, 0, v1, vcc
	global_load_dword v23, v[2:3], off offset:2048 nt
	v_add_co_u32_e32 v2, vcc, s6, v0
	s_mov_b32 s6, 0x1647000
	s_nop 0
	v_addc_co_u32_e32 v3, vcc, 0, v1, vcc
	global_load_dword v28, v[2:3], off nt
	v_add_co_u32_e32 v2, vcc, s6, v0
	s_mov_b32 s6, 0x164d000
	s_nop 0
	v_addc_co_u32_e32 v3, vcc, 0, v1, vcc
	global_load_dword v26, v[2:3], off offset:2048 nt
	v_add_co_u32_e32 v2, vcc, s6, v0
	s_mov_b32 s6, 0x1652000
	s_nop 0
	v_addc_co_u32_e32 v3, vcc, 0, v1, vcc
	global_load_dword v29, v[2:3], off nt
	v_add_co_u32_e32 v2, vcc, s6, v0
	s_mov_b32 s6, 0x1658000
	s_nop 0
	v_addc_co_u32_e32 v3, vcc, 0, v1, vcc
	global_load_dword v27, v[2:3], off offset:2048 nt
	v_add_co_u32_e32 v2, vcc, s6, v0
	s_mov_b32 s6, 0x165d000
	s_nop 0
	v_addc_co_u32_e32 v3, vcc, 0, v1, vcc
	global_load_dword v32, v[2:3], off nt
	v_add_co_u32_e32 v2, vcc, s6, v0
	s_mov_b32 s6, 0x1663000
	s_nop 0
	v_addc_co_u32_e32 v3, vcc, 0, v1, vcc
	global_load_dword v30, v[2:3], off offset:2048 nt
	v_add_co_u32_e32 v2, vcc, s6, v0
	s_mov_b32 s6, 0x1668000
	s_nop 0
	v_addc_co_u32_e32 v3, vcc, 0, v1, vcc
	global_load_dword v33, v[2:3], off nt
	v_add_co_u32_e32 v2, vcc, s6, v0
	s_mov_b32 s6, 0x166e000
	s_nop 0
	v_addc_co_u32_e32 v3, vcc, 0, v1, vcc
	global_load_dword v31, v[2:3], off offset:2048 nt
	v_add_co_u32_e32 v2, vcc, s6, v0
	s_mov_b32 s6, 0x1673000
	s_nop 0
	v_addc_co_u32_e32 v3, vcc, 0, v1, vcc
	global_load_dword v36, v[2:3], off nt
	v_add_co_u32_e32 v2, vcc, s6, v0
	s_mov_b32 s6, 0x1679000
	s_nop 0
	v_addc_co_u32_e32 v3, vcc, 0, v1, vcc
	global_load_dword v34, v[2:3], off offset:2048 nt
	v_add_co_u32_e32 v2, vcc, s6, v0
	s_mov_b32 s6, 0x167e000
	s_nop 0
	v_addc_co_u32_e32 v3, vcc, 0, v1, vcc
	global_load_dword v37, v[2:3], off nt
	v_add_co_u32_e32 v2, vcc, s6, v0
	s_mov_b32 s6, 0x1684000
	s_nop 0
	v_addc_co_u32_e32 v3, vcc, 0, v1, vcc
	global_load_dword v35, v[2:3], off offset:2048 nt
	v_add_co_u32_e32 v2, vcc, s6, v0
	s_mov_b32 s6, 0x1689000
	s_nop 0
	v_addc_co_u32_e32 v3, vcc, 0, v1, vcc
	global_load_dword v40, v[2:3], off nt
	v_add_co_u32_e32 v2, vcc, s6, v0
	s_mov_b32 s6, 0x168f000
	s_nop 0
	v_addc_co_u32_e32 v3, vcc, 0, v1, vcc
	global_load_dword v38, v[2:3], off offset:2048 nt
	v_add_co_u32_e32 v2, vcc, s6, v0
	s_mov_b32 s6, 0x1694000
	s_nop 0
	v_addc_co_u32_e32 v3, vcc, 0, v1, vcc
	global_load_dword v41, v[2:3], off nt
	v_add_co_u32_e32 v2, vcc, s6, v0
	s_mov_b32 s6, 0x169a000
	s_nop 0
	v_addc_co_u32_e32 v3, vcc, 0, v1, vcc
	global_load_dword v39, v[2:3], off offset:2048 nt
	v_add_co_u32_e32 v2, vcc, s6, v0
	s_mov_b32 s6, 0x169f000
	s_nop 0
	v_addc_co_u32_e32 v3, vcc, 0, v1, vcc
	global_load_dword v44, v[2:3], off nt
	v_add_co_u32_e32 v2, vcc, s6, v0
	s_mov_b32 s6, 0x16a5000
	s_nop 0
	v_addc_co_u32_e32 v3, vcc, 0, v1, vcc
	global_load_dword v42, v[2:3], off offset:2048 nt
	v_add_co_u32_e32 v2, vcc, s6, v0
	s_mov_b32 s6, 0x16aa000
	s_nop 0
	v_addc_co_u32_e32 v3, vcc, 0, v1, vcc
	global_load_dword v45, v[2:3], off nt
	v_add_co_u32_e32 v2, vcc, s6, v0
	s_mov_b32 s6, 0x16b0000
	s_nop 0
	v_addc_co_u32_e32 v3, vcc, 0, v1, vcc
	global_load_dword v43, v[2:3], off offset:2048 nt
	v_add_co_u32_e32 v2, vcc, s6, v0
	s_mov_b32 s6, 0x16b5000
	s_nop 0
	v_addc_co_u32_e32 v3, vcc, 0, v1, vcc
	global_load_dword v48, v[2:3], off nt
	v_add_co_u32_e32 v2, vcc, s6, v0
; __device__ __forceinline__ void transpose_item(const float* __restrict__ W, int K, int N, bf16* __restrict__ WT, const float* __restrict__ ksc, int mode, int row_off, int item, int lane) {
;     ...
;     for (int i = 0; i < 64; ++i) v[i] = __builtin_nontemporal_load(src + (size_t)i * N);
;     if (ksc) {
	s_mov_b32 s6, 0x16bb000
	s_nop 0
	v_addc_co_u32_e32 v3, vcc, 0, v1, vcc
	global_load_dword v46, v[2:3], off offset:2048 nt
	v_add_co_u32_e32 v2, vcc, s6, v0
	s_mov_b32 s6, 0x16c0000
	s_nop 0
	v_addc_co_u32_e32 v3, vcc, 0, v1, vcc
	global_load_dword v49, v[2:3], off nt
	v_add_co_u32_e32 v2, vcc, s6, v0
	s_mov_b32 s6, 0x16c6000
	s_nop 0
	v_addc_co_u32_e32 v3, vcc, 0, v1, vcc
	global_load_dword v47, v[2:3], off offset:2048 nt
	v_add_co_u32_e32 v2, vcc, s6, v0
	s_mov_b32 s6, 0x16cb000
	s_nop 0
	v_addc_co_u32_e32 v3, vcc, 0, v1, vcc
	global_load_dword v52, v[2:3], off nt
	v_add_co_u32_e32 v2, vcc, s6, v0
	s_mov_b32 s6, 0x16d1000
	s_nop 0
	v_addc_co_u32_e32 v3, vcc, 0, v1, vcc
	global_load_dword v50, v[2:3], off offset:2048 nt
	v_add_co_u32_e32 v2, vcc, s6, v0
	s_mov_b32 s6, 0x16d6000
	s_nop 0
	v_addc_co_u32_e32 v3, vcc, 0, v1, vcc
	global_load_dword v53, v[2:3], off nt
	v_add_co_u32_e32 v2, vcc, s6, v0
	s_mov_b32 s6, 0x16dc000
	s_nop 0
	v_addc_co_u32_e32 v3, vcc, 0, v1, vcc
	global_load_dword v51, v[2:3], off offset:2048 nt
	v_add_co_u32_e32 v2, vcc, s6, v0
	s_mov_b32 s6, 0x16e1000
	s_nop 0
	v_addc_co_u32_e32 v3, vcc, 0, v1, vcc
	global_load_dword v56, v[2:3], off nt
	v_add_co_u32_e32 v2, vcc, s6, v0
	s_mov_b32 s6, 0x16e7000
	s_nop 0
	v_addc_co_u32_e32 v3, vcc, 0, v1, vcc
	global_load_dword v54, v[2:3], off offset:2048 nt
	v_add_co_u32_e32 v2, vcc, s6, v0
	s_mov_b32 s6, 0x16ec000
	s_nop 0
	v_addc_co_u32_e32 v3, vcc, 0, v1, vcc
	global_load_dword v57, v[2:3], off nt
	v_add_co_u32_e32 v2, vcc, s6, v0
	s_mov_b32 s6, 0x16f2000
	s_nop 0
	v_addc_co_u32_e32 v3, vcc, 0, v1, vcc
	global_load_dword v55, v[2:3], off offset:2048 nt
	v_add_co_u32_e32 v2, vcc, s6, v0
	s_mov_b32 s6, 0x16f7000
	s_nop 0
	v_addc_co_u32_e32 v3, vcc, 0, v1, vcc
	global_load_dword v60, v[2:3], off nt
	v_add_co_u32_e32 v2, vcc, s6, v0
	s_mov_b32 s6, 0x16fd000
	s_nop 0
	v_addc_co_u32_e32 v3, vcc, 0, v1, vcc
	global_load_dword v58, v[2:3], off offset:2048 nt
	v_add_co_u32_e32 v2, vcc, s6, v0
	s_mov_b32 s6, 0x1702000
	s_nop 0
	v_addc_co_u32_e32 v3, vcc, 0, v1, vcc
	global_load_dword v61, v[2:3], off nt
	v_add_co_u32_e32 v2, vcc, s6, v0
	s_mov_b32 s6, 0x1708000
	s_nop 0
	v_addc_co_u32_e32 v3, vcc, 0, v1, vcc
	global_load_dword v59, v[2:3], off offset:2048 nt
	v_add_co_u32_e32 v2, vcc, s6, v0
	s_mov_b32 s6, 0x170d000
	s_nop 0
	v_addc_co_u32_e32 v3, vcc, 0, v1, vcc
	global_load_dword v64, v[2:3], off nt
	v_add_co_u32_e32 v2, vcc, s6, v0
	s_mov_b32 s6, 0x1713000
	s_nop 0
	v_addc_co_u32_e32 v3, vcc, 0, v1, vcc
	global_load_dword v62, v[2:3], off offset:2048 nt
	v_add_co_u32_e32 v2, vcc, s6, v0
	s_mov_b32 s6, 0x1718000
	s_nop 0
	v_addc_co_u32_e32 v3, vcc, 0, v1, vcc
	global_load_dword v65, v[2:3], off nt
	v_add_co_u32_e32 v2, vcc, s6, v0
	s_mov_b32 s6, 0x171e000
	s_nop 0
	v_addc_co_u32_e32 v3, vcc, 0, v1, vcc
	global_load_dword v63, v[2:3], off offset:2048 nt
	v_add_co_u32_e32 v2, vcc, s6, v0
	s_mov_b32 s6, 0x1723000
	s_nop 0
	v_addc_co_u32_e32 v3, vcc, 0, v1, vcc
	global_load_dword v68, v[2:3], off nt
	v_add_co_u32_e32 v2, vcc, s6, v0
	s_mov_b32 s6, 0x1729000
	s_nop 0
	v_addc_co_u32_e32 v3, vcc, 0, v1, vcc
	global_load_dword v66, v[2:3], off offset:2048 nt
	v_add_co_u32_e32 v2, vcc, s6, v0
	s_mov_b32 s6, 0x172e000
	s_nop 0
	v_addc_co_u32_e32 v3, vcc, 0, v1, vcc
	global_load_dword v69, v[2:3], off nt
	v_add_co_u32_e32 v2, vcc, s6, v0
	s_mov_b32 s6, 0x1734000
	s_nop 0
	v_addc_co_u32_e32 v3, vcc, 0, v1, vcc
	global_load_dword v67, v[2:3], off offset:2048 nt
	v_add_co_u32_e32 v2, vcc, s6, v0
	s_mov_b32 s6, 0x1739000
	s_nop 0
	v_addc_co_u32_e32 v3, vcc, 0, v1, vcc
	global_load_dword v70, v[2:3], off nt
	v_add_co_u32_e32 v2, vcc, s6, v0
	s_mov_b32 s6, 0x173f000
	s_nop 0
	v_addc_co_u32_e32 v3, vcc, 0, v1, vcc
	global_load_dword v72, v[2:3], off offset:2048 nt
	v_add_co_u32_e32 v2, vcc, s6, v0
	s_mov_b32 s6, 0x1744000
	s_nop 0
	v_addc_co_u32_e32 v3, vcc, 0, v1, vcc
	global_load_dword v71, v[2:3], off nt
	v_add_co_u32_e32 v2, vcc, s6, v0
	s_mov_b32 s6, 0x174a000
	s_nop 0
	v_addc_co_u32_e32 v3, vcc, 0, v1, vcc
	global_load_dword v73, v[2:3], off offset:2048 nt
	v_add_co_u32_e32 v2, vcc, s6, v0
	s_mov_b32 s6, 0x174f000
	s_nop 0
	v_addc_co_u32_e32 v3, vcc, 0, v1, vcc
	global_load_dword v74, v[2:3], off nt
	v_add_co_u32_e32 v2, vcc, s6, v0
	s_mov_b32 s6, 0x1755000
	s_nop 0
	v_addc_co_u32_e32 v3, vcc, 0, v1, vcc
	global_load_dword v75, v[2:3], off offset:2048 nt
	v_add_co_u32_e32 v2, vcc, s6, v0
	s_mov_b32 s6, 0x175a000
	s_nop 0
	v_addc_co_u32_e32 v3, vcc, 0, v1, vcc
	v_add_co_u32_e32 v0, vcc, s6, v0
	global_load_dword v76, v[2:3], off nt
	s_nop 0
	v_addc_co_u32_e32 v1, vcc, 0, v1, vcc
	global_load_dword v77, v[0:1], off offset:2048 nt
	s_cmp_eq_u64 s[4:5], 0
	s_cbranch_scc1 .Lcx1_96
; __device__ __forceinline__ void transpose_item(const float* __restrict__ W, int K, int N, bf16* __restrict__ WT, const float* __restrict__ ksc, int mode, int row_off, int item, int lane) {
;     ...
;     if (ksc) {
; #pragma unroll
;         for (int i = 0; i < 64; ++i) v[i] *= ksc[k0 + i];
;     }
	s_lshl_b32 s6, s24, 2
	s_add_u32 s6, s4, s6
	s_addc_u32 s7, s5, 0
	s_add_u32 s4, s6, 0x1000
	s_addc_u32 s5, s7, 0
	global_load_dwordx4 v[0:3], v13, s[4:5] offset:48
	global_load_dwordx4 v[4:7], v13, s[4:5] offset:32
	global_load_dwordx4 v[8:11], v13, s[4:5] offset:16
	global_load_dwordx4 v[86:89], v83, s[6:7]
	global_load_dwordx4 v[184:187], v13, s[4:5] offset:112
	global_load_dwordx4 v[188:191], v13, s[4:5] offset:96
	global_load_dwordx4 v[192:195], v13, s[4:5] offset:80
	global_load_dwordx4 v[196:199], v13, s[4:5] offset:64
	global_load_dwordx4 v[204:207], v13, s[4:5] offset:176
	global_load_dwordx4 v[208:211], v13, s[4:5] offset:160
	global_load_dwordx4 v[212:215], v13, s[4:5] offset:144
	global_load_dwordx4 v[216:219], v13, s[4:5] offset:128
	global_load_dwordx4 v[220:223], v13, s[4:5] offset:224
	global_load_dwordx4 v[224:227], v13, s[4:5] offset:208
	global_load_dwordx4 v[228:231], v13, s[4:5] offset:192
	global_load_dwordx4 v[232:235], v13, s[4:5] offset:240
	s_waitcnt vmcnt(0)
	v_mov_b32_e32 v90, v86
	v_mov_b32_e32 v91, v88
	v_mov_b32_e32 v88, v87
	v_mov_b32_e32 v86, v8
	v_mov_b32_e32 v87, v10
	v_mov_b32_e32 v10, v9
	v_mov_b32_e32 v8, v4
	v_mov_b32_e32 v9, v6
	v_mov_b32_e32 v6, v5
	v_mov_b32_e32 v4, v0
	v_mov_b32_e32 v5, v2
	v_mov_b32_e32 v2, v1
	v_pk_mul_f32 v[14:15], v[14:15], v[88:89]
	v_pk_mul_f32 v[20:21], v[20:21], v[86:87]
	v_pk_mul_f32 v[18:19], v[18:19], v[10:11]
	v_pk_mul_f32 v[24:25], v[24:25], v[8:9]
	v_pk_mul_f32 v[22:23], v[22:23], v[6:7]
	v_pk_mul_f32 v[28:29], v[28:29], v[4:5]
	v_pk_mul_f32 v[26:27], v[26:27], v[2:3]
	v_mov_b32_e32 v0, v184
	v_mov_b32_e32 v1, v185
	v_mov_b32_e32 v2, v186
	v_mov_b32_e32 v3, v187
	v_mov_b32_e32 v4, v188
	v_mov_b32_e32 v5, v189
	v_mov_b32_e32 v6, v190
	v_mov_b32_e32 v7, v191
	v_mov_b32_e32 v8, v192
	v_mov_b32_e32 v9, v193
	v_mov_b32_e32 v10, v194
	v_mov_b32_e32 v11, v195
	v_mov_b32_e32 v86, v196
	v_mov_b32_e32 v87, v197
	v_mov_b32_e32 v88, v198
	v_mov_b32_e32 v89, v199
	v_pk_mul_f32 v[16:17], v[16:17], v[90:91]
	s_waitcnt vmcnt(0)
	v_mov_b32_e32 v90, v86
	v_mov_b32_e32 v91, v88
	v_mov_b32_e32 v88, v87
	v_mov_b32_e32 v86, v8
	v_mov_b32_e32 v87, v10
	v_mov_b32_e32 v10, v9
	v_mov_b32_e32 v8, v4
	v_mov_b32_e32 v9, v6
	v_mov_b32_e32 v6, v5
	v_mov_b32_e32 v4, v0
	v_mov_b32_e32 v5, v2
	v_mov_b32_e32 v2, v1
	v_pk_mul_f32 v[30:31], v[30:31], v[88:89]
	v_pk_mul_f32 v[36:37], v[36:37], v[86:87]
	v_pk_mul_f32 v[34:35], v[34:35], v[10:11]
	v_pk_mul_f32 v[40:41], v[40:41], v[8:9]
	v_pk_mul_f32 v[38:39], v[38:39], v[6:7]
	v_pk_mul_f32 v[44:45], v[44:45], v[4:5]
	v_pk_mul_f32 v[42:43], v[42:43], v[2:3]
	v_mov_b32_e32 v0, v204
	v_mov_b32_e32 v1, v205
	v_mov_b32_e32 v2, v206
	v_mov_b32_e32 v3, v207
	v_mov_b32_e32 v4, v208
	v_mov_b32_e32 v5, v209
	v_mov_b32_e32 v6, v210
	v_mov_b32_e32 v7, v211
	v_mov_b32_e32 v8, v212
	v_mov_b32_e32 v9, v213
	v_mov_b32_e32 v10, v214
	v_mov_b32_e32 v11, v215
	v_mov_b32_e32 v86, v216
	v_mov_b32_e32 v87, v217
	v_mov_b32_e32 v88, v218
	v_mov_b32_e32 v89, v219
	v_pk_mul_f32 v[32:33], v[32:33], v[90:91]
	s_waitcnt vmcnt(0)
	v_mov_b32_e32 v90, v86
	v_mov_b32_e32 v91, v88
	v_mov_b32_e32 v88, v87
	v_mov_b32_e32 v86, v8
	v_mov_b32_e32 v87, v10
	v_mov_b32_e32 v10, v9
	v_mov_b32_e32 v8, v4
	v_mov_b32_e32 v9, v6
	v_mov_b32_e32 v6, v5
	v_mov_b32_e32 v4, v0
	v_mov_b32_e32 v5, v2
	v_mov_b32_e32 v2, v1
	v_pk_mul_f32 v[46:47], v[46:47], v[88:89]
	v_pk_mul_f32 v[52:53], v[52:53], v[86:87]
	v_pk_mul_f32 v[50:51], v[50:51], v[10:11]
	v_pk_mul_f32 v[56:57], v[56:57], v[8:9]
	v_pk_mul_f32 v[54:55], v[54:55], v[6:7]
	v_pk_mul_f32 v[60:61], v[60:61], v[4:5]
	v_pk_mul_f32 v[58:59], v[58:59], v[2:3]
	v_mov_b32_e32 v0, v220
	v_mov_b32_e32 v1, v221
	v_mov_b32_e32 v2, v222
	v_mov_b32_e32 v3, v223
	v_mov_b32_e32 v4, v224
	v_mov_b32_e32 v5, v225
	v_mov_b32_e32 v6, v226
	v_mov_b32_e32 v7, v227
	v_mov_b32_e32 v86, v228
	v_mov_b32_e32 v87, v229
	v_mov_b32_e32 v88, v230
	v_mov_b32_e32 v89, v231
	v_mov_b32_e32 v8, v232
	v_mov_b32_e32 v9, v233
	v_mov_b32_e32 v10, v234
	v_mov_b32_e32 v11, v235
	v_pk_mul_f32 v[48:49], v[48:49], v[90:91]
	s_waitcnt vmcnt(1)
	v_mov_b32_e32 v90, v86
	v_mov_b32_e32 v91, v88
	v_mov_b32_e32 v88, v87
	v_mov_b32_e32 v86, v4
	v_mov_b32_e32 v87, v6
	v_mov_b32_e32 v6, v5
	v_mov_b32_e32 v4, v0
	v_mov_b32_e32 v5, v2
	v_mov_b32_e32 v2, v1
	v_pk_mul_f32 v[64:65], v[64:65], v[90:91]
	v_pk_mul_f32 v[62:63], v[62:63], v[88:89]
	v_pk_mul_f32 v[68:69], v[68:69], v[86:87]
	v_pk_mul_f32 v[66:67], v[66:67], v[6:7]
	v_pk_mul_f32 v[70:71], v[70:71], v[4:5]
	v_pk_mul_f32 v[72:73], v[72:73], v[2:3]
	s_waitcnt vmcnt(0)
	v_pk_mul_f32 v[74:75], v[74:75], v[8:9]
	v_pk_mul_f32 v[76:77], v[76:77], v[10:11]

; __device__ __forceinline__ void transpose_item(const float* __restrict__ W, int K, int N, bf16* __restrict__ WT, const float* __restrict__ ksc, int mode, int row_off, int item, int lane) {
;     const int nblk = N / 64, kb = item / nblk, nb = item % nblk, k0 = 64 * kb, n = 64 * nb + lane;
;     const float* src = W + (size_t)k0 * N + n;
;     float v[64];
; #pragma unroll
;     for (int i = 0; i < 64; ++i) v[i] = __builtin_nontemporal_load(src + (size_t)i * N);
; __device__ __forceinline__ void convert_layer(ArgsP a, int L, int first, int stride, int lane) {
;     ...
;         if (r < I_IN) transpose_item(a->in[3] + (size_t)L * D * INW, D, INW, WIN + (size_t)L * INW * D, a->in[2] + L * D, 1, 0, r, lane);
.Lcx1_105:
	s_andn2_b64 vcc, exec, s[4:5]
	s_cbranch_vccnz .Lcx1_88
	s_mul_hi_u32 s4, s1, 0xcccccccd
	s_lshr_b32 s91, s4, 5
	s_mul_i32 s4, s91, 0xa00
	v_subrev_u32_e32 v12, s4, v82
	s_load_dwordx4 s[4:7], s[12:13], 0x10
	s_lshl_b32 s24, s91, 6
	s_mul_i32 s91, s91, 0xa0000
	s_mul_hi_u32 s92, s24, 0x2800
	s_waitcnt lgkmcnt(0)
	s_add_u32 s6, s6, s91
	s_addc_u32 s7, s7, s92
	v_lshl_add_u64 v[66:67], v[12:13], 2, s[6:7]
	s_mov_b32 s6, 0xa00000
	v_add_co_u32_e32 v0, vcc, s6, v66
	s_mov_b32 s6, 0xa02000
	s_nop 0
	v_addc_co_u32_e32 v1, vcc, 0, v67, vcc
	v_add_co_u32_e32 v2, vcc, s6, v66
	s_mov_b32 s6, 0xa05000
	s_nop 0
	v_addc_co_u32_e32 v3, vcc, 0, v67, vcc
	global_load_dword v0, v[0:1], off nt
	s_cmp_eq_u64 s[4:5], 0
	global_load_dword v1, v[2:3], off offset:2048 nt
	v_add_co_u32_e32 v2, vcc, s6, v66
	s_mov_b32 s6, 0xa07000
	s_nop 0
	v_addc_co_u32_e32 v3, vcc, 0, v67, vcc
	v_add_co_u32_e32 v4, vcc, s6, v66
	s_mov_b32 s6, 0xa0a000
	s_nop 0
	v_addc_co_u32_e32 v5, vcc, 0, v67, vcc
	global_load_dword v2, v[2:3], off nt
	s_nop 0
	global_load_dword v3, v[4:5], off offset:2048 nt
	v_add_co_u32_e32 v4, vcc, s6, v66
	s_mov_b32 s6, 0xa0c000
	s_nop 0
	v_addc_co_u32_e32 v5, vcc, 0, v67, vcc
	v_add_co_u32_e32 v6, vcc, s6, v66
	global_load_dword v4, v[4:5], off nt
	s_nop 0
	v_addc_co_u32_e32 v7, vcc, 0, v67, vcc
	global_load_dword v5, v[6:7], off offset:2048 nt
	v_add_co_u32_e32 v6, vcc, s33, v66
	s_nop 1
	v_addc_co_u32_e32 v7, vcc, 0, v67, vcc
	v_add_co_u32_e32 v8, vcc, s34, v66
	global_load_dword v6, v[6:7], off nt
	s_nop 0
	v_addc_co_u32_e32 v9, vcc, 0, v67, vcc
	global_load_dword v7, v[8:9], off offset:2048 nt
	v_add_co_u32_e32 v8, vcc, s35, v66
	s_nop 1
	v_addc_co_u32_e32 v9, vcc, 0, v67, vcc
	v_add_co_u32_e32 v10, vcc, s36, v66
	global_load_dword v8, v[8:9], off nt
	s_nop 0
	v_addc_co_u32_e32 v11, vcc, 0, v67, vcc
	global_load_dword v9, v[10:11], off offset:2048 nt
	v_add_co_u32_e32 v10, vcc, s37, v66
	s_nop 1
	v_addc_co_u32_e32 v11, vcc, 0, v67, vcc
	v_add_co_u32_e32 v14, vcc, s38, v66
	global_load_dword v10, v[10:11], off nt
	s_nop 0
	v_addc_co_u32_e32 v15, vcc, 0, v67, vcc
	global_load_dword v11, v[14:15], off offset:2048 nt
	v_add_co_u32_e32 v14, vcc, s39, v66
	s_nop 1
	v_addc_co_u32_e32 v15, vcc, 0, v67, vcc
	v_add_co_u32_e32 v16, vcc, s40, v66
	global_load_dword v14, v[14:15], off nt
	s_nop 0
	v_addc_co_u32_e32 v17, vcc, 0, v67, vcc
	global_load_dword v15, v[16:17], off offset:2048 nt
	v_add_co_u32_e32 v16, vcc, s41, v66
	s_nop 1
	v_addc_co_u32_e32 v17, vcc, 0, v67, vcc
	v_add_co_u32_e32 v18, vcc, s42, v66
	global_load_dword v16, v[16:17], off nt
	s_nop 0
	v_addc_co_u32_e32 v19, vcc, 0, v67, vcc
	global_load_dword v17, v[18:19], off offset:2048 nt
	v_add_co_u32_e32 v18, vcc, s43, v66
	s_nop 1
	v_addc_co_u32_e32 v19, vcc, 0, v67, vcc
	v_add_co_u32_e32 v20, vcc, s44, v66
	global_load_dword v18, v[18:19], off nt
	s_nop 0
	v_addc_co_u32_e32 v21, vcc, 0, v67, vcc
	global_load_dword v19, v[20:21], off offset:2048 nt
	v_add_co_u32_e32 v20, vcc, s45, v66
	s_nop 1
	v_addc_co_u32_e32 v21, vcc, 0, v67, vcc
	v_add_co_u32_e32 v22, vcc, s46, v66
	global_load_dword v20, v[20:21], off nt
	s_nop 0
	v_addc_co_u32_e32 v23, vcc, 0, v67, vcc
	global_load_dword v21, v[22:23], off offset:2048 nt
	v_add_co_u32_e32 v22, vcc, s47, v66
	s_nop 1
	v_addc_co_u32_e32 v23, vcc, 0, v67, vcc
	v_add_co_u32_e32 v24, vcc, s48, v66
	global_load_dword v22, v[22:23], off nt
	s_nop 0
	v_addc_co_u32_e32 v25, vcc, 0, v67, vcc
	global_load_dword v23, v[24:25], off offset:2048 nt
	v_add_co_u32_e32 v24, vcc, s49, v66
	s_nop 1
	v_addc_co_u32_e32 v25, vcc, 0, v67, vcc
	v_add_co_u32_e32 v26, vcc, s50, v66
	global_load_dword v24, v[24:25], off nt
	s_nop 0
	v_addc_co_u32_e32 v27, vcc, 0, v67, vcc
	global_load_dword v25, v[26:27], off offset:2048 nt
	v_add_co_u32_e32 v26, vcc, s51, v66
	s_nop 1
	v_addc_co_u32_e32 v27, vcc, 0, v67, vcc
	v_add_co_u32_e32 v28, vcc, s52, v66
	global_load_dword v26, v[26:27], off nt
	s_nop 0
	v_addc_co_u32_e32 v29, vcc, 0, v67, vcc
	global_load_dword v27, v[28:29], off offset:2048 nt
	v_add_co_u32_e32 v28, vcc, s53, v66
	s_nop 1
	v_addc_co_u32_e32 v29, vcc, 0, v67, vcc
	v_add_co_u32_e32 v30, vcc, s54, v66
	global_load_dword v28, v[28:29], off nt
	s_nop 0
	v_addc_co_u32_e32 v31, vcc, 0, v67, vcc
	global_load_dword v29, v[30:31], off offset:2048 nt
	v_add_co_u32_e32 v30, vcc, s55, v66
	s_nop 1
	v_addc_co_u32_e32 v31, vcc, 0, v67, vcc
	v_add_co_u32_e32 v32, vcc, s56, v66
	global_load_dword v30, v[30:31], off nt
	s_nop 0
	v_addc_co_u32_e32 v33, vcc, 0, v67, vcc
	global_load_dword v31, v[32:33], off offset:2048 nt
	v_add_co_u32_e32 v32, vcc, s57, v66
	s_nop 1
	v_addc_co_u32_e32 v33, vcc, 0, v67, vcc
	v_add_co_u32_e32 v34, vcc, s58, v66
	global_load_dword v32, v[32:33], off nt
	s_nop 0
	v_addc_co_u32_e32 v35, vcc, 0, v67, vcc
	global_load_dword v33, v[34:35], off offset:2048 nt
	v_add_co_u32_e32 v34, vcc, s59, v66
	s_nop 1
	v_addc_co_u32_e32 v35, vcc, 0, v67, vcc
	v_add_co_u32_e32 v36, vcc, s60, v66
	global_load_dword v34, v[34:35], off nt
	s_nop 0
	v_addc_co_u32_e32 v37, vcc, 0, v67, vcc
	global_load_dword v35, v[36:37], off offset:2048 nt
	v_add_co_u32_e32 v36, vcc, s61, v66
	s_nop 1
	v_addc_co_u32_e32 v37, vcc, 0, v67, vcc
	v_add_co_u32_e32 v38, vcc, s62, v66
	global_load_dword v36, v[36:37], off nt
	s_nop 0
	v_addc_co_u32_e32 v39, vcc, 0, v67, vcc
	global_load_dword v37, v[38:39], off offset:2048 nt
	v_add_co_u32_e32 v38, vcc, s63, v66
	s_nop 1
	v_addc_co_u32_e32 v39, vcc, 0, v67, vcc
	v_add_co_u32_e32 v40, vcc, s64, v66
	global_load_dword v38, v[38:39], off nt
	s_nop 0
	v_addc_co_u32_e32 v41, vcc, 0, v67, vcc
	global_load_dword v39, v[40:41], off offset:2048 nt
; __device__ __forceinline__ void transpose_item(const float* __restrict__ W, int K, int N, bf16* __restrict__ WT, const float* __restrict__ ksc, int mode, int row_off, int item, int lane) {
;     ...
;     for (int i = 0; i < 64; ++i) v[i] = __builtin_nontemporal_load(src + (size_t)i * N);
;     if (ksc) {
	v_add_co_u32_e32 v40, vcc, s65, v66
	s_nop 1
	v_addc_co_u32_e32 v41, vcc, 0, v67, vcc
	v_add_co_u32_e32 v42, vcc, s66, v66
	global_load_dword v40, v[40:41], off nt
	s_nop 0
	v_addc_co_u32_e32 v43, vcc, 0, v67, vcc
	global_load_dword v41, v[42:43], off offset:2048 nt
	v_add_co_u32_e32 v42, vcc, s67, v66
	s_nop 1
	v_addc_co_u32_e32 v43, vcc, 0, v67, vcc
	v_add_co_u32_e32 v44, vcc, s68, v66
	global_load_dword v42, v[42:43], off nt
	s_nop 0
	v_addc_co_u32_e32 v45, vcc, 0, v67, vcc
	global_load_dword v43, v[44:45], off offset:2048 nt
	v_add_co_u32_e32 v44, vcc, s69, v66
	s_nop 1
	v_addc_co_u32_e32 v45, vcc, 0, v67, vcc
	v_add_co_u32_e32 v46, vcc, s70, v66
	global_load_dword v44, v[44:45], off nt
	s_nop 0
	v_addc_co_u32_e32 v47, vcc, 0, v67, vcc
	global_load_dword v45, v[46:47], off offset:2048 nt
	v_add_co_u32_e32 v46, vcc, s71, v66
	s_nop 1
	v_addc_co_u32_e32 v47, vcc, 0, v67, vcc
	v_add_co_u32_e32 v48, vcc, s72, v66
	global_load_dword v46, v[46:47], off nt
	s_nop 0
	v_addc_co_u32_e32 v49, vcc, 0, v67, vcc
	global_load_dword v47, v[48:49], off offset:2048 nt
	v_add_co_u32_e32 v48, vcc, s73, v66
	s_nop 1
	v_addc_co_u32_e32 v49, vcc, 0, v67, vcc
	v_add_co_u32_e32 v50, vcc, s74, v66
	global_load_dword v48, v[48:49], off nt
	s_nop 0
	v_addc_co_u32_e32 v51, vcc, 0, v67, vcc
	global_load_dword v49, v[50:51], off offset:2048 nt
	v_add_co_u32_e32 v50, vcc, s75, v66
	s_nop 1
	v_addc_co_u32_e32 v51, vcc, 0, v67, vcc
	v_add_co_u32_e32 v52, vcc, s76, v66
	global_load_dword v50, v[50:51], off nt
	s_nop 0
	v_addc_co_u32_e32 v53, vcc, 0, v67, vcc
	global_load_dword v51, v[52:53], off offset:2048 nt
	v_add_co_u32_e32 v52, vcc, s77, v66
	s_nop 1
	v_addc_co_u32_e32 v53, vcc, 0, v67, vcc
	v_add_co_u32_e32 v54, vcc, s78, v66
	global_load_dword v52, v[52:53], off nt
	s_nop 0
	v_addc_co_u32_e32 v55, vcc, 0, v67, vcc
	global_load_dword v53, v[54:55], off offset:2048 nt
	v_add_co_u32_e32 v54, vcc, s79, v66
	s_nop 1
	v_addc_co_u32_e32 v55, vcc, 0, v67, vcc
	v_add_co_u32_e32 v56, vcc, s80, v66
	global_load_dword v54, v[54:55], off nt
	s_nop 0
	v_addc_co_u32_e32 v57, vcc, 0, v67, vcc
	global_load_dword v55, v[56:57], off offset:2048 nt
	v_add_co_u32_e32 v56, vcc, s81, v66
	s_nop 1
	v_addc_co_u32_e32 v57, vcc, 0, v67, vcc
	v_add_co_u32_e32 v58, vcc, s82, v66
	global_load_dword v56, v[56:57], off nt
	s_nop 0
	v_addc_co_u32_e32 v59, vcc, 0, v67, vcc
	global_load_dword v57, v[58:59], off offset:2048 nt
	v_add_co_u32_e32 v58, vcc, s83, v66
	s_nop 1
	v_addc_co_u32_e32 v59, vcc, 0, v67, vcc
	v_add_co_u32_e32 v60, vcc, s84, v66
	global_load_dword v58, v[58:59], off nt
	s_nop 0
	v_addc_co_u32_e32 v61, vcc, 0, v67, vcc
	global_load_dword v59, v[60:61], off offset:2048 nt
	v_add_co_u32_e32 v60, vcc, s85, v66
	s_nop 1
	v_addc_co_u32_e32 v61, vcc, 0, v67, vcc
	v_add_co_u32_e32 v62, vcc, s86, v66
	global_load_dword v60, v[60:61], off nt
	s_nop 0
	v_addc_co_u32_e32 v63, vcc, 0, v67, vcc
	global_load_dword v61, v[62:63], off offset:2048 nt
	v_add_co_u32_e32 v62, vcc, s87, v66
	s_nop 1
	v_addc_co_u32_e32 v63, vcc, 0, v67, vcc
	v_add_co_u32_e32 v64, vcc, s88, v66
	global_load_dword v62, v[62:63], off nt
	s_nop 0
	v_addc_co_u32_e32 v65, vcc, 0, v67, vcc
	global_load_dword v63, v[64:65], off offset:2048 nt
	v_add_co_u32_e32 v64, vcc, s89, v66
	s_nop 1
	v_addc_co_u32_e32 v65, vcc, 0, v67, vcc
	v_add_co_u32_e32 v66, vcc, s90, v66
	global_load_dword v64, v[64:65], off nt
	s_nop 0
	v_addc_co_u32_e32 v67, vcc, 0, v67, vcc
	global_load_dword v65, v[66:67], off offset:2048 nt
	s_cbranch_scc1 .Lcx1_87
; __device__ __forceinline__ void transpose_item(const float* __restrict__ W, int K, int N, bf16* __restrict__ WT, const float* __restrict__ ksc, int mode, int row_off, int item, int lane) {
;     ...
;     if (ksc) {
; #pragma unroll
;         for (int i = 0; i < 64; ++i) v[i] *= ksc[k0 + i];
;     }
	s_lshl_b64 s[6:7], s[24:25], 2
	s_add_u32 s6, s4, s6
	s_addc_u32 s7, s5, s7
	s_add_u32 s4, s6, 0x1000
	s_addc_u32 s5, s7, 0
	global_load_dwordx4 v[66:69], v13, s[4:5] offset:48
	global_load_dwordx4 v[70:73], v13, s[4:5] offset:32
	global_load_dwordx4 v[74:77], v13, s[4:5] offset:16
	global_load_dwordx4 v[86:89], v83, s[6:7]
	global_load_dwordx4 v[184:187], v13, s[4:5] offset:112
	global_load_dwordx4 v[188:191], v13, s[4:5] offset:96
	global_load_dwordx4 v[192:195], v13, s[4:5] offset:80
	global_load_dwordx4 v[196:199], v13, s[4:5] offset:64
	global_load_dwordx4 v[204:207], v13, s[4:5] offset:176
	global_load_dwordx4 v[208:211], v13, s[4:5] offset:160
	global_load_dwordx4 v[212:215], v13, s[4:5] offset:144
	global_load_dwordx4 v[216:219], v13, s[4:5] offset:128
	global_load_dwordx4 v[220:223], v13, s[4:5] offset:240
	global_load_dwordx4 v[224:227], v13, s[4:5] offset:224
	global_load_dwordx4 v[228:231], v13, s[4:5] offset:208
	global_load_dwordx4 v[232:235], v13, s[4:5] offset:192
	s_waitcnt vmcnt(0)
	v_pk_mul_f32 v[14:15], v[14:15], v[66:67]
	s_waitcnt vmcnt(2)
	v_pk_mul_f32 v[8:9], v[8:9], v[70:71]
	s_waitcnt vmcnt(1)
	v_pk_mul_f32 v[4:5], v[4:5], v[74:75]
	s_waitcnt vmcnt(0)
	v_pk_mul_f32 v[0:1], v[0:1], v[86:87]
	v_pk_mul_f32 v[2:3], v[2:3], v[88:89]
	v_pk_mul_f32 v[6:7], v[6:7], v[76:77]
	v_pk_mul_f32 v[10:11], v[10:11], v[72:73]
	v_pk_mul_f32 v[16:17], v[16:17], v[68:69]
	v_mov_b32_e32 v66, v184
	v_mov_b32_e32 v67, v185
	v_mov_b32_e32 v68, v186
	v_mov_b32_e32 v69, v187
	v_mov_b32_e32 v70, v188
	v_mov_b32_e32 v71, v189
	v_mov_b32_e32 v72, v190
	v_mov_b32_e32 v73, v191
	v_mov_b32_e32 v74, v192
	v_mov_b32_e32 v75, v193
	v_mov_b32_e32 v76, v194
	v_mov_b32_e32 v77, v195
	v_mov_b32_e32 v86, v196
	v_mov_b32_e32 v87, v197
	v_mov_b32_e32 v88, v198
	v_mov_b32_e32 v89, v199
	s_waitcnt vmcnt(3)
	v_pk_mul_f32 v[30:31], v[30:31], v[66:67]
	s_waitcnt vmcnt(2)
	v_pk_mul_f32 v[26:27], v[26:27], v[70:71]
	s_waitcnt vmcnt(1)
	v_pk_mul_f32 v[22:23], v[22:23], v[74:75]
	s_waitcnt vmcnt(0)
	v_pk_mul_f32 v[18:19], v[18:19], v[86:87]
	v_pk_mul_f32 v[20:21], v[20:21], v[88:89]
	v_pk_mul_f32 v[24:25], v[24:25], v[76:77]
	v_pk_mul_f32 v[28:29], v[28:29], v[72:73]
	v_pk_mul_f32 v[32:33], v[32:33], v[68:69]
	v_mov_b32_e32 v66, v204
	v_mov_b32_e32 v67, v205
	v_mov_b32_e32 v68, v206
	v_mov_b32_e32 v69, v207
	v_mov_b32_e32 v70, v208
	v_mov_b32_e32 v71, v209
	v_mov_b32_e32 v72, v210
	v_mov_b32_e32 v73, v211
	v_mov_b32_e32 v74, v212
	v_mov_b32_e32 v75, v213
	v_mov_b32_e32 v76, v214
	v_mov_b32_e32 v77, v215
	v_mov_b32_e32 v86, v216
	v_mov_b32_e32 v87, v217
	v_mov_b32_e32 v88, v218
	v_mov_b32_e32 v89, v219
	s_waitcnt vmcnt(3)
	v_pk_mul_f32 v[46:47], v[46:47], v[66:67]
	s_waitcnt vmcnt(2)
	v_pk_mul_f32 v[42:43], v[42:43], v[70:71]
	s_waitcnt vmcnt(1)
	v_pk_mul_f32 v[38:39], v[38:39], v[74:75]
	s_waitcnt vmcnt(0)
	v_pk_mul_f32 v[34:35], v[34:35], v[86:87]
	v_pk_mul_f32 v[36:37], v[36:37], v[88:89]
	v_pk_mul_f32 v[40:41], v[40:41], v[76:77]
	v_pk_mul_f32 v[44:45], v[44:45], v[72:73]
	v_pk_mul_f32 v[48:49], v[48:49], v[68:69]
	v_mov_b32_e32 v66, v220
	v_mov_b32_e32 v67, v221
	v_mov_b32_e32 v68, v222
	v_mov_b32_e32 v69, v223
	v_mov_b32_e32 v70, v224
	v_mov_b32_e32 v71, v225
	v_mov_b32_e32 v72, v226
	v_mov_b32_e32 v73, v227
	v_mov_b32_e32 v74, v228
	v_mov_b32_e32 v75, v229
	v_mov_b32_e32 v76, v230
	v_mov_b32_e32 v77, v231
	v_mov_b32_e32 v86, v232
	v_mov_b32_e32 v87, v233
	v_mov_b32_e32 v88, v234
	v_mov_b32_e32 v89, v235
	s_waitcnt vmcnt(3)
	v_pk_mul_f32 v[62:63], v[62:63], v[66:67]
	s_waitcnt vmcnt(2)
	v_pk_mul_f32 v[58:59], v[58:59], v[70:71]
	s_waitcnt vmcnt(1)
	v_pk_mul_f32 v[54:55], v[54:55], v[74:75]
	s_waitcnt vmcnt(0)
	v_pk_mul_f32 v[50:51], v[50:51], v[86:87]
	v_pk_mul_f32 v[52:53], v[52:53], v[88:89]
	v_pk_mul_f32 v[56:57], v[56:57], v[76:77]
	v_pk_mul_f32 v[60:61], v[60:61], v[72:73]
	v_pk_mul_f32 v[64:65], v[64:65], v[68:69]
	s_branch .Lcx1_87

; __device__ __forceinline__ void transpose_item(const float* __restrict__ W, int K, int N, bf16* __restrict__ WT, const float* __restrict__ ksc, int mode, int row_off, int item, int lane) {
;     const int nblk = N / 64, kb = item / nblk, nb = item % nblk, k0 = 64 * kb, n = 64 * nb + lane;
;     const float* src = W + (size_t)k0 * N + n;
;     float v[64];
; #pragma unroll
;     for (int i = 0; i < 64; ++i) v[i] = __builtin_nontemporal_load(src + (size_t)i * N);
; __device__ __forceinline__ void convert_layer(ArgsP a, int L, int first, int stride, int lane) {
;     ...
;         else if (r < I_IN + I_OUT + I_GU) transpose_item(a->in[18] + (size_t)L * D * GU, D, GU, WGU + (size_t)L * GU * D, a->in[17] + L * D, 2, 0, r - I_IN - I_OUT, lane);
.LBB0_685:
	s_andn2_b64 vcc, exec, s[20:21]
	s_cbranch_vccnz .LBB0_693
	s_add_i32 s14, s1, 0xfc80
	s_and_b32 s15, s14, 0xffff
	s_mul_i32 s15, s15, 0xba2f
	s_load_dwordx4 s[20:23], s[24:25], 0x88
	s_lshr_b32 s40, s15, 16
	s_lshr_b32 s15, s15, 22
	s_mulk_i32 s15, 0x58
	s_sub_i32 s14, s14, s15
	s_and_b32 s85, s14, 0xffff
	s_and_b32 s40, s40, 0xffc0
	s_lshl_b32 s84, s85, 6
	s_mul_i32 s14, s40, 0x5800
	v_or_b32_e32 v78, s84, v80
	s_waitcnt lgkmcnt(0)
	s_add_u32 s22, s22, s14
	s_addc_u32 s23, s23, 0
	v_lshlrev_b32_e32 v12, 2, v78
	v_lshl_add_u64 v[0:1], s[22:23], 0, v[12:13]
	s_mov_b32 s14, 0x2c00000
	v_add_co_u32_e32 v2, vcc, s14, v0
	s_mov_b32 s14, 0x2c05000
	s_nop 0
	v_addc_co_u32_e32 v3, vcc, 0, v1, vcc
	global_load_dword v16, v[2:3], off nt
	v_add_co_u32_e32 v2, vcc, s14, v0
	s_mov_b32 s14, 0x2c0b000
	s_nop 0
	v_addc_co_u32_e32 v3, vcc, 0, v1, vcc
	global_load_dword v14, v[2:3], off offset:2048 nt
	v_add_co_u32_e32 v2, vcc, s14, v0
	s_mov_b32 s14, 0x2c10000
	s_nop 0
	v_addc_co_u32_e32 v3, vcc, 0, v1, vcc
	global_load_dword v17, v[2:3], off nt
	v_add_co_u32_e32 v2, vcc, s14, v0
	s_mov_b32 s14, 0x2c16000
	s_nop 0
	v_addc_co_u32_e32 v3, vcc, 0, v1, vcc
	global_load_dword v15, v[2:3], off offset:2048 nt
	v_add_co_u32_e32 v2, vcc, s14, v0
	s_mov_b32 s14, 0x2c1b000
	s_nop 0
	v_addc_co_u32_e32 v3, vcc, 0, v1, vcc
	global_load_dword v20, v[2:3], off nt
	v_add_co_u32_e32 v2, vcc, s14, v0
	s_mov_b32 s14, 0x2c21000
	s_nop 0
	v_addc_co_u32_e32 v3, vcc, 0, v1, vcc
	global_load_dword v18, v[2:3], off offset:2048 nt
	v_add_co_u32_e32 v2, vcc, s14, v0
	s_mov_b32 s14, 0x2c26000
	s_nop 0
	v_addc_co_u32_e32 v3, vcc, 0, v1, vcc
	global_load_dword v21, v[2:3], off nt
	v_add_co_u32_e32 v2, vcc, s14, v0
	s_mov_b32 s14, 0x2c2c000
	s_nop 0
	v_addc_co_u32_e32 v3, vcc, 0, v1, vcc
	global_load_dword v19, v[2:3], off offset:2048 nt
	v_add_co_u32_e32 v2, vcc, s14, v0
	s_mov_b32 s14, 0x2c31000
	s_nop 0
	v_addc_co_u32_e32 v3, vcc, 0, v1, vcc
	global_load_dword v24, v[2:3], off nt
	v_add_co_u32_e32 v2, vcc, s14, v0
	s_mov_b32 s14, 0x2c37000
	s_nop 0
	v_addc_co_u32_e32 v3, vcc, 0, v1, vcc
	global_load_dword v22, v[2:3], off offset:2048 nt
	v_add_co_u32_e32 v2, vcc, s14, v0
	s_mov_b32 s14, 0x2c3c000
	s_nop 0
	v_addc_co_u32_e32 v3, vcc, 0, v1, vcc
	global_load_dword v25, v[2:3], off nt
	v_add_co_u32_e32 v2, vcc, s14, v0
	s_mov_b32 s14, 0x2c42000
	s_nop 0
	v_addc_co_u32_e32 v3, vcc, 0, v1, vcc
	global_load_dword v23, v[2:3], off offset:2048 nt
	v_add_co_u32_e32 v2, vcc, s14, v0
	s_mov_b32 s14, 0x2c47000
	s_nop 0
	v_addc_co_u32_e32 v3, vcc, 0, v1, vcc
	global_load_dword v28, v[2:3], off nt
	v_add_co_u32_e32 v2, vcc, s14, v0
	s_mov_b32 s14, 0x2c4d000
	s_nop 0
	v_addc_co_u32_e32 v3, vcc, 0, v1, vcc
	global_load_dword v26, v[2:3], off offset:2048 nt
	v_add_co_u32_e32 v2, vcc, s14, v0
	s_mov_b32 s14, 0x2c52000
	s_nop 0
	v_addc_co_u32_e32 v3, vcc, 0, v1, vcc
	global_load_dword v29, v[2:3], off nt
	v_add_co_u32_e32 v2, vcc, s14, v0
	s_mov_b32 s14, 0x2c58000
	s_nop 0
	v_addc_co_u32_e32 v3, vcc, 0, v1, vcc
	global_load_dword v27, v[2:3], off offset:2048 nt
	v_add_co_u32_e32 v2, vcc, s14, v0
	s_mov_b32 s14, 0x2c5d000
	s_nop 0
	v_addc_co_u32_e32 v3, vcc, 0, v1, vcc
	global_load_dword v32, v[2:3], off nt
	v_add_co_u32_e32 v2, vcc, s14, v0
	s_mov_b32 s14, 0x2c63000
	s_nop 0
	v_addc_co_u32_e32 v3, vcc, 0, v1, vcc
	global_load_dword v30, v[2:3], off offset:2048 nt
	v_add_co_u32_e32 v2, vcc, s14, v0
	s_mov_b32 s14, 0x2c68000
	s_nop 0
	v_addc_co_u32_e32 v3, vcc, 0, v1, vcc
	global_load_dword v33, v[2:3], off nt
	v_add_co_u32_e32 v2, vcc, s14, v0
	s_mov_b32 s14, 0x2c6e000
	s_nop 0
	v_addc_co_u32_e32 v3, vcc, 0, v1, vcc
	global_load_dword v31, v[2:3], off offset:2048 nt
	v_add_co_u32_e32 v2, vcc, s14, v0
	s_mov_b32 s14, 0x2c73000
	s_nop 0
	v_addc_co_u32_e32 v3, vcc, 0, v1, vcc
	global_load_dword v36, v[2:3], off nt
	v_add_co_u32_e32 v2, vcc, s14, v0
	s_mov_b32 s14, 0x2c79000
	s_nop 0
	v_addc_co_u32_e32 v3, vcc, 0, v1, vcc
	global_load_dword v34, v[2:3], off offset:2048 nt
	v_add_co_u32_e32 v2, vcc, s14, v0
	s_mov_b32 s14, 0x2c7e000
	s_nop 0
	v_addc_co_u32_e32 v3, vcc, 0, v1, vcc
	global_load_dword v37, v[2:3], off nt
	v_add_co_u32_e32 v2, vcc, s14, v0
	s_mov_b32 s14, 0x2c84000
	s_nop 0
	v_addc_co_u32_e32 v3, vcc, 0, v1, vcc
	global_load_dword v35, v[2:3], off offset:2048 nt
	v_add_co_u32_e32 v2, vcc, s14, v0
	s_mov_b32 s14, 0x2c89000
	s_nop 0
	v_addc_co_u32_e32 v3, vcc, 0, v1, vcc
	global_load_dword v40, v[2:3], off nt
	v_add_co_u32_e32 v2, vcc, s14, v0
	s_mov_b32 s14, 0x2c8f000
	s_nop 0
	v_addc_co_u32_e32 v3, vcc, 0, v1, vcc
	global_load_dword v38, v[2:3], off offset:2048 nt
	v_add_co_u32_e32 v2, vcc, s14, v0
	s_mov_b32 s14, 0x2c94000
	s_nop 0
	v_addc_co_u32_e32 v3, vcc, 0, v1, vcc
	global_load_dword v41, v[2:3], off nt
	v_add_co_u32_e32 v2, vcc, s14, v0
	s_mov_b32 s14, 0x2c9a000
	s_nop 0
	v_addc_co_u32_e32 v3, vcc, 0, v1, vcc
	global_load_dword v39, v[2:3], off offset:2048 nt
	v_add_co_u32_e32 v2, vcc, s14, v0
	s_mov_b32 s14, 0x2c9f000
	s_nop 0
	v_addc_co_u32_e32 v3, vcc, 0, v1, vcc
	global_load_dword v44, v[2:3], off nt
	v_add_co_u32_e32 v2, vcc, s14, v0
	s_mov_b32 s14, 0x2ca5000
	s_nop 0
	v_addc_co_u32_e32 v3, vcc, 0, v1, vcc
	global_load_dword v42, v[2:3], off offset:2048 nt
	v_add_co_u32_e32 v2, vcc, s14, v0
	s_mov_b32 s14, 0x2caa000
	s_nop 0
	v_addc_co_u32_e32 v3, vcc, 0, v1, vcc
	global_load_dword v45, v[2:3], off nt
	v_add_co_u32_e32 v2, vcc, s14, v0
	s_mov_b32 s14, 0x2cb0000
	s_nop 0
	v_addc_co_u32_e32 v3, vcc, 0, v1, vcc
	global_load_dword v43, v[2:3], off offset:2048 nt
	v_add_co_u32_e32 v2, vcc, s14, v0
	s_mov_b32 s14, 0x2cb5000
	s_nop 0
	v_addc_co_u32_e32 v3, vcc, 0, v1, vcc
; __device__ __forceinline__ void transpose_item(const float* __restrict__ W, int K, int N, bf16* __restrict__ WT, const float* __restrict__ ksc, int mode, int row_off, int item, int lane) {
;     ...
;     for (int i = 0; i < 64; ++i) v[i] = __builtin_nontemporal_load(src + (size_t)i * N);
;     if (ksc) {
	global_load_dword v48, v[2:3], off nt
	v_add_co_u32_e32 v2, vcc, s14, v0
	s_mov_b32 s14, 0x2cbb000
	s_nop 0
	v_addc_co_u32_e32 v3, vcc, 0, v1, vcc
	global_load_dword v46, v[2:3], off offset:2048 nt
	v_add_co_u32_e32 v2, vcc, s14, v0
	s_mov_b32 s14, 0x2cc0000
	s_nop 0
	v_addc_co_u32_e32 v3, vcc, 0, v1, vcc
	global_load_dword v49, v[2:3], off nt
	v_add_co_u32_e32 v2, vcc, s14, v0
	s_mov_b32 s14, 0x2cc6000
	s_nop 0
	v_addc_co_u32_e32 v3, vcc, 0, v1, vcc
	global_load_dword v47, v[2:3], off offset:2048 nt
	v_add_co_u32_e32 v2, vcc, s14, v0
	s_mov_b32 s14, 0x2ccb000
	s_nop 0
	v_addc_co_u32_e32 v3, vcc, 0, v1, vcc
	global_load_dword v52, v[2:3], off nt
	v_add_co_u32_e32 v2, vcc, s14, v0
	s_mov_b32 s14, 0x2cd1000
	s_nop 0
	v_addc_co_u32_e32 v3, vcc, 0, v1, vcc
	global_load_dword v50, v[2:3], off offset:2048 nt
	v_add_co_u32_e32 v2, vcc, s14, v0
	s_mov_b32 s14, 0x2cd6000
	s_nop 0
	v_addc_co_u32_e32 v3, vcc, 0, v1, vcc
	global_load_dword v53, v[2:3], off nt
	v_add_co_u32_e32 v2, vcc, s14, v0
	s_mov_b32 s14, 0x2cdc000
	s_nop 0
	v_addc_co_u32_e32 v3, vcc, 0, v1, vcc
	global_load_dword v51, v[2:3], off offset:2048 nt
	v_add_co_u32_e32 v2, vcc, s14, v0
	s_mov_b32 s14, 0x2ce1000
	s_nop 0
	v_addc_co_u32_e32 v3, vcc, 0, v1, vcc
	global_load_dword v56, v[2:3], off nt
	v_add_co_u32_e32 v2, vcc, s14, v0
	s_mov_b32 s14, 0x2ce7000
	s_nop 0
	v_addc_co_u32_e32 v3, vcc, 0, v1, vcc
	global_load_dword v54, v[2:3], off offset:2048 nt
	v_add_co_u32_e32 v2, vcc, s14, v0
	s_mov_b32 s14, 0x2cec000
	s_nop 0
	v_addc_co_u32_e32 v3, vcc, 0, v1, vcc
	global_load_dword v57, v[2:3], off nt
	v_add_co_u32_e32 v2, vcc, s14, v0
	s_mov_b32 s14, 0x2cf2000
	s_nop 0
	v_addc_co_u32_e32 v3, vcc, 0, v1, vcc
	global_load_dword v55, v[2:3], off offset:2048 nt
	v_add_co_u32_e32 v2, vcc, s14, v0
	s_mov_b32 s14, 0x2cf7000
	s_nop 0
	v_addc_co_u32_e32 v3, vcc, 0, v1, vcc
	global_load_dword v60, v[2:3], off nt
	v_add_co_u32_e32 v2, vcc, s14, v0
	s_mov_b32 s14, 0x2cfd000
	s_nop 0
	v_addc_co_u32_e32 v3, vcc, 0, v1, vcc
	global_load_dword v58, v[2:3], off offset:2048 nt
	v_add_co_u32_e32 v2, vcc, s14, v0
	s_mov_b32 s14, 0x2d02000
	s_nop 0
	v_addc_co_u32_e32 v3, vcc, 0, v1, vcc
	global_load_dword v61, v[2:3], off nt
	v_add_co_u32_e32 v2, vcc, s14, v0
	s_mov_b32 s14, 0x2d08000
	s_nop 0
	v_addc_co_u32_e32 v3, vcc, 0, v1, vcc
	global_load_dword v59, v[2:3], off offset:2048 nt
	v_add_co_u32_e32 v2, vcc, s14, v0
	s_mov_b32 s14, 0x2d0d000
	s_nop 0
	v_addc_co_u32_e32 v3, vcc, 0, v1, vcc
	global_load_dword v64, v[2:3], off nt
	v_add_co_u32_e32 v2, vcc, s14, v0
	s_mov_b32 s14, 0x2d13000
	s_nop 0
	v_addc_co_u32_e32 v3, vcc, 0, v1, vcc
	global_load_dword v62, v[2:3], off offset:2048 nt
	v_add_co_u32_e32 v2, vcc, s14, v0
	s_mov_b32 s14, 0x2d18000
	s_nop 0
	v_addc_co_u32_e32 v3, vcc, 0, v1, vcc
	global_load_dword v65, v[2:3], off nt
	v_add_co_u32_e32 v2, vcc, s14, v0
	s_mov_b32 s14, 0x2d1e000
	s_nop 0
	v_addc_co_u32_e32 v3, vcc, 0, v1, vcc
	global_load_dword v63, v[2:3], off offset:2048 nt
	v_add_co_u32_e32 v2, vcc, s14, v0
	s_mov_b32 s14, 0x2d23000
	s_nop 0
	v_addc_co_u32_e32 v3, vcc, 0, v1, vcc
	global_load_dword v68, v[2:3], off nt
	v_add_co_u32_e32 v2, vcc, s14, v0
	s_mov_b32 s14, 0x2d29000
	s_nop 0
	v_addc_co_u32_e32 v3, vcc, 0, v1, vcc
	global_load_dword v66, v[2:3], off offset:2048 nt
	v_add_co_u32_e32 v2, vcc, s14, v0
	s_mov_b32 s14, 0x2d2e000
	s_nop 0
	v_addc_co_u32_e32 v3, vcc, 0, v1, vcc
	global_load_dword v69, v[2:3], off nt
	v_add_co_u32_e32 v2, vcc, s14, v0
	s_mov_b32 s14, 0x2d34000
	s_nop 0
	v_addc_co_u32_e32 v3, vcc, 0, v1, vcc
	global_load_dword v67, v[2:3], off offset:2048 nt
	v_add_co_u32_e32 v2, vcc, s14, v0
	s_mov_b32 s14, 0x2d39000
	s_nop 0
	v_addc_co_u32_e32 v3, vcc, 0, v1, vcc
	global_load_dword v70, v[2:3], off nt
	v_add_co_u32_e32 v2, vcc, s14, v0
	s_mov_b32 s14, 0x2d3f000
	s_nop 0
	v_addc_co_u32_e32 v3, vcc, 0, v1, vcc
	global_load_dword v72, v[2:3], off offset:2048 nt
	v_add_co_u32_e32 v2, vcc, s14, v0
	s_mov_b32 s14, 0x2d44000
	s_nop 0
	v_addc_co_u32_e32 v3, vcc, 0, v1, vcc
	global_load_dword v71, v[2:3], off nt
	v_add_co_u32_e32 v2, vcc, s14, v0
	s_mov_b32 s14, 0x2d4a000
	s_nop 0
	v_addc_co_u32_e32 v3, vcc, 0, v1, vcc
	global_load_dword v73, v[2:3], off offset:2048 nt
	v_add_co_u32_e32 v2, vcc, s14, v0
	s_mov_b32 s14, 0x2d4f000
	s_nop 0
	v_addc_co_u32_e32 v3, vcc, 0, v1, vcc
	global_load_dword v74, v[2:3], off nt
	v_add_co_u32_e32 v2, vcc, s14, v0
	s_mov_b32 s14, 0x2d55000
	s_nop 0
	v_addc_co_u32_e32 v3, vcc, 0, v1, vcc
	global_load_dword v75, v[2:3], off offset:2048 nt
	v_add_co_u32_e32 v2, vcc, s14, v0
	s_mov_b32 s14, 0x2d5a000
	s_nop 0
	v_addc_co_u32_e32 v3, vcc, 0, v1, vcc
	v_add_co_u32_e32 v0, vcc, s14, v0
	global_load_dword v76, v[2:3], off nt
	s_nop 0
	v_addc_co_u32_e32 v1, vcc, 0, v1, vcc
	global_load_dword v77, v[0:1], off offset:2048 nt
	s_cmp_eq_u64 s[20:21], 0
	s_cbranch_scc1 .LBB0_688
; __device__ __forceinline__ void transpose_item(const float* __restrict__ W, int K, int N, bf16* __restrict__ WT, const float* __restrict__ ksc, int mode, int row_off, int item, int lane) {
;     ...
;     if (ksc) {
; #pragma unroll
;         for (int i = 0; i < 64; ++i) v[i] *= ksc[k0 + i];
;     }
	s_lshl_b32 s14, s40, 2
	s_add_u32 s22, s20, s14
	s_addc_u32 s23, s21, 0
	s_add_u32 s20, s22, 0x2000
	s_addc_u32 s21, s23, 0
	global_load_dwordx4 v[0:3], v13, s[20:21] offset:48
	global_load_dwordx4 v[4:7], v13, s[20:21] offset:32
	global_load_dwordx4 v[8:11], v13, s[20:21] offset:16
	global_load_dwordx4 v[86:89], v83, s[22:23]
	global_load_dwordx4 v[152:155], v13, s[20:21] offset:112
	global_load_dwordx4 v[156:159], v13, s[20:21] offset:96
	global_load_dwordx4 v[160:163], v13, s[20:21] offset:80
	global_load_dwordx4 v[164:167], v13, s[20:21] offset:64
	global_load_dwordx4 v[168:171], v13, s[20:21] offset:176
	global_load_dwordx4 v[188:191], v13, s[20:21] offset:160
	global_load_dwordx4 v[192:195], v13, s[20:21] offset:144
	global_load_dwordx4 v[204:207], v13, s[20:21] offset:128
	global_load_dwordx4 v[208:211], v13, s[20:21] offset:224
	global_load_dwordx4 v[212:215], v13, s[20:21] offset:208
	global_load_dwordx4 v[216:219], v13, s[20:21] offset:192
	global_load_dwordx4 v[220:223], v13, s[20:21] offset:240
	s_waitcnt vmcnt(0)
	v_mov_b32_e32 v90, v86
	v_mov_b32_e32 v91, v88
	v_mov_b32_e32 v88, v87
	v_mov_b32_e32 v86, v8
	v_mov_b32_e32 v87, v10
	v_mov_b32_e32 v10, v9
	v_mov_b32_e32 v8, v4
	v_mov_b32_e32 v9, v6
	v_mov_b32_e32 v6, v5
	v_mov_b32_e32 v4, v0
	v_mov_b32_e32 v5, v2
	v_mov_b32_e32 v2, v1
	v_pk_mul_f32 v[14:15], v[14:15], v[88:89]
	v_pk_mul_f32 v[20:21], v[20:21], v[86:87]
	v_pk_mul_f32 v[18:19], v[18:19], v[10:11]
	v_pk_mul_f32 v[24:25], v[24:25], v[8:9]
	v_pk_mul_f32 v[22:23], v[22:23], v[6:7]
	v_pk_mul_f32 v[28:29], v[28:29], v[4:5]
	v_pk_mul_f32 v[26:27], v[26:27], v[2:3]
	v_mov_b32_e32 v0, v152
	v_mov_b32_e32 v1, v153
	v_mov_b32_e32 v2, v154
	v_mov_b32_e32 v3, v155
	v_mov_b32_e32 v4, v156
	v_mov_b32_e32 v5, v157
	v_mov_b32_e32 v6, v158
	v_mov_b32_e32 v7, v159
	v_mov_b32_e32 v8, v160
	v_mov_b32_e32 v9, v161
	v_mov_b32_e32 v10, v162
	v_mov_b32_e32 v11, v163
	v_mov_b32_e32 v86, v164
	v_mov_b32_e32 v87, v165
	v_mov_b32_e32 v88, v166
	v_mov_b32_e32 v89, v167
	v_pk_mul_f32 v[16:17], v[16:17], v[90:91]
	s_waitcnt vmcnt(0)
	v_mov_b32_e32 v90, v86
	v_mov_b32_e32 v91, v88
	v_mov_b32_e32 v88, v87
	v_mov_b32_e32 v86, v8
	v_mov_b32_e32 v87, v10
	v_mov_b32_e32 v10, v9
	v_mov_b32_e32 v8, v4
	v_mov_b32_e32 v9, v6
	v_mov_b32_e32 v6, v5
	v_mov_b32_e32 v4, v0
	v_mov_b32_e32 v5, v2
	v_mov_b32_e32 v2, v1
	v_pk_mul_f32 v[30:31], v[30:31], v[88:89]
	v_pk_mul_f32 v[36:37], v[36:37], v[86:87]
	v_pk_mul_f32 v[34:35], v[34:35], v[10:11]
	v_pk_mul_f32 v[40:41], v[40:41], v[8:9]
	v_pk_mul_f32 v[38:39], v[38:39], v[6:7]
	v_pk_mul_f32 v[44:45], v[44:45], v[4:5]
	v_pk_mul_f32 v[42:43], v[42:43], v[2:3]
	v_mov_b32_e32 v0, v168
	v_mov_b32_e32 v1, v169
	v_mov_b32_e32 v2, v170
	v_mov_b32_e32 v3, v171
	v_mov_b32_e32 v4, v188
	v_mov_b32_e32 v5, v189
	v_mov_b32_e32 v6, v190
	v_mov_b32_e32 v7, v191
	v_mov_b32_e32 v8, v192
	v_mov_b32_e32 v9, v193
	v_mov_b32_e32 v10, v194
	v_mov_b32_e32 v11, v195
	v_mov_b32_e32 v86, v204
	v_mov_b32_e32 v87, v205
	v_mov_b32_e32 v88, v206
	v_mov_b32_e32 v89, v207
	v_pk_mul_f32 v[32:33], v[32:33], v[90:91]
	s_waitcnt vmcnt(0)
	v_mov_b32_e32 v90, v86
	v_mov_b32_e32 v91, v88
	v_mov_b32_e32 v88, v87
	v_mov_b32_e32 v86, v8
	v_mov_b32_e32 v87, v10
	v_mov_b32_e32 v10, v9
	v_mov_b32_e32 v8, v4
	v_mov_b32_e32 v9, v6
	v_mov_b32_e32 v6, v5
	v_mov_b32_e32 v4, v0
	v_mov_b32_e32 v5, v2
	v_mov_b32_e32 v2, v1
	v_pk_mul_f32 v[46:47], v[46:47], v[88:89]
	v_pk_mul_f32 v[52:53], v[52:53], v[86:87]
	v_pk_mul_f32 v[50:51], v[50:51], v[10:11]
	v_pk_mul_f32 v[56:57], v[56:57], v[8:9]
	v_pk_mul_f32 v[54:55], v[54:55], v[6:7]
	v_pk_mul_f32 v[60:61], v[60:61], v[4:5]
	v_pk_mul_f32 v[58:59], v[58:59], v[2:3]
	v_mov_b32_e32 v0, v208
	v_mov_b32_e32 v1, v209
	v_mov_b32_e32 v2, v210
	v_mov_b32_e32 v3, v211
	v_mov_b32_e32 v4, v212
	v_mov_b32_e32 v5, v213
	v_mov_b32_e32 v6, v214
	v_mov_b32_e32 v7, v215
	v_mov_b32_e32 v86, v216
	v_mov_b32_e32 v87, v217
	v_mov_b32_e32 v88, v218
	v_mov_b32_e32 v89, v219
	v_mov_b32_e32 v8, v220
	v_mov_b32_e32 v9, v221
	v_mov_b32_e32 v10, v222
	v_mov_b32_e32 v11, v223
	v_pk_mul_f32 v[48:49], v[48:49], v[90:91]
	s_waitcnt vmcnt(1)
	v_mov_b32_e32 v90, v86
	v_mov_b32_e32 v91, v88
	v_mov_b32_e32 v88, v87
	v_mov_b32_e32 v86, v4
	v_mov_b32_e32 v87, v6
	v_mov_b32_e32 v6, v5
	v_mov_b32_e32 v4, v0
	v_mov_b32_e32 v5, v2
	v_mov_b32_e32 v2, v1
	v_pk_mul_f32 v[64:65], v[64:65], v[90:91]
	v_pk_mul_f32 v[62:63], v[62:63], v[88:89]
	v_pk_mul_f32 v[68:69], v[68:69], v[86:87]
	v_pk_mul_f32 v[66:67], v[66:67], v[6:7]
	v_pk_mul_f32 v[70:71], v[70:71], v[4:5]
	v_pk_mul_f32 v[72:73], v[72:73], v[2:3]
	s_waitcnt vmcnt(0)
	v_pk_mul_f32 v[74:75], v[74:75], v[8:9]
	v_pk_mul_f32 v[76:77], v[76:77], v[10:11]

; __device__ __forceinline__ void transpose_item(const float* __restrict__ W, int K, int N, bf16* __restrict__ WT, const float* __restrict__ ksc, int mode, int row_off, int item, int lane) {
;     const int nblk = N / 64, kb = item / nblk, nb = item % nblk, k0 = 64 * kb, n = 64 * nb + lane;
;     const float* src = W + (size_t)k0 * N + n;
;     float v[64];
; #pragma unroll
;     for (int i = 0; i < 64; ++i) v[i] = __builtin_nontemporal_load(src + (size_t)i * N);
; __device__ __forceinline__ void convert_layer(ArgsP a, int L, int first, int stride, int lane) {
;     ...
;         if (r < I_IN) transpose_item(a->in[3] + (size_t)L * D * INW, D, INW, WIN + (size_t)L * INW * D, a->in[2] + L * D, 1, 0, r, lane);
.LBB0_697:
	s_andn2_b64 vcc, exec, s[20:21]
	s_cbranch_vccnz .LBB0_680
	s_load_dwordx4 s[20:23], s[24:25], 0x10
	s_mul_hi_u32 s14, s1, 0xcccccccd
	s_lshr_b32 s14, s14, 5
	s_mul_i32 s15, s14, 0xa00
	s_lshl_b32 s40, s14, 6
	s_mul_i32 s14, s14, 0xa0000
	v_subrev_u32_e32 v12, s15, v82
	s_mul_hi_u32 s15, s40, 0x2800
	s_waitcnt lgkmcnt(0)
	s_add_u32 s22, s22, s14
	s_addc_u32 s23, s23, s15
	v_lshl_add_u64 v[66:67], v[12:13], 2, s[22:23]
	s_mov_b32 s14, 0x1400000
	v_add_co_u32_e32 v0, vcc, s14, v66
	s_mov_b32 s14, 0x1402000
	s_nop 0
	v_addc_co_u32_e32 v1, vcc, 0, v67, vcc
	v_add_co_u32_e32 v2, vcc, s14, v66
	s_mov_b32 s14, 0x1405000
	s_nop 0
	v_addc_co_u32_e32 v3, vcc, 0, v67, vcc
	global_load_dword v0, v[0:1], off nt
	s_cmp_eq_u64 s[20:21], 0
	global_load_dword v1, v[2:3], off offset:2048 nt
	v_add_co_u32_e32 v2, vcc, s14, v66
	s_mov_b32 s14, 0x1407000
	s_nop 0
	v_addc_co_u32_e32 v3, vcc, 0, v67, vcc
	v_add_co_u32_e32 v4, vcc, s14, v66
	s_mov_b32 s14, 0x140a000
	s_nop 0
	v_addc_co_u32_e32 v5, vcc, 0, v67, vcc
	global_load_dword v2, v[2:3], off nt
	s_nop 0
	global_load_dword v3, v[4:5], off offset:2048 nt
	v_add_co_u32_e32 v4, vcc, s14, v66
	s_mov_b32 s14, 0x140c000
	s_nop 0
	v_addc_co_u32_e32 v5, vcc, 0, v67, vcc
	v_add_co_u32_e32 v6, vcc, s14, v66
	s_mov_b32 s14, 0x140f000
	s_nop 0
	v_addc_co_u32_e32 v7, vcc, 0, v67, vcc
	global_load_dword v4, v[4:5], off nt
	s_nop 0
	global_load_dword v5, v[6:7], off offset:2048 nt
	v_add_co_u32_e32 v6, vcc, s14, v66
	s_mov_b32 s14, 0x1411000
	s_nop 0
	v_addc_co_u32_e32 v7, vcc, 0, v67, vcc
	v_add_co_u32_e32 v8, vcc, s14, v66
	s_mov_b32 s14, 0x1414000
	s_nop 0
	v_addc_co_u32_e32 v9, vcc, 0, v67, vcc
	global_load_dword v6, v[6:7], off nt
	s_nop 0
	global_load_dword v7, v[8:9], off offset:2048 nt
	v_add_co_u32_e32 v8, vcc, s14, v66
	s_mov_b32 s14, 0x1416000
	s_nop 0
	v_addc_co_u32_e32 v9, vcc, 0, v67, vcc
	v_add_co_u32_e32 v10, vcc, s14, v66
	s_mov_b32 s14, 0x1419000
	s_nop 0
	v_addc_co_u32_e32 v11, vcc, 0, v67, vcc
	global_load_dword v8, v[8:9], off nt
	s_nop 0
	global_load_dword v9, v[10:11], off offset:2048 nt
	v_add_co_u32_e32 v10, vcc, s14, v66
	s_mov_b32 s14, 0x141b000
	s_nop 0
	v_addc_co_u32_e32 v11, vcc, 0, v67, vcc
	v_add_co_u32_e32 v14, vcc, s14, v66
	s_mov_b32 s14, 0x141e000
	s_nop 0
	v_addc_co_u32_e32 v15, vcc, 0, v67, vcc
	global_load_dword v10, v[10:11], off nt
	s_nop 0
	global_load_dword v11, v[14:15], off offset:2048 nt
	v_add_co_u32_e32 v14, vcc, s14, v66
	s_mov_b32 s14, 0x1420000
	s_nop 0
	v_addc_co_u32_e32 v15, vcc, 0, v67, vcc
	v_add_co_u32_e32 v16, vcc, s14, v66
	s_mov_b32 s14, 0x1423000
	s_nop 0
	v_addc_co_u32_e32 v17, vcc, 0, v67, vcc
	global_load_dword v14, v[14:15], off nt
	s_nop 0
	global_load_dword v15, v[16:17], off offset:2048 nt
	v_add_co_u32_e32 v16, vcc, s14, v66
	s_mov_b32 s14, 0x1425000
	s_nop 0
	v_addc_co_u32_e32 v17, vcc, 0, v67, vcc
	v_add_co_u32_e32 v18, vcc, s14, v66
	s_mov_b32 s14, 0x1428000
	s_nop 0
	v_addc_co_u32_e32 v19, vcc, 0, v67, vcc
	global_load_dword v16, v[16:17], off nt
	s_nop 0
	global_load_dword v17, v[18:19], off offset:2048 nt
	v_add_co_u32_e32 v18, vcc, s14, v66
	s_mov_b32 s14, 0x142a000
	s_nop 0
	v_addc_co_u32_e32 v19, vcc, 0, v67, vcc
	v_add_co_u32_e32 v20, vcc, s14, v66
	s_mov_b32 s14, 0x142d000
	s_nop 0
	v_addc_co_u32_e32 v21, vcc, 0, v67, vcc
	global_load_dword v18, v[18:19], off nt
	s_nop 0
	global_load_dword v19, v[20:21], off offset:2048 nt
	v_add_co_u32_e32 v20, vcc, s14, v66
	s_mov_b32 s14, 0x142f000
	s_nop 0
	v_addc_co_u32_e32 v21, vcc, 0, v67, vcc
	v_add_co_u32_e32 v22, vcc, s14, v66
	s_mov_b32 s14, 0x1432000
	s_nop 0
	v_addc_co_u32_e32 v23, vcc, 0, v67, vcc
	global_load_dword v20, v[20:21], off nt
	s_nop 0
	global_load_dword v21, v[22:23], off offset:2048 nt
	v_add_co_u32_e32 v22, vcc, s14, v66
	s_mov_b32 s14, 0x1434000
	s_nop 0
	v_addc_co_u32_e32 v23, vcc, 0, v67, vcc
	v_add_co_u32_e32 v24, vcc, s14, v66
	s_mov_b32 s14, 0x1437000
	s_nop 0
	v_addc_co_u32_e32 v25, vcc, 0, v67, vcc
	global_load_dword v22, v[22:23], off nt
	s_nop 0
	global_load_dword v23, v[24:25], off offset:2048 nt
	v_add_co_u32_e32 v24, vcc, s14, v66
	s_nop 1
	v_addc_co_u32_e32 v25, vcc, 0, v67, vcc
	v_add_co_u32_e32 v26, vcc, s33, v66
	global_load_dword v24, v[24:25], off nt
	s_nop 0
	v_addc_co_u32_e32 v27, vcc, 0, v67, vcc
	global_load_dword v25, v[26:27], off offset:2048 nt
	v_add_co_u32_e32 v26, vcc, s44, v66
	s_nop 1
	v_addc_co_u32_e32 v27, vcc, 0, v67, vcc
	v_add_co_u32_e32 v28, vcc, s45, v66
	global_load_dword v26, v[26:27], off nt
	s_nop 0
	v_addc_co_u32_e32 v29, vcc, 0, v67, vcc
	global_load_dword v27, v[28:29], off offset:2048 nt
	v_add_co_u32_e32 v28, vcc, s46, v66
	s_nop 1
	v_addc_co_u32_e32 v29, vcc, 0, v67, vcc
	v_add_co_u32_e32 v30, vcc, s47, v66
	global_load_dword v28, v[28:29], off nt
	s_nop 0
	v_addc_co_u32_e32 v31, vcc, 0, v67, vcc
	global_load_dword v29, v[30:31], off offset:2048 nt
	v_add_co_u32_e32 v30, vcc, s48, v66
	s_nop 1
	v_addc_co_u32_e32 v31, vcc, 0, v67, vcc
	v_add_co_u32_e32 v32, vcc, s49, v66
	global_load_dword v30, v[30:31], off nt
	s_nop 0
	v_addc_co_u32_e32 v33, vcc, 0, v67, vcc
	global_load_dword v31, v[32:33], off offset:2048 nt
	v_add_co_u32_e32 v32, vcc, s50, v66
	s_nop 1
	v_addc_co_u32_e32 v33, vcc, 0, v67, vcc
	v_add_co_u32_e32 v34, vcc, s51, v66
	global_load_dword v32, v[32:33], off nt
	s_nop 0
	v_addc_co_u32_e32 v35, vcc, 0, v67, vcc
	global_load_dword v33, v[34:35], off offset:2048 nt
	v_add_co_u32_e32 v34, vcc, s52, v66
	s_nop 1
	v_addc_co_u32_e32 v35, vcc, 0, v67, vcc
	v_add_co_u32_e32 v36, vcc, s53, v66
	global_load_dword v34, v[34:35], off nt
	s_nop 0
	v_addc_co_u32_e32 v37, vcc, 0, v67, vcc
	global_load_dword v35, v[36:37], off offset:2048 nt
; __device__ __forceinline__ void transpose_item(const float* __restrict__ W, int K, int N, bf16* __restrict__ WT, const float* __restrict__ ksc, int mode, int row_off, int item, int lane) {
;     const int nblk = N / 64, kb = item / nblk, nb = item % nblk, k0 = 64 * kb, n = 64 * nb + lane;
;     const float* src = W + (size_t)k0 * N + n;
;     float v[64];
; #pragma unroll
;     for (int i = 0; i < 64; ++i) v[i] = __builtin_nontemporal_load(src + (size_t)i * N);
	v_add_co_u32_e32 v36, vcc, s54, v66
	s_nop 1
	v_addc_co_u32_e32 v37, vcc, 0, v67, vcc
	v_add_co_u32_e32 v38, vcc, s55, v66
	global_load_dword v36, v[36:37], off nt
	s_nop 0
	v_addc_co_u32_e32 v39, vcc, 0, v67, vcc
	global_load_dword v37, v[38:39], off offset:2048 nt
	v_add_co_u32_e32 v38, vcc, s56, v66
	s_nop 1
	v_addc_co_u32_e32 v39, vcc, 0, v67, vcc
	v_add_co_u32_e32 v40, vcc, s57, v66
	global_load_dword v38, v[38:39], off nt
	s_nop 0
	v_addc_co_u32_e32 v41, vcc, 0, v67, vcc
	global_load_dword v39, v[40:41], off offset:2048 nt
	v_add_co_u32_e32 v40, vcc, s58, v66
	s_nop 1
	v_addc_co_u32_e32 v41, vcc, 0, v67, vcc
	v_add_co_u32_e32 v42, vcc, s59, v66
	global_load_dword v40, v[40:41], off nt
	s_nop 0
	v_addc_co_u32_e32 v43, vcc, 0, v67, vcc
	global_load_dword v41, v[42:43], off offset:2048 nt
	v_add_co_u32_e32 v42, vcc, s60, v66
	s_nop 1
	v_addc_co_u32_e32 v43, vcc, 0, v67, vcc
	v_add_co_u32_e32 v44, vcc, s61, v66
	global_load_dword v42, v[42:43], off nt
	s_nop 0
	v_addc_co_u32_e32 v45, vcc, 0, v67, vcc
	global_load_dword v43, v[44:45], off offset:2048 nt
	v_add_co_u32_e32 v44, vcc, s62, v66
	s_nop 1
	v_addc_co_u32_e32 v45, vcc, 0, v67, vcc
	v_add_co_u32_e32 v46, vcc, s63, v66
	global_load_dword v44, v[44:45], off nt
	s_nop 0
	v_addc_co_u32_e32 v47, vcc, 0, v67, vcc
	global_load_dword v45, v[46:47], off offset:2048 nt
	v_add_co_u32_e32 v46, vcc, s64, v66
	s_nop 1
	v_addc_co_u32_e32 v47, vcc, 0, v67, vcc
	v_add_co_u32_e32 v48, vcc, s65, v66
	global_load_dword v46, v[46:47], off nt
	s_nop 0
	v_addc_co_u32_e32 v49, vcc, 0, v67, vcc
	global_load_dword v47, v[48:49], off offset:2048 nt
	v_add_co_u32_e32 v48, vcc, s66, v66
	s_nop 1
	v_addc_co_u32_e32 v49, vcc, 0, v67, vcc
	v_add_co_u32_e32 v50, vcc, s67, v66
	global_load_dword v48, v[48:49], off nt
	s_nop 0
	v_addc_co_u32_e32 v51, vcc, 0, v67, vcc
	global_load_dword v49, v[50:51], off offset:2048 nt
	v_add_co_u32_e32 v50, vcc, s68, v66
	s_nop 1
	v_addc_co_u32_e32 v51, vcc, 0, v67, vcc
	v_add_co_u32_e32 v52, vcc, s69, v66
	global_load_dword v50, v[50:51], off nt
	s_nop 0
	v_addc_co_u32_e32 v53, vcc, 0, v67, vcc
	global_load_dword v51, v[52:53], off offset:2048 nt
	v_add_co_u32_e32 v52, vcc, s70, v66
	s_nop 1
	v_addc_co_u32_e32 v53, vcc, 0, v67, vcc
	v_add_co_u32_e32 v54, vcc, s71, v66
	global_load_dword v52, v[52:53], off nt
	s_nop 0
	v_addc_co_u32_e32 v55, vcc, 0, v67, vcc
	global_load_dword v53, v[54:55], off offset:2048 nt
	v_add_co_u32_e32 v54, vcc, s72, v66
	s_nop 1
	v_addc_co_u32_e32 v55, vcc, 0, v67, vcc
	v_add_co_u32_e32 v56, vcc, s73, v66
	global_load_dword v54, v[54:55], off nt
	s_nop 0
	v_addc_co_u32_e32 v57, vcc, 0, v67, vcc
	global_load_dword v55, v[56:57], off offset:2048 nt
	v_add_co_u32_e32 v56, vcc, s74, v66
	s_nop 1
	v_addc_co_u32_e32 v57, vcc, 0, v67, vcc
	v_add_co_u32_e32 v58, vcc, s75, v66
	global_load_dword v56, v[56:57], off nt
	s_nop 0
	v_addc_co_u32_e32 v59, vcc, 0, v67, vcc
	global_load_dword v57, v[58:59], off offset:2048 nt
	v_add_co_u32_e32 v58, vcc, s76, v66
	s_nop 1
	v_addc_co_u32_e32 v59, vcc, 0, v67, vcc
	v_add_co_u32_e32 v60, vcc, s77, v66
	global_load_dword v58, v[58:59], off nt
	s_nop 0
	v_addc_co_u32_e32 v61, vcc, 0, v67, vcc
	global_load_dword v59, v[60:61], off offset:2048 nt
	v_add_co_u32_e32 v60, vcc, s78, v66
	s_nop 1
	v_addc_co_u32_e32 v61, vcc, 0, v67, vcc
	v_add_co_u32_e32 v62, vcc, s79, v66
	global_load_dword v60, v[60:61], off nt
	s_nop 0
	v_addc_co_u32_e32 v63, vcc, 0, v67, vcc
	global_load_dword v61, v[62:63], off offset:2048 nt
	v_add_co_u32_e32 v62, vcc, s80, v66
	s_nop 1
	v_addc_co_u32_e32 v63, vcc, 0, v67, vcc
	v_add_co_u32_e32 v64, vcc, s81, v66
	global_load_dword v62, v[62:63], off nt
	s_nop 0
	v_addc_co_u32_e32 v65, vcc, 0, v67, vcc
	global_load_dword v63, v[64:65], off offset:2048 nt
	v_add_co_u32_e32 v64, vcc, s82, v66
	s_nop 1
	v_addc_co_u32_e32 v65, vcc, 0, v67, vcc
	v_add_co_u32_e32 v66, vcc, s83, v66
	global_load_dword v64, v[64:65], off nt
	s_nop 0
	v_addc_co_u32_e32 v67, vcc, 0, v67, vcc
	global_load_dword v65, v[66:67], off offset:2048 nt
	s_cbranch_scc1 .LBB0_679
; __device__ __forceinline__ void transpose_item(const float* __restrict__ W, int K, int N, bf16* __restrict__ WT, const float* __restrict__ ksc, int mode, int row_off, int item, int lane) {
;     ...
;     if (ksc) {
; #pragma unroll
;         for (int i = 0; i < 64; ++i) v[i] *= ksc[k0 + i];
;     }
	s_lshl_b64 s[22:23], s[40:41], 2
	s_add_u32 s22, s20, s22
	s_addc_u32 s23, s21, s23
	s_add_u32 s20, s22, 0x2000
	s_addc_u32 s21, s23, 0
	global_load_dwordx4 v[66:69], v13, s[20:21] offset:48
	global_load_dwordx4 v[70:73], v13, s[20:21] offset:32
	global_load_dwordx4 v[74:77], v13, s[20:21] offset:16
	global_load_dwordx4 v[86:89], v83, s[22:23]
	global_load_dwordx4 v[152:155], v13, s[20:21] offset:112
	global_load_dwordx4 v[156:159], v13, s[20:21] offset:96
	global_load_dwordx4 v[160:163], v13, s[20:21] offset:80
	global_load_dwordx4 v[164:167], v13, s[20:21] offset:64
	global_load_dwordx4 v[168:171], v13, s[20:21] offset:176
	global_load_dwordx4 v[188:191], v13, s[20:21] offset:160
	global_load_dwordx4 v[192:195], v13, s[20:21] offset:144
	global_load_dwordx4 v[204:207], v13, s[20:21] offset:128
	global_load_dwordx4 v[208:211], v13, s[20:21] offset:240
	global_load_dwordx4 v[212:215], v13, s[20:21] offset:224
	global_load_dwordx4 v[216:219], v13, s[20:21] offset:208
	global_load_dwordx4 v[220:223], v13, s[20:21] offset:192
	s_waitcnt vmcnt(0)
	v_pk_mul_f32 v[14:15], v[14:15], v[66:67]
	s_waitcnt vmcnt(2)
	v_pk_mul_f32 v[8:9], v[8:9], v[70:71]
	s_waitcnt vmcnt(1)
	v_pk_mul_f32 v[4:5], v[4:5], v[74:75]
	s_waitcnt vmcnt(0)
	v_pk_mul_f32 v[0:1], v[0:1], v[86:87]
	v_pk_mul_f32 v[2:3], v[2:3], v[88:89]
	v_pk_mul_f32 v[6:7], v[6:7], v[76:77]
	v_pk_mul_f32 v[10:11], v[10:11], v[72:73]
	v_pk_mul_f32 v[16:17], v[16:17], v[68:69]
	v_mov_b32_e32 v66, v152
	v_mov_b32_e32 v67, v153
	v_mov_b32_e32 v68, v154
	v_mov_b32_e32 v69, v155
	v_mov_b32_e32 v70, v156
	v_mov_b32_e32 v71, v157
	v_mov_b32_e32 v72, v158
	v_mov_b32_e32 v73, v159
	v_mov_b32_e32 v74, v160
	v_mov_b32_e32 v75, v161
	v_mov_b32_e32 v76, v162
	v_mov_b32_e32 v77, v163
	v_mov_b32_e32 v86, v164
	v_mov_b32_e32 v87, v165
	v_mov_b32_e32 v88, v166
	v_mov_b32_e32 v89, v167
	s_waitcnt vmcnt(3)
	v_pk_mul_f32 v[30:31], v[30:31], v[66:67]
	s_waitcnt vmcnt(2)
	v_pk_mul_f32 v[26:27], v[26:27], v[70:71]
	s_waitcnt vmcnt(1)
	v_pk_mul_f32 v[22:23], v[22:23], v[74:75]
	s_waitcnt vmcnt(0)
	v_pk_mul_f32 v[18:19], v[18:19], v[86:87]
	v_pk_mul_f32 v[20:21], v[20:21], v[88:89]
	v_pk_mul_f32 v[24:25], v[24:25], v[76:77]
	v_pk_mul_f32 v[28:29], v[28:29], v[72:73]
	v_pk_mul_f32 v[32:33], v[32:33], v[68:69]
	v_mov_b32_e32 v66, v168
	v_mov_b32_e32 v67, v169
	v_mov_b32_e32 v68, v170
	v_mov_b32_e32 v69, v171
	v_mov_b32_e32 v70, v188
	v_mov_b32_e32 v71, v189
	v_mov_b32_e32 v72, v190
	v_mov_b32_e32 v73, v191
	v_mov_b32_e32 v74, v192
	v_mov_b32_e32 v75, v193
	v_mov_b32_e32 v76, v194
	v_mov_b32_e32 v77, v195
	v_mov_b32_e32 v86, v204
	v_mov_b32_e32 v87, v205
	v_mov_b32_e32 v88, v206
	v_mov_b32_e32 v89, v207
	s_waitcnt vmcnt(3)
	v_pk_mul_f32 v[46:47], v[46:47], v[66:67]
	s_waitcnt vmcnt(2)
	v_pk_mul_f32 v[42:43], v[42:43], v[70:71]
	s_waitcnt vmcnt(1)
	v_pk_mul_f32 v[38:39], v[38:39], v[74:75]
	s_waitcnt vmcnt(0)
	v_pk_mul_f32 v[34:35], v[34:35], v[86:87]
	v_pk_mul_f32 v[36:37], v[36:37], v[88:89]
	v_pk_mul_f32 v[40:41], v[40:41], v[76:77]
	v_pk_mul_f32 v[44:45], v[44:45], v[72:73]
	v_pk_mul_f32 v[48:49], v[48:49], v[68:69]
	v_mov_b32_e32 v66, v208
	v_mov_b32_e32 v67, v209
	v_mov_b32_e32 v68, v210
	v_mov_b32_e32 v69, v211
	v_mov_b32_e32 v70, v212
	v_mov_b32_e32 v71, v213
	v_mov_b32_e32 v72, v214
	v_mov_b32_e32 v73, v215
	v_mov_b32_e32 v74, v216
	v_mov_b32_e32 v75, v217
	v_mov_b32_e32 v76, v218
	v_mov_b32_e32 v77, v219
	v_mov_b32_e32 v86, v220
	v_mov_b32_e32 v87, v221
	v_mov_b32_e32 v88, v222
	v_mov_b32_e32 v89, v223
	s_waitcnt vmcnt(3)
	v_pk_mul_f32 v[62:63], v[62:63], v[66:67]
	s_waitcnt vmcnt(2)
	v_pk_mul_f32 v[58:59], v[58:59], v[70:71]
	s_waitcnt vmcnt(1)
	v_pk_mul_f32 v[54:55], v[54:55], v[74:75]
	s_waitcnt vmcnt(0)
	v_pk_mul_f32 v[50:51], v[50:51], v[86:87]
	v_pk_mul_f32 v[52:53], v[52:53], v[88:89]
	v_pk_mul_f32 v[56:57], v[56:57], v[76:77]
	v_pk_mul_f32 v[60:61], v[60:61], v[72:73]
	v_pk_mul_f32 v[64:65], v[64:65], v[68:69]
	s_branch .LBB0_679

; __device__ __forceinline__ void transpose_item(const float* __restrict__ W, int K, int N, bf16* __restrict__ WT, const float* __restrict__ ksc, int mode, int row_off, int item, int lane) {
;     const int nblk = N / 64, kb = item / nblk, nb = item % nblk, k0 = 64 * kb, n = 64 * nb + lane;
;     const float* src = W + (size_t)k0 * N + n;
;     float v[64];
; #pragma unroll
;     for (int i = 0; i < 64; ++i) v[i] = __builtin_nontemporal_load(src + (size_t)i * N);
; __device__ __forceinline__ void convert_layer(ArgsP a, int L, int first, int stride, int lane) {
;     ...
;         else if (r < I_IN + I_OUT + I_GU) transpose_item(a->in[18] + (size_t)L * D * GU, D, GU, WGU + (size_t)L * GU * D, a->in[17] + L * D, 2, 0, r - I_IN - I_OUT, lane);
.Lcx3_685:
	s_andn2_b64 vcc, exec, s[20:21]
	s_cbranch_vccnz .Lcx3_693
	s_add_i32 s14, s1, 0xfc80
	s_and_b32 s15, s14, 0xffff
	s_mul_i32 s15, s15, 0xba2f
	s_load_dwordx4 s[20:23], s[24:25], 0x88
	s_lshr_b32 s40, s15, 16
	s_lshr_b32 s15, s15, 22
	s_mulk_i32 s15, 0x58
	s_sub_i32 s14, s14, s15
	s_and_b32 s85, s14, 0xffff
	s_and_b32 s40, s40, 0xffc0
	s_lshl_b32 s84, s85, 6
	s_mul_i32 s14, s40, 0x5800
	v_or_b32_e32 v78, s84, v80
	s_waitcnt lgkmcnt(0)
	s_add_u32 s22, s22, s14
	s_addc_u32 s23, s23, 0
	v_lshlrev_b32_e32 v12, 2, v78
	v_lshl_add_u64 v[0:1], s[22:23], 0, v[12:13]
	s_mov_b32 s14, 0x2c00000
	v_add_co_u32_e32 v2, vcc, s14, v0
	s_mov_b32 s14, 0x2c05000
	s_nop 0
	v_addc_co_u32_e32 v3, vcc, 0, v1, vcc
	global_load_dword v16, v[2:3], off nt
	v_add_co_u32_e32 v2, vcc, s14, v0
	s_mov_b32 s14, 0x2c0b000
	s_nop 0
	v_addc_co_u32_e32 v3, vcc, 0, v1, vcc
	global_load_dword v14, v[2:3], off offset:2048 nt
	v_add_co_u32_e32 v2, vcc, s14, v0
	s_mov_b32 s14, 0x2c10000
	s_nop 0
	v_addc_co_u32_e32 v3, vcc, 0, v1, vcc
	global_load_dword v17, v[2:3], off nt
	v_add_co_u32_e32 v2, vcc, s14, v0
	s_mov_b32 s14, 0x2c16000
	s_nop 0
	v_addc_co_u32_e32 v3, vcc, 0, v1, vcc
	global_load_dword v15, v[2:3], off offset:2048 nt
	v_add_co_u32_e32 v2, vcc, s14, v0
	s_mov_b32 s14, 0x2c1b000
	s_nop 0
	v_addc_co_u32_e32 v3, vcc, 0, v1, vcc
	global_load_dword v20, v[2:3], off nt
	v_add_co_u32_e32 v2, vcc, s14, v0
	s_mov_b32 s14, 0x2c21000
	s_nop 0
	v_addc_co_u32_e32 v3, vcc, 0, v1, vcc
	global_load_dword v18, v[2:3], off offset:2048 nt
	v_add_co_u32_e32 v2, vcc, s14, v0
	s_mov_b32 s14, 0x2c26000
	s_nop 0
	v_addc_co_u32_e32 v3, vcc, 0, v1, vcc
	global_load_dword v21, v[2:3], off nt
	v_add_co_u32_e32 v2, vcc, s14, v0
	s_mov_b32 s14, 0x2c2c000
	s_nop 0
	v_addc_co_u32_e32 v3, vcc, 0, v1, vcc
	global_load_dword v19, v[2:3], off offset:2048 nt
	v_add_co_u32_e32 v2, vcc, s14, v0
	s_mov_b32 s14, 0x2c31000
	s_nop 0
	v_addc_co_u32_e32 v3, vcc, 0, v1, vcc
	global_load_dword v24, v[2:3], off nt
	v_add_co_u32_e32 v2, vcc, s14, v0
	s_mov_b32 s14, 0x2c37000
	s_nop 0
	v_addc_co_u32_e32 v3, vcc, 0, v1, vcc
	global_load_dword v22, v[2:3], off offset:2048 nt
	v_add_co_u32_e32 v2, vcc, s14, v0
	s_mov_b32 s14, 0x2c3c000
	s_nop 0
	v_addc_co_u32_e32 v3, vcc, 0, v1, vcc
	global_load_dword v25, v[2:3], off nt
	v_add_co_u32_e32 v2, vcc, s14, v0
	s_mov_b32 s14, 0x2c42000
	s_nop 0
	v_addc_co_u32_e32 v3, vcc, 0, v1, vcc
	global_load_dword v23, v[2:3], off offset:2048 nt
	v_add_co_u32_e32 v2, vcc, s14, v0
	s_mov_b32 s14, 0x2c47000
	s_nop 0
	v_addc_co_u32_e32 v3, vcc, 0, v1, vcc
	global_load_dword v28, v[2:3], off nt
	v_add_co_u32_e32 v2, vcc, s14, v0
	s_mov_b32 s14, 0x2c4d000
	s_nop 0
	v_addc_co_u32_e32 v3, vcc, 0, v1, vcc
	global_load_dword v26, v[2:3], off offset:2048 nt
	v_add_co_u32_e32 v2, vcc, s14, v0
	s_mov_b32 s14, 0x2c52000
	s_nop 0
	v_addc_co_u32_e32 v3, vcc, 0, v1, vcc
	global_load_dword v29, v[2:3], off nt
	v_add_co_u32_e32 v2, vcc, s14, v0
	s_mov_b32 s14, 0x2c58000
	s_nop 0
	v_addc_co_u32_e32 v3, vcc, 0, v1, vcc
	global_load_dword v27, v[2:3], off offset:2048 nt
	v_add_co_u32_e32 v2, vcc, s14, v0
	s_mov_b32 s14, 0x2c5d000
	s_nop 0
	v_addc_co_u32_e32 v3, vcc, 0, v1, vcc
	global_load_dword v32, v[2:3], off nt
	v_add_co_u32_e32 v2, vcc, s14, v0
	s_mov_b32 s14, 0x2c63000
	s_nop 0
	v_addc_co_u32_e32 v3, vcc, 0, v1, vcc
	global_load_dword v30, v[2:3], off offset:2048 nt
	v_add_co_u32_e32 v2, vcc, s14, v0
	s_mov_b32 s14, 0x2c68000
	s_nop 0
	v_addc_co_u32_e32 v3, vcc, 0, v1, vcc
	global_load_dword v33, v[2:3], off nt
	v_add_co_u32_e32 v2, vcc, s14, v0
	s_mov_b32 s14, 0x2c6e000
	s_nop 0
	v_addc_co_u32_e32 v3, vcc, 0, v1, vcc
	global_load_dword v31, v[2:3], off offset:2048 nt
	v_add_co_u32_e32 v2, vcc, s14, v0
	s_mov_b32 s14, 0x2c73000
	s_nop 0
	v_addc_co_u32_e32 v3, vcc, 0, v1, vcc
	global_load_dword v36, v[2:3], off nt
	v_add_co_u32_e32 v2, vcc, s14, v0
	s_mov_b32 s14, 0x2c79000
	s_nop 0
	v_addc_co_u32_e32 v3, vcc, 0, v1, vcc
	global_load_dword v34, v[2:3], off offset:2048 nt
	v_add_co_u32_e32 v2, vcc, s14, v0
	s_mov_b32 s14, 0x2c7e000
	s_nop 0
	v_addc_co_u32_e32 v3, vcc, 0, v1, vcc
	global_load_dword v37, v[2:3], off nt
	v_add_co_u32_e32 v2, vcc, s14, v0
	s_mov_b32 s14, 0x2c84000
	s_nop 0
	v_addc_co_u32_e32 v3, vcc, 0, v1, vcc
	global_load_dword v35, v[2:3], off offset:2048 nt
	v_add_co_u32_e32 v2, vcc, s14, v0
	s_mov_b32 s14, 0x2c89000
	s_nop 0
	v_addc_co_u32_e32 v3, vcc, 0, v1, vcc
	global_load_dword v40, v[2:3], off nt
	v_add_co_u32_e32 v2, vcc, s14, v0
	s_mov_b32 s14, 0x2c8f000
	s_nop 0
	v_addc_co_u32_e32 v3, vcc, 0, v1, vcc
	global_load_dword v38, v[2:3], off offset:2048 nt
	v_add_co_u32_e32 v2, vcc, s14, v0
	s_mov_b32 s14, 0x2c94000
	s_nop 0
	v_addc_co_u32_e32 v3, vcc, 0, v1, vcc
	global_load_dword v41, v[2:3], off nt
	v_add_co_u32_e32 v2, vcc, s14, v0
	s_mov_b32 s14, 0x2c9a000
	s_nop 0
	v_addc_co_u32_e32 v3, vcc, 0, v1, vcc
	global_load_dword v39, v[2:3], off offset:2048 nt
	v_add_co_u32_e32 v2, vcc, s14, v0
	s_mov_b32 s14, 0x2c9f000
	s_nop 0
	v_addc_co_u32_e32 v3, vcc, 0, v1, vcc
	global_load_dword v44, v[2:3], off nt
	v_add_co_u32_e32 v2, vcc, s14, v0
	s_mov_b32 s14, 0x2ca5000
	s_nop 0
	v_addc_co_u32_e32 v3, vcc, 0, v1, vcc
	global_load_dword v42, v[2:3], off offset:2048 nt
	v_add_co_u32_e32 v2, vcc, s14, v0
	s_mov_b32 s14, 0x2caa000
	s_nop 0
	v_addc_co_u32_e32 v3, vcc, 0, v1, vcc
	global_load_dword v45, v[2:3], off nt
	v_add_co_u32_e32 v2, vcc, s14, v0
	s_mov_b32 s14, 0x2cb0000
	s_nop 0
	v_addc_co_u32_e32 v3, vcc, 0, v1, vcc
	global_load_dword v43, v[2:3], off offset:2048 nt
	v_add_co_u32_e32 v2, vcc, s14, v0
	s_mov_b32 s14, 0x2cb5000
	s_nop 0
	v_addc_co_u32_e32 v3, vcc, 0, v1, vcc
; __device__ __forceinline__ void transpose_item(const float* __restrict__ W, int K, int N, bf16* __restrict__ WT, const float* __restrict__ ksc, int mode, int row_off, int item, int lane) {
;     ...
;     for (int i = 0; i < 64; ++i) v[i] = __builtin_nontemporal_load(src + (size_t)i * N);
	global_load_dword v48, v[2:3], off nt
	v_add_co_u32_e32 v2, vcc, s14, v0
	s_mov_b32 s14, 0x2cbb000
	s_nop 0
	v_addc_co_u32_e32 v3, vcc, 0, v1, vcc
	global_load_dword v46, v[2:3], off offset:2048 nt
	v_add_co_u32_e32 v2, vcc, s14, v0
	s_mov_b32 s14, 0x2cc0000
	s_nop 0
	v_addc_co_u32_e32 v3, vcc, 0, v1, vcc
	global_load_dword v49, v[2:3], off nt
	v_add_co_u32_e32 v2, vcc, s14, v0
	s_mov_b32 s14, 0x2cc6000
	s_nop 0
	v_addc_co_u32_e32 v3, vcc, 0, v1, vcc
	global_load_dword v47, v[2:3], off offset:2048 nt
	v_add_co_u32_e32 v2, vcc, s14, v0
	s_mov_b32 s14, 0x2ccb000
	s_nop 0
	v_addc_co_u32_e32 v3, vcc, 0, v1, vcc
	global_load_dword v52, v[2:3], off nt
	v_add_co_u32_e32 v2, vcc, s14, v0
	s_mov_b32 s14, 0x2cd1000
	s_nop 0
	v_addc_co_u32_e32 v3, vcc, 0, v1, vcc
	global_load_dword v50, v[2:3], off offset:2048 nt
	v_add_co_u32_e32 v2, vcc, s14, v0
	s_mov_b32 s14, 0x2cd6000
	s_nop 0
	v_addc_co_u32_e32 v3, vcc, 0, v1, vcc
	global_load_dword v53, v[2:3], off nt
	v_add_co_u32_e32 v2, vcc, s14, v0
	s_mov_b32 s14, 0x2cdc000
	s_nop 0
	v_addc_co_u32_e32 v3, vcc, 0, v1, vcc
	global_load_dword v51, v[2:3], off offset:2048 nt
	v_add_co_u32_e32 v2, vcc, s14, v0
	s_mov_b32 s14, 0x2ce1000
	s_nop 0
	v_addc_co_u32_e32 v3, vcc, 0, v1, vcc
	global_load_dword v56, v[2:3], off nt
	v_add_co_u32_e32 v2, vcc, s14, v0
	s_mov_b32 s14, 0x2ce7000
	s_nop 0
	v_addc_co_u32_e32 v3, vcc, 0, v1, vcc
	global_load_dword v54, v[2:3], off offset:2048 nt
	v_add_co_u32_e32 v2, vcc, s14, v0
	s_mov_b32 s14, 0x2cec000
	s_nop 0
	v_addc_co_u32_e32 v3, vcc, 0, v1, vcc
	global_load_dword v57, v[2:3], off nt
	v_add_co_u32_e32 v2, vcc, s14, v0
	s_mov_b32 s14, 0x2cf2000
	s_nop 0
	v_addc_co_u32_e32 v3, vcc, 0, v1, vcc
	global_load_dword v55, v[2:3], off offset:2048 nt
	v_add_co_u32_e32 v2, vcc, s14, v0
	s_mov_b32 s14, 0x2cf7000
	s_nop 0
	v_addc_co_u32_e32 v3, vcc, 0, v1, vcc
	global_load_dword v60, v[2:3], off nt
	v_add_co_u32_e32 v2, vcc, s14, v0
	s_mov_b32 s14, 0x2cfd000
	s_nop 0
	v_addc_co_u32_e32 v3, vcc, 0, v1, vcc
	global_load_dword v58, v[2:3], off offset:2048 nt
	v_add_co_u32_e32 v2, vcc, s14, v0
	s_mov_b32 s14, 0x2d02000
	s_nop 0
	v_addc_co_u32_e32 v3, vcc, 0, v1, vcc
	global_load_dword v61, v[2:3], off nt
	v_add_co_u32_e32 v2, vcc, s14, v0
	s_mov_b32 s14, 0x2d08000
	s_nop 0
	v_addc_co_u32_e32 v3, vcc, 0, v1, vcc
	global_load_dword v59, v[2:3], off offset:2048 nt
	v_add_co_u32_e32 v2, vcc, s14, v0
	s_mov_b32 s14, 0x2d0d000
	s_nop 0
	v_addc_co_u32_e32 v3, vcc, 0, v1, vcc
	global_load_dword v64, v[2:3], off nt
	v_add_co_u32_e32 v2, vcc, s14, v0
	s_mov_b32 s14, 0x2d13000
	s_nop 0
	v_addc_co_u32_e32 v3, vcc, 0, v1, vcc
	global_load_dword v62, v[2:3], off offset:2048 nt
	v_add_co_u32_e32 v2, vcc, s14, v0
	s_mov_b32 s14, 0x2d18000
	s_nop 0
	v_addc_co_u32_e32 v3, vcc, 0, v1, vcc
	global_load_dword v65, v[2:3], off nt
	v_add_co_u32_e32 v2, vcc, s14, v0
	s_mov_b32 s14, 0x2d1e000
	s_nop 0
	v_addc_co_u32_e32 v3, vcc, 0, v1, vcc
	global_load_dword v63, v[2:3], off offset:2048 nt
	v_add_co_u32_e32 v2, vcc, s14, v0
	s_mov_b32 s14, 0x2d23000
	s_nop 0
	v_addc_co_u32_e32 v3, vcc, 0, v1, vcc
	global_load_dword v68, v[2:3], off nt
	v_add_co_u32_e32 v2, vcc, s14, v0
	s_mov_b32 s14, 0x2d29000
	s_nop 0
	v_addc_co_u32_e32 v3, vcc, 0, v1, vcc
	global_load_dword v66, v[2:3], off offset:2048 nt
	v_add_co_u32_e32 v2, vcc, s14, v0
	s_mov_b32 s14, 0x2d2e000
	s_nop 0
	v_addc_co_u32_e32 v3, vcc, 0, v1, vcc
	global_load_dword v69, v[2:3], off nt
	v_add_co_u32_e32 v2, vcc, s14, v0
	s_mov_b32 s14, 0x2d34000
	s_nop 0
	v_addc_co_u32_e32 v3, vcc, 0, v1, vcc
	global_load_dword v67, v[2:3], off offset:2048 nt
	v_add_co_u32_e32 v2, vcc, s14, v0
	s_mov_b32 s14, 0x2d39000
	s_nop 0
	v_addc_co_u32_e32 v3, vcc, 0, v1, vcc
	global_load_dword v70, v[2:3], off nt
	v_add_co_u32_e32 v2, vcc, s14, v0
	s_mov_b32 s14, 0x2d3f000
	s_nop 0
	v_addc_co_u32_e32 v3, vcc, 0, v1, vcc
	global_load_dword v72, v[2:3], off offset:2048 nt
	v_add_co_u32_e32 v2, vcc, s14, v0
	s_mov_b32 s14, 0x2d44000
	s_nop 0
	v_addc_co_u32_e32 v3, vcc, 0, v1, vcc
	global_load_dword v71, v[2:3], off nt
	v_add_co_u32_e32 v2, vcc, s14, v0
	s_mov_b32 s14, 0x2d4a000
	s_nop 0
	v_addc_co_u32_e32 v3, vcc, 0, v1, vcc
	global_load_dword v73, v[2:3], off offset:2048 nt
	v_add_co_u32_e32 v2, vcc, s14, v0
	s_mov_b32 s14, 0x2d4f000
	s_nop 0
	v_addc_co_u32_e32 v3, vcc, 0, v1, vcc
	global_load_dword v74, v[2:3], off nt
	v_add_co_u32_e32 v2, vcc, s14, v0
	s_mov_b32 s14, 0x2d55000
	s_nop 0
	v_addc_co_u32_e32 v3, vcc, 0, v1, vcc
	global_load_dword v75, v[2:3], off offset:2048 nt
	v_add_co_u32_e32 v2, vcc, s14, v0
	s_mov_b32 s14, 0x2d5a000
	s_nop 0
	v_addc_co_u32_e32 v3, vcc, 0, v1, vcc
	v_add_co_u32_e32 v0, vcc, s14, v0
	global_load_dword v76, v[2:3], off nt
	s_nop 0
	v_addc_co_u32_e32 v1, vcc, 0, v1, vcc
	global_load_dword v77, v[0:1], off offset:2048 nt
	s_cmp_eq_u64 s[20:21], 0
	s_cbranch_scc1 .Lcx3_688
; __device__ __forceinline__ void transpose_item(const float* __restrict__ W, int K, int N, bf16* __restrict__ WT, const float* __restrict__ ksc, int mode, int row_off, int item, int lane) {
;     ...
;     if (ksc) {
; #pragma unroll
;         for (int i = 0; i < 64; ++i) v[i] *= ksc[k0 + i];
;     }
	s_lshl_b32 s14, s40, 2
	s_add_u32 s22, s20, s14
	s_addc_u32 s23, s21, 0
	s_add_u32 s20, s22, 0x2000
	s_addc_u32 s21, s23, 0
	global_load_dwordx4 v[0:3], v13, s[20:21] offset:48
	global_load_dwordx4 v[4:7], v13, s[20:21] offset:32
	global_load_dwordx4 v[8:11], v13, s[20:21] offset:16
	global_load_dwordx4 v[86:89], v83, s[22:23]
	global_load_dwordx4 v[180:183], v13, s[20:21] offset:112
	global_load_dwordx4 v[184:187], v13, s[20:21] offset:96
	global_load_dwordx4 v[188:191], v13, s[20:21] offset:80
	global_load_dwordx4 v[192:195], v13, s[20:21] offset:64
	global_load_dwordx4 v[196:199], v13, s[20:21] offset:176
	global_load_dwordx4 v[204:207], v13, s[20:21] offset:160
	global_load_dwordx4 v[208:211], v13, s[20:21] offset:144
	global_load_dwordx4 v[212:215], v13, s[20:21] offset:128
	global_load_dwordx4 v[216:219], v13, s[20:21] offset:224
	global_load_dwordx4 v[220:223], v13, s[20:21] offset:208
	global_load_dwordx4 v[224:227], v13, s[20:21] offset:192
	global_load_dwordx4 v[228:231], v13, s[20:21] offset:240
	s_waitcnt vmcnt(0)
	v_mov_b32_e32 v90, v86
	v_mov_b32_e32 v91, v88
	v_mov_b32_e32 v88, v87
	v_mov_b32_e32 v86, v8
	v_mov_b32_e32 v87, v10
	v_mov_b32_e32 v10, v9
	v_mov_b32_e32 v8, v4
	v_mov_b32_e32 v9, v6
	v_mov_b32_e32 v6, v5
	v_mov_b32_e32 v4, v0
	v_mov_b32_e32 v5, v2
	v_mov_b32_e32 v2, v1
	v_pk_mul_f32 v[14:15], v[14:15], v[88:89]
	v_pk_mul_f32 v[20:21], v[20:21], v[86:87]
	v_pk_mul_f32 v[18:19], v[18:19], v[10:11]
	v_pk_mul_f32 v[24:25], v[24:25], v[8:9]
	v_pk_mul_f32 v[22:23], v[22:23], v[6:7]
	v_pk_mul_f32 v[28:29], v[28:29], v[4:5]
	v_pk_mul_f32 v[26:27], v[26:27], v[2:3]
	v_mov_b32_e32 v0, v180
	v_mov_b32_e32 v1, v181
	v_mov_b32_e32 v2, v182
	v_mov_b32_e32 v3, v183
	v_mov_b32_e32 v4, v184
	v_mov_b32_e32 v5, v185
	v_mov_b32_e32 v6, v186
	v_mov_b32_e32 v7, v187
	v_mov_b32_e32 v8, v188
	v_mov_b32_e32 v9, v189
	v_mov_b32_e32 v10, v190
	v_mov_b32_e32 v11, v191
	v_mov_b32_e32 v86, v192
	v_mov_b32_e32 v87, v193
	v_mov_b32_e32 v88, v194
	v_mov_b32_e32 v89, v195
	v_pk_mul_f32 v[16:17], v[16:17], v[90:91]
	s_waitcnt vmcnt(0)
	v_mov_b32_e32 v90, v86
	v_mov_b32_e32 v91, v88
	v_mov_b32_e32 v88, v87
	v_mov_b32_e32 v86, v8
	v_mov_b32_e32 v87, v10
	v_mov_b32_e32 v10, v9
	v_mov_b32_e32 v8, v4
	v_mov_b32_e32 v9, v6
	v_mov_b32_e32 v6, v5
	v_mov_b32_e32 v4, v0
	v_mov_b32_e32 v5, v2
	v_mov_b32_e32 v2, v1
	v_pk_mul_f32 v[30:31], v[30:31], v[88:89]
	v_pk_mul_f32 v[36:37], v[36:37], v[86:87]
	v_pk_mul_f32 v[34:35], v[34:35], v[10:11]
	v_pk_mul_f32 v[40:41], v[40:41], v[8:9]
	v_pk_mul_f32 v[38:39], v[38:39], v[6:7]
	v_pk_mul_f32 v[44:45], v[44:45], v[4:5]
	v_pk_mul_f32 v[42:43], v[42:43], v[2:3]
	v_mov_b32_e32 v0, v196
	v_mov_b32_e32 v1, v197
	v_mov_b32_e32 v2, v198
	v_mov_b32_e32 v3, v199
	v_mov_b32_e32 v4, v204
	v_mov_b32_e32 v5, v205
	v_mov_b32_e32 v6, v206
	v_mov_b32_e32 v7, v207
	v_mov_b32_e32 v8, v208
	v_mov_b32_e32 v9, v209
	v_mov_b32_e32 v10, v210
	v_mov_b32_e32 v11, v211
	v_mov_b32_e32 v86, v212
	v_mov_b32_e32 v87, v213
	v_mov_b32_e32 v88, v214
	v_mov_b32_e32 v89, v215
	v_pk_mul_f32 v[32:33], v[32:33], v[90:91]
	s_waitcnt vmcnt(0)
	v_mov_b32_e32 v90, v86
	v_mov_b32_e32 v91, v88
	v_mov_b32_e32 v88, v87
	v_mov_b32_e32 v86, v8
	v_mov_b32_e32 v87, v10
	v_mov_b32_e32 v10, v9
	v_mov_b32_e32 v8, v4
	v_mov_b32_e32 v9, v6
	v_mov_b32_e32 v6, v5
	v_mov_b32_e32 v4, v0
	v_mov_b32_e32 v5, v2
	v_mov_b32_e32 v2, v1
	v_pk_mul_f32 v[46:47], v[46:47], v[88:89]
	v_pk_mul_f32 v[52:53], v[52:53], v[86:87]
	v_pk_mul_f32 v[50:51], v[50:51], v[10:11]
	v_pk_mul_f32 v[56:57], v[56:57], v[8:9]
	v_pk_mul_f32 v[54:55], v[54:55], v[6:7]
	v_pk_mul_f32 v[60:61], v[60:61], v[4:5]
	v_pk_mul_f32 v[58:59], v[58:59], v[2:3]
	v_mov_b32_e32 v0, v216
	v_mov_b32_e32 v1, v217
	v_mov_b32_e32 v2, v218
	v_mov_b32_e32 v3, v219
	v_mov_b32_e32 v4, v220
	v_mov_b32_e32 v5, v221
	v_mov_b32_e32 v6, v222
	v_mov_b32_e32 v7, v223
	v_mov_b32_e32 v86, v224
	v_mov_b32_e32 v87, v225
	v_mov_b32_e32 v88, v226
	v_mov_b32_e32 v89, v227
	v_mov_b32_e32 v8, v228
	v_mov_b32_e32 v9, v229
	v_mov_b32_e32 v10, v230
	v_mov_b32_e32 v11, v231
	v_pk_mul_f32 v[48:49], v[48:49], v[90:91]
	s_waitcnt vmcnt(1)
	v_mov_b32_e32 v90, v86
	v_mov_b32_e32 v91, v88
	v_mov_b32_e32 v88, v87
	v_mov_b32_e32 v86, v4
	v_mov_b32_e32 v87, v6
	v_mov_b32_e32 v6, v5
	v_mov_b32_e32 v4, v0
	v_mov_b32_e32 v5, v2
	v_mov_b32_e32 v2, v1
	v_pk_mul_f32 v[64:65], v[64:65], v[90:91]
	v_pk_mul_f32 v[62:63], v[62:63], v[88:89]
	v_pk_mul_f32 v[68:69], v[68:69], v[86:87]
	v_pk_mul_f32 v[66:67], v[66:67], v[6:7]
	v_pk_mul_f32 v[70:71], v[70:71], v[4:5]
	v_pk_mul_f32 v[72:73], v[72:73], v[2:3]
	s_waitcnt vmcnt(0)
	v_pk_mul_f32 v[74:75], v[74:75], v[8:9]
	v_pk_mul_f32 v[76:77], v[76:77], v[10:11]

; __device__ __forceinline__ void transpose_item(const float* __restrict__ W, int K, int N, bf16* __restrict__ WT, const float* __restrict__ ksc, int mode, int row_off, int item, int lane) {
;     const int nblk = N / 64, kb = item / nblk, nb = item % nblk, k0 = 64 * kb, n = 64 * nb + lane;
;     const float* src = W + (size_t)k0 * N + n;
;     float v[64];
; #pragma unroll
;     for (int i = 0; i < 64; ++i) v[i] = __builtin_nontemporal_load(src + (size_t)i * N);
; __device__ __forceinline__ void convert_layer(ArgsP a, int L, int first, int stride, int lane) {
;     ...
;         if (r < I_IN) transpose_item(a->in[3] + (size_t)L * D * INW, D, INW, WIN + (size_t)L * INW * D, a->in[2] + L * D, 1, 0, r, lane);
.Lcx3_697:
	s_andn2_b64 vcc, exec, s[20:21]
	s_cbranch_vccnz .Lcx3_680
	s_load_dwordx4 s[20:23], s[24:25], 0x10
	s_mul_hi_u32 s14, s1, 0xcccccccd
	s_lshr_b32 s14, s14, 5
	s_mul_i32 s15, s14, 0xa00
	s_lshl_b32 s40, s14, 6
	s_mul_i32 s14, s14, 0xa0000
	v_subrev_u32_e32 v12, s15, v82
	s_mul_hi_u32 s15, s40, 0x2800
	s_waitcnt lgkmcnt(0)
	s_add_u32 s22, s22, s14
	s_addc_u32 s23, s23, s15
	v_lshl_add_u64 v[66:67], v[12:13], 2, s[22:23]
	s_mov_b32 s14, 0x1400000
	v_add_co_u32_e32 v0, vcc, s14, v66
	s_mov_b32 s14, 0x1402000
	s_nop 0
	v_addc_co_u32_e32 v1, vcc, 0, v67, vcc
	v_add_co_u32_e32 v2, vcc, s14, v66
	s_mov_b32 s14, 0x1405000
	s_nop 0
	v_addc_co_u32_e32 v3, vcc, 0, v67, vcc
	global_load_dword v0, v[0:1], off nt
	s_cmp_eq_u64 s[20:21], 0
	global_load_dword v1, v[2:3], off offset:2048 nt
	v_add_co_u32_e32 v2, vcc, s14, v66
	s_mov_b32 s14, 0x1407000
	s_nop 0
	v_addc_co_u32_e32 v3, vcc, 0, v67, vcc
	v_add_co_u32_e32 v4, vcc, s14, v66
	s_mov_b32 s14, 0x140a000
	s_nop 0
	v_addc_co_u32_e32 v5, vcc, 0, v67, vcc
	global_load_dword v2, v[2:3], off nt
	s_nop 0
	global_load_dword v3, v[4:5], off offset:2048 nt
	v_add_co_u32_e32 v4, vcc, s14, v66
	s_mov_b32 s14, 0x140c000
	s_nop 0
	v_addc_co_u32_e32 v5, vcc, 0, v67, vcc
	v_add_co_u32_e32 v6, vcc, s14, v66
	s_mov_b32 s14, 0x140f000
	s_nop 0
	v_addc_co_u32_e32 v7, vcc, 0, v67, vcc
	global_load_dword v4, v[4:5], off nt
	s_nop 0
	global_load_dword v5, v[6:7], off offset:2048 nt
	v_add_co_u32_e32 v6, vcc, s14, v66
	s_mov_b32 s14, 0x1411000
	s_nop 0
	v_addc_co_u32_e32 v7, vcc, 0, v67, vcc
	v_add_co_u32_e32 v8, vcc, s14, v66
	s_mov_b32 s14, 0x1414000
	s_nop 0
	v_addc_co_u32_e32 v9, vcc, 0, v67, vcc
	global_load_dword v6, v[6:7], off nt
	s_nop 0
	global_load_dword v7, v[8:9], off offset:2048 nt
	v_add_co_u32_e32 v8, vcc, s14, v66
	s_mov_b32 s14, 0x1416000
	s_nop 0
	v_addc_co_u32_e32 v9, vcc, 0, v67, vcc
	v_add_co_u32_e32 v10, vcc, s14, v66
	s_mov_b32 s14, 0x1419000
	s_nop 0
	v_addc_co_u32_e32 v11, vcc, 0, v67, vcc
	global_load_dword v8, v[8:9], off nt
	s_nop 0
	global_load_dword v9, v[10:11], off offset:2048 nt
	v_add_co_u32_e32 v10, vcc, s14, v66
	s_mov_b32 s14, 0x141b000
	s_nop 0
	v_addc_co_u32_e32 v11, vcc, 0, v67, vcc
	v_add_co_u32_e32 v14, vcc, s14, v66
	s_mov_b32 s14, 0x141e000
	s_nop 0
	v_addc_co_u32_e32 v15, vcc, 0, v67, vcc
	global_load_dword v10, v[10:11], off nt
	s_nop 0
	global_load_dword v11, v[14:15], off offset:2048 nt
	v_add_co_u32_e32 v14, vcc, s14, v66
	s_mov_b32 s14, 0x1420000
	s_nop 0
	v_addc_co_u32_e32 v15, vcc, 0, v67, vcc
	v_add_co_u32_e32 v16, vcc, s14, v66
	s_mov_b32 s14, 0x1423000
	s_nop 0
	v_addc_co_u32_e32 v17, vcc, 0, v67, vcc
	global_load_dword v14, v[14:15], off nt
	s_nop 0
	global_load_dword v15, v[16:17], off offset:2048 nt
	v_add_co_u32_e32 v16, vcc, s14, v66
	s_mov_b32 s14, 0x1425000
	s_nop 0
	v_addc_co_u32_e32 v17, vcc, 0, v67, vcc
	v_add_co_u32_e32 v18, vcc, s14, v66
	s_mov_b32 s14, 0x1428000
	s_nop 0
	v_addc_co_u32_e32 v19, vcc, 0, v67, vcc
	global_load_dword v16, v[16:17], off nt
	s_nop 0
	global_load_dword v17, v[18:19], off offset:2048 nt
	v_add_co_u32_e32 v18, vcc, s14, v66
	s_mov_b32 s14, 0x142a000
	s_nop 0
	v_addc_co_u32_e32 v19, vcc, 0, v67, vcc
	v_add_co_u32_e32 v20, vcc, s14, v66
	s_mov_b32 s14, 0x142d000
	s_nop 0
	v_addc_co_u32_e32 v21, vcc, 0, v67, vcc
	global_load_dword v18, v[18:19], off nt
	s_nop 0
	global_load_dword v19, v[20:21], off offset:2048 nt
	v_add_co_u32_e32 v20, vcc, s14, v66
	s_mov_b32 s14, 0x142f000
	s_nop 0
	v_addc_co_u32_e32 v21, vcc, 0, v67, vcc
	v_add_co_u32_e32 v22, vcc, s14, v66
	s_mov_b32 s14, 0x1432000
	s_nop 0
	v_addc_co_u32_e32 v23, vcc, 0, v67, vcc
	global_load_dword v20, v[20:21], off nt
	s_nop 0
	global_load_dword v21, v[22:23], off offset:2048 nt
	v_add_co_u32_e32 v22, vcc, s14, v66
	s_mov_b32 s14, 0x1434000
	s_nop 0
	v_addc_co_u32_e32 v23, vcc, 0, v67, vcc
	v_add_co_u32_e32 v24, vcc, s14, v66
	s_mov_b32 s14, 0x1437000
	s_nop 0
	v_addc_co_u32_e32 v25, vcc, 0, v67, vcc
	global_load_dword v22, v[22:23], off nt
	s_nop 0
	global_load_dword v23, v[24:25], off offset:2048 nt
	v_add_co_u32_e32 v24, vcc, s14, v66
	s_nop 1
	v_addc_co_u32_e32 v25, vcc, 0, v67, vcc
	v_add_co_u32_e32 v26, vcc, s33, v66
	global_load_dword v24, v[24:25], off nt
	s_nop 0
	v_addc_co_u32_e32 v27, vcc, 0, v67, vcc
	global_load_dword v25, v[26:27], off offset:2048 nt
	v_add_co_u32_e32 v26, vcc, s44, v66
	s_nop 1
	v_addc_co_u32_e32 v27, vcc, 0, v67, vcc
	v_add_co_u32_e32 v28, vcc, s45, v66
	global_load_dword v26, v[26:27], off nt
	s_nop 0
	v_addc_co_u32_e32 v29, vcc, 0, v67, vcc
	global_load_dword v27, v[28:29], off offset:2048 nt
	v_add_co_u32_e32 v28, vcc, s46, v66
	s_nop 1
	v_addc_co_u32_e32 v29, vcc, 0, v67, vcc
	v_add_co_u32_e32 v30, vcc, s47, v66
	global_load_dword v28, v[28:29], off nt
	s_nop 0
	v_addc_co_u32_e32 v31, vcc, 0, v67, vcc
	global_load_dword v29, v[30:31], off offset:2048 nt
	v_add_co_u32_e32 v30, vcc, s48, v66
	s_nop 1
	v_addc_co_u32_e32 v31, vcc, 0, v67, vcc
	v_add_co_u32_e32 v32, vcc, s49, v66
	global_load_dword v30, v[30:31], off nt
	s_nop 0
	v_addc_co_u32_e32 v33, vcc, 0, v67, vcc
	global_load_dword v31, v[32:33], off offset:2048 nt
	v_add_co_u32_e32 v32, vcc, s50, v66
	s_nop 1
	v_addc_co_u32_e32 v33, vcc, 0, v67, vcc
	v_add_co_u32_e32 v34, vcc, s51, v66
	global_load_dword v32, v[32:33], off nt
	s_nop 0
	v_addc_co_u32_e32 v35, vcc, 0, v67, vcc
	global_load_dword v33, v[34:35], off offset:2048 nt
	v_add_co_u32_e32 v34, vcc, s52, v66
	s_nop 1
	v_addc_co_u32_e32 v35, vcc, 0, v67, vcc
	v_add_co_u32_e32 v36, vcc, s53, v66
	global_load_dword v34, v[34:35], off nt
	s_nop 0
	v_addc_co_u32_e32 v37, vcc, 0, v67, vcc
	global_load_dword v35, v[36:37], off offset:2048 nt
; __device__ __forceinline__ void transpose_item(const float* __restrict__ W, int K, int N, bf16* __restrict__ WT, const float* __restrict__ ksc, int mode, int row_off, int item, int lane) {
;     ...
;     for (int i = 0; i < 64; ++i) v[i] = __builtin_nontemporal_load(src + (size_t)i * N);
	v_add_co_u32_e32 v36, vcc, s54, v66
	s_nop 1
	v_addc_co_u32_e32 v37, vcc, 0, v67, vcc
	v_add_co_u32_e32 v38, vcc, s55, v66
	global_load_dword v36, v[36:37], off nt
	s_nop 0
	v_addc_co_u32_e32 v39, vcc, 0, v67, vcc
	global_load_dword v37, v[38:39], off offset:2048 nt
	v_add_co_u32_e32 v38, vcc, s56, v66
	s_nop 1
	v_addc_co_u32_e32 v39, vcc, 0, v67, vcc
	v_add_co_u32_e32 v40, vcc, s57, v66
	global_load_dword v38, v[38:39], off nt
	s_nop 0
	v_addc_co_u32_e32 v41, vcc, 0, v67, vcc
	global_load_dword v39, v[40:41], off offset:2048 nt
	v_add_co_u32_e32 v40, vcc, s58, v66
	s_nop 1
	v_addc_co_u32_e32 v41, vcc, 0, v67, vcc
	v_add_co_u32_e32 v42, vcc, s59, v66
	global_load_dword v40, v[40:41], off nt
	s_nop 0
	v_addc_co_u32_e32 v43, vcc, 0, v67, vcc
	global_load_dword v41, v[42:43], off offset:2048 nt
	v_add_co_u32_e32 v42, vcc, s60, v66
	s_nop 1
	v_addc_co_u32_e32 v43, vcc, 0, v67, vcc
	v_add_co_u32_e32 v44, vcc, s61, v66
	global_load_dword v42, v[42:43], off nt
	s_nop 0
	v_addc_co_u32_e32 v45, vcc, 0, v67, vcc
	global_load_dword v43, v[44:45], off offset:2048 nt
	v_add_co_u32_e32 v44, vcc, s62, v66
	s_nop 1
	v_addc_co_u32_e32 v45, vcc, 0, v67, vcc
	v_add_co_u32_e32 v46, vcc, s63, v66
	global_load_dword v44, v[44:45], off nt
	s_nop 0
	v_addc_co_u32_e32 v47, vcc, 0, v67, vcc
	global_load_dword v45, v[46:47], off offset:2048 nt
	v_add_co_u32_e32 v46, vcc, s64, v66
	s_nop 1
	v_addc_co_u32_e32 v47, vcc, 0, v67, vcc
	v_add_co_u32_e32 v48, vcc, s65, v66
	global_load_dword v46, v[46:47], off nt
	s_nop 0
	v_addc_co_u32_e32 v49, vcc, 0, v67, vcc
	global_load_dword v47, v[48:49], off offset:2048 nt
	v_add_co_u32_e32 v48, vcc, s66, v66
	s_nop 1
	v_addc_co_u32_e32 v49, vcc, 0, v67, vcc
	v_add_co_u32_e32 v50, vcc, s67, v66
	global_load_dword v48, v[48:49], off nt
	s_nop 0
	v_addc_co_u32_e32 v51, vcc, 0, v67, vcc
	global_load_dword v49, v[50:51], off offset:2048 nt
	v_add_co_u32_e32 v50, vcc, s68, v66
	s_nop 1
	v_addc_co_u32_e32 v51, vcc, 0, v67, vcc
	v_add_co_u32_e32 v52, vcc, s69, v66
	global_load_dword v50, v[50:51], off nt
	s_nop 0
	v_addc_co_u32_e32 v53, vcc, 0, v67, vcc
	global_load_dword v51, v[52:53], off offset:2048 nt
	v_add_co_u32_e32 v52, vcc, s70, v66
	s_nop 1
	v_addc_co_u32_e32 v53, vcc, 0, v67, vcc
	v_add_co_u32_e32 v54, vcc, s71, v66
	global_load_dword v52, v[52:53], off nt
	s_nop 0
	v_addc_co_u32_e32 v55, vcc, 0, v67, vcc
	global_load_dword v53, v[54:55], off offset:2048 nt
	v_add_co_u32_e32 v54, vcc, s72, v66
	s_nop 1
	v_addc_co_u32_e32 v55, vcc, 0, v67, vcc
	v_add_co_u32_e32 v56, vcc, s73, v66
	global_load_dword v54, v[54:55], off nt
	s_nop 0
	v_addc_co_u32_e32 v57, vcc, 0, v67, vcc
	global_load_dword v55, v[56:57], off offset:2048 nt
	v_add_co_u32_e32 v56, vcc, s74, v66
	s_nop 1
	v_addc_co_u32_e32 v57, vcc, 0, v67, vcc
	v_add_co_u32_e32 v58, vcc, s75, v66
	global_load_dword v56, v[56:57], off nt
	s_nop 0
	v_addc_co_u32_e32 v59, vcc, 0, v67, vcc
	global_load_dword v57, v[58:59], off offset:2048 nt
	v_add_co_u32_e32 v58, vcc, s76, v66
	s_nop 1
	v_addc_co_u32_e32 v59, vcc, 0, v67, vcc
	v_add_co_u32_e32 v60, vcc, s77, v66
	global_load_dword v58, v[58:59], off nt
	s_nop 0
	v_addc_co_u32_e32 v61, vcc, 0, v67, vcc
	global_load_dword v59, v[60:61], off offset:2048 nt
	v_add_co_u32_e32 v60, vcc, s78, v66
	s_nop 1
	v_addc_co_u32_e32 v61, vcc, 0, v67, vcc
	v_add_co_u32_e32 v62, vcc, s79, v66
	global_load_dword v60, v[60:61], off nt
	s_nop 0
	v_addc_co_u32_e32 v63, vcc, 0, v67, vcc
	global_load_dword v61, v[62:63], off offset:2048 nt
	v_add_co_u32_e32 v62, vcc, s80, v66
	s_nop 1
	v_addc_co_u32_e32 v63, vcc, 0, v67, vcc
	v_add_co_u32_e32 v64, vcc, s81, v66
	global_load_dword v62, v[62:63], off nt
	s_nop 0
	v_addc_co_u32_e32 v65, vcc, 0, v67, vcc
	global_load_dword v63, v[64:65], off offset:2048 nt
	v_add_co_u32_e32 v64, vcc, s82, v66
	s_nop 1
	v_addc_co_u32_e32 v65, vcc, 0, v67, vcc
	v_add_co_u32_e32 v66, vcc, s83, v66
	global_load_dword v64, v[64:65], off nt
	s_nop 0
	v_addc_co_u32_e32 v67, vcc, 0, v67, vcc
	global_load_dword v65, v[66:67], off offset:2048 nt
	s_cbranch_scc1 .Lcx3_679
; __device__ __forceinline__ void transpose_item(const float* __restrict__ W, int K, int N, bf16* __restrict__ WT, const float* __restrict__ ksc, int mode, int row_off, int item, int lane) {
;     ...
;     if (ksc) {
; #pragma unroll
;         for (int i = 0; i < 64; ++i) v[i] *= ksc[k0 + i];
;     }
	s_lshl_b64 s[22:23], s[40:41], 2
	s_add_u32 s22, s20, s22
	s_addc_u32 s23, s21, s23
	s_add_u32 s20, s22, 0x2000
	s_addc_u32 s21, s23, 0
	global_load_dwordx4 v[66:69], v13, s[20:21] offset:48
	global_load_dwordx4 v[70:73], v13, s[20:21] offset:32
	global_load_dwordx4 v[74:77], v13, s[20:21] offset:16
	global_load_dwordx4 v[86:89], v83, s[22:23]
	global_load_dwordx4 v[180:183], v13, s[20:21] offset:112
	global_load_dwordx4 v[184:187], v13, s[20:21] offset:96
	global_load_dwordx4 v[188:191], v13, s[20:21] offset:80
	global_load_dwordx4 v[192:195], v13, s[20:21] offset:64
	global_load_dwordx4 v[196:199], v13, s[20:21] offset:176
	global_load_dwordx4 v[204:207], v13, s[20:21] offset:160
	global_load_dwordx4 v[208:211], v13, s[20:21] offset:144
	global_load_dwordx4 v[212:215], v13, s[20:21] offset:128
	global_load_dwordx4 v[216:219], v13, s[20:21] offset:240
	global_load_dwordx4 v[220:223], v13, s[20:21] offset:224
	global_load_dwordx4 v[224:227], v13, s[20:21] offset:208
	global_load_dwordx4 v[228:231], v13, s[20:21] offset:192
	s_waitcnt vmcnt(0)
	v_pk_mul_f32 v[14:15], v[14:15], v[66:67]
	s_waitcnt vmcnt(2)
	v_pk_mul_f32 v[8:9], v[8:9], v[70:71]
	s_waitcnt vmcnt(1)
	v_pk_mul_f32 v[4:5], v[4:5], v[74:75]
	s_waitcnt vmcnt(0)
	v_pk_mul_f32 v[0:1], v[0:1], v[86:87]
	v_pk_mul_f32 v[2:3], v[2:3], v[88:89]
	v_pk_mul_f32 v[6:7], v[6:7], v[76:77]
	v_pk_mul_f32 v[10:11], v[10:11], v[72:73]
	v_pk_mul_f32 v[16:17], v[16:17], v[68:69]
	v_mov_b32_e32 v66, v180
	v_mov_b32_e32 v67, v181
	v_mov_b32_e32 v68, v182
	v_mov_b32_e32 v69, v183
	v_mov_b32_e32 v70, v184
	v_mov_b32_e32 v71, v185
	v_mov_b32_e32 v72, v186
	v_mov_b32_e32 v73, v187
	v_mov_b32_e32 v74, v188
	v_mov_b32_e32 v75, v189
	v_mov_b32_e32 v76, v190
	v_mov_b32_e32 v77, v191
	v_mov_b32_e32 v86, v192
	v_mov_b32_e32 v87, v193
	v_mov_b32_e32 v88, v194
	v_mov_b32_e32 v89, v195
	s_waitcnt vmcnt(3)
	v_pk_mul_f32 v[30:31], v[30:31], v[66:67]
	s_waitcnt vmcnt(2)
	v_pk_mul_f32 v[26:27], v[26:27], v[70:71]
	s_waitcnt vmcnt(1)
	v_pk_mul_f32 v[22:23], v[22:23], v[74:75]
	s_waitcnt vmcnt(0)
	v_pk_mul_f32 v[18:19], v[18:19], v[86:87]
	v_pk_mul_f32 v[20:21], v[20:21], v[88:89]
	v_pk_mul_f32 v[24:25], v[24:25], v[76:77]
	v_pk_mul_f32 v[28:29], v[28:29], v[72:73]
	v_pk_mul_f32 v[32:33], v[32:33], v[68:69]
	v_mov_b32_e32 v66, v196
	v_mov_b32_e32 v67, v197
	v_mov_b32_e32 v68, v198
	v_mov_b32_e32 v69, v199
	v_mov_b32_e32 v70, v204
	v_mov_b32_e32 v71, v205
	v_mov_b32_e32 v72, v206
	v_mov_b32_e32 v73, v207
	v_mov_b32_e32 v74, v208
	v_mov_b32_e32 v75, v209
	v_mov_b32_e32 v76, v210
	v_mov_b32_e32 v77, v211
	v_mov_b32_e32 v86, v212
	v_mov_b32_e32 v87, v213
	v_mov_b32_e32 v88, v214
	v_mov_b32_e32 v89, v215
	s_waitcnt vmcnt(3)
	v_pk_mul_f32 v[46:47], v[46:47], v[66:67]
	s_waitcnt vmcnt(2)
	v_pk_mul_f32 v[42:43], v[42:43], v[70:71]
	s_waitcnt vmcnt(1)
	v_pk_mul_f32 v[38:39], v[38:39], v[74:75]
	s_waitcnt vmcnt(0)
	v_pk_mul_f32 v[34:35], v[34:35], v[86:87]
	v_pk_mul_f32 v[36:37], v[36:37], v[88:89]
	v_pk_mul_f32 v[40:41], v[40:41], v[76:77]
	v_pk_mul_f32 v[44:45], v[44:45], v[72:73]
	v_pk_mul_f32 v[48:49], v[48:49], v[68:69]
	v_mov_b32_e32 v66, v216
	v_mov_b32_e32 v67, v217
	v_mov_b32_e32 v68, v218
	v_mov_b32_e32 v69, v219
	v_mov_b32_e32 v70, v220
	v_mov_b32_e32 v71, v221
	v_mov_b32_e32 v72, v222
	v_mov_b32_e32 v73, v223
	v_mov_b32_e32 v74, v224
	v_mov_b32_e32 v75, v225
	v_mov_b32_e32 v76, v226
	v_mov_b32_e32 v77, v227
	v_mov_b32_e32 v86, v228
	v_mov_b32_e32 v87, v229
	v_mov_b32_e32 v88, v230
	v_mov_b32_e32 v89, v231
	s_waitcnt vmcnt(3)
	v_pk_mul_f32 v[62:63], v[62:63], v[66:67]
	s_waitcnt vmcnt(2)
	v_pk_mul_f32 v[58:59], v[58:59], v[70:71]
	s_waitcnt vmcnt(1)
	v_pk_mul_f32 v[54:55], v[54:55], v[74:75]
	s_waitcnt vmcnt(0)
	v_pk_mul_f32 v[50:51], v[50:51], v[86:87]
	v_pk_mul_f32 v[52:53], v[52:53], v[88:89]
	v_pk_mul_f32 v[56:57], v[56:57], v[76:77]
	v_pk_mul_f32 v[60:61], v[60:61], v[72:73]
	v_pk_mul_f32 v[64:65], v[64:65], v[68:69]
	s_branch .Lcx3_679

; __device__ __forceinline__ void transpose_item(const float* __restrict__ W, int K, int N, bf16* __restrict__ WT, const float* __restrict__ ksc, int mode, int row_off, int item, int lane) {
;     const int nblk = N / 64, kb = item / nblk, nb = item % nblk, k0 = 64 * kb, n = 64 * nb + lane;
;     const float* src = W + (size_t)k0 * N + n;
;     float v[64];
; #pragma unroll
;     for (int i = 0; i < 64; ++i) v[i] = __builtin_nontemporal_load(src + (size_t)i * N);
; __device__ __forceinline__ void convert_layer(ArgsP a, int L, int first, int stride, int lane) {
;     ...
;         else if (r < I_IN + I_OUT + I_GU) transpose_item(a->in[18] + (size_t)L * D * GU, D, GU, WGU + (size_t)L * GU * D, a->in[17] + L * D, 2, 0, r - I_IN - I_OUT, lane);
.Lcx4_685:
	s_andn2_b64 vcc, exec, s[20:21]
	s_cbranch_vccnz .Lcx4_693
	s_add_i32 s14, s1, 0xfc80
	s_and_b32 s15, s14, 0xffff
	s_mul_i32 s15, s15, 0xba2f
	s_load_dwordx4 s[20:23], s[24:25], 0x88
	s_lshr_b32 s40, s15, 16
	s_lshr_b32 s15, s15, 22
	s_mulk_i32 s15, 0x58
	s_sub_i32 s14, s14, s15
	s_and_b32 s85, s14, 0xffff
	s_and_b32 s40, s40, 0xffc0
	s_lshl_b32 s84, s85, 6
	s_mul_i32 s14, s40, 0x5800
	v_or_b32_e32 v78, s84, v80
	s_waitcnt lgkmcnt(0)
	s_add_u32 s22, s22, s14
	s_addc_u32 s23, s23, 0
	v_lshlrev_b32_e32 v12, 2, v78
	v_lshl_add_u64 v[0:1], s[22:23], 0, v[12:13]
	s_mov_b32 s14, 0x2c00000
	v_add_co_u32_e32 v2, vcc, s14, v0
	s_mov_b32 s14, 0x2c05000
	s_nop 0
	v_addc_co_u32_e32 v3, vcc, 0, v1, vcc
	global_load_dword v16, v[2:3], off nt
	v_add_co_u32_e32 v2, vcc, s14, v0
	s_mov_b32 s14, 0x2c0b000
	s_nop 0
	v_addc_co_u32_e32 v3, vcc, 0, v1, vcc
	global_load_dword v14, v[2:3], off offset:2048 nt
	v_add_co_u32_e32 v2, vcc, s14, v0
	s_mov_b32 s14, 0x2c10000
	s_nop 0
	v_addc_co_u32_e32 v3, vcc, 0, v1, vcc
	global_load_dword v17, v[2:3], off nt
	v_add_co_u32_e32 v2, vcc, s14, v0
	s_mov_b32 s14, 0x2c16000
	s_nop 0
	v_addc_co_u32_e32 v3, vcc, 0, v1, vcc
	global_load_dword v15, v[2:3], off offset:2048 nt
	v_add_co_u32_e32 v2, vcc, s14, v0
	s_mov_b32 s14, 0x2c1b000
	s_nop 0
	v_addc_co_u32_e32 v3, vcc, 0, v1, vcc
	global_load_dword v20, v[2:3], off nt
	v_add_co_u32_e32 v2, vcc, s14, v0
	s_mov_b32 s14, 0x2c21000
	s_nop 0
	v_addc_co_u32_e32 v3, vcc, 0, v1, vcc
	global_load_dword v18, v[2:3], off offset:2048 nt
	v_add_co_u32_e32 v2, vcc, s14, v0
	s_mov_b32 s14, 0x2c26000
	s_nop 0
	v_addc_co_u32_e32 v3, vcc, 0, v1, vcc
	global_load_dword v21, v[2:3], off nt
	v_add_co_u32_e32 v2, vcc, s14, v0
	s_mov_b32 s14, 0x2c2c000
	s_nop 0
	v_addc_co_u32_e32 v3, vcc, 0, v1, vcc
	global_load_dword v19, v[2:3], off offset:2048 nt
	v_add_co_u32_e32 v2, vcc, s14, v0
	s_mov_b32 s14, 0x2c31000
	s_nop 0
	v_addc_co_u32_e32 v3, vcc, 0, v1, vcc
	global_load_dword v24, v[2:3], off nt
	v_add_co_u32_e32 v2, vcc, s14, v0
	s_mov_b32 s14, 0x2c37000
	s_nop 0
	v_addc_co_u32_e32 v3, vcc, 0, v1, vcc
	global_load_dword v22, v[2:3], off offset:2048 nt
	v_add_co_u32_e32 v2, vcc, s14, v0
	s_mov_b32 s14, 0x2c3c000
	s_nop 0
	v_addc_co_u32_e32 v3, vcc, 0, v1, vcc
	global_load_dword v25, v[2:3], off nt
	v_add_co_u32_e32 v2, vcc, s14, v0
	s_mov_b32 s14, 0x2c42000
	s_nop 0
	v_addc_co_u32_e32 v3, vcc, 0, v1, vcc
	global_load_dword v23, v[2:3], off offset:2048 nt
	v_add_co_u32_e32 v2, vcc, s14, v0
	s_mov_b32 s14, 0x2c47000
	s_nop 0
	v_addc_co_u32_e32 v3, vcc, 0, v1, vcc
	global_load_dword v28, v[2:3], off nt
	v_add_co_u32_e32 v2, vcc, s14, v0
	s_mov_b32 s14, 0x2c4d000
	s_nop 0
	v_addc_co_u32_e32 v3, vcc, 0, v1, vcc
	global_load_dword v26, v[2:3], off offset:2048 nt
	v_add_co_u32_e32 v2, vcc, s14, v0
	s_mov_b32 s14, 0x2c52000
	s_nop 0
	v_addc_co_u32_e32 v3, vcc, 0, v1, vcc
	global_load_dword v29, v[2:3], off nt
	v_add_co_u32_e32 v2, vcc, s14, v0
	s_mov_b32 s14, 0x2c58000
	s_nop 0
	v_addc_co_u32_e32 v3, vcc, 0, v1, vcc
	global_load_dword v27, v[2:3], off offset:2048 nt
	v_add_co_u32_e32 v2, vcc, s14, v0
	s_mov_b32 s14, 0x2c5d000
	s_nop 0
	v_addc_co_u32_e32 v3, vcc, 0, v1, vcc
	global_load_dword v32, v[2:3], off nt
	v_add_co_u32_e32 v2, vcc, s14, v0
	s_mov_b32 s14, 0x2c63000
	s_nop 0
	v_addc_co_u32_e32 v3, vcc, 0, v1, vcc
	global_load_dword v30, v[2:3], off offset:2048 nt
	v_add_co_u32_e32 v2, vcc, s14, v0
	s_mov_b32 s14, 0x2c68000
	s_nop 0
	v_addc_co_u32_e32 v3, vcc, 0, v1, vcc
	global_load_dword v33, v[2:3], off nt
	v_add_co_u32_e32 v2, vcc, s14, v0
	s_mov_b32 s14, 0x2c6e000
	s_nop 0
	v_addc_co_u32_e32 v3, vcc, 0, v1, vcc
	global_load_dword v31, v[2:3], off offset:2048 nt
	v_add_co_u32_e32 v2, vcc, s14, v0
	s_mov_b32 s14, 0x2c73000
	s_nop 0
	v_addc_co_u32_e32 v3, vcc, 0, v1, vcc
	global_load_dword v36, v[2:3], off nt
	v_add_co_u32_e32 v2, vcc, s14, v0
	s_mov_b32 s14, 0x2c79000
	s_nop 0
	v_addc_co_u32_e32 v3, vcc, 0, v1, vcc
	global_load_dword v34, v[2:3], off offset:2048 nt
	v_add_co_u32_e32 v2, vcc, s14, v0
	s_mov_b32 s14, 0x2c7e000
	s_nop 0
	v_addc_co_u32_e32 v3, vcc, 0, v1, vcc
	global_load_dword v37, v[2:3], off nt
	v_add_co_u32_e32 v2, vcc, s14, v0
	s_mov_b32 s14, 0x2c84000
	s_nop 0
	v_addc_co_u32_e32 v3, vcc, 0, v1, vcc
	global_load_dword v35, v[2:3], off offset:2048 nt
	v_add_co_u32_e32 v2, vcc, s14, v0
	s_mov_b32 s14, 0x2c89000
	s_nop 0
	v_addc_co_u32_e32 v3, vcc, 0, v1, vcc
	global_load_dword v40, v[2:3], off nt
	v_add_co_u32_e32 v2, vcc, s14, v0
	s_mov_b32 s14, 0x2c8f000
	s_nop 0
	v_addc_co_u32_e32 v3, vcc, 0, v1, vcc
	global_load_dword v38, v[2:3], off offset:2048 nt
	v_add_co_u32_e32 v2, vcc, s14, v0
	s_mov_b32 s14, 0x2c94000
	s_nop 0
	v_addc_co_u32_e32 v3, vcc, 0, v1, vcc
	global_load_dword v41, v[2:3], off nt
	v_add_co_u32_e32 v2, vcc, s14, v0
	s_mov_b32 s14, 0x2c9a000
	s_nop 0
	v_addc_co_u32_e32 v3, vcc, 0, v1, vcc
	global_load_dword v39, v[2:3], off offset:2048 nt
	v_add_co_u32_e32 v2, vcc, s14, v0
	s_mov_b32 s14, 0x2c9f000
	s_nop 0
	v_addc_co_u32_e32 v3, vcc, 0, v1, vcc
	global_load_dword v44, v[2:3], off nt
	v_add_co_u32_e32 v2, vcc, s14, v0
	s_mov_b32 s14, 0x2ca5000
	s_nop 0
	v_addc_co_u32_e32 v3, vcc, 0, v1, vcc
	global_load_dword v42, v[2:3], off offset:2048 nt
	v_add_co_u32_e32 v2, vcc, s14, v0
	s_mov_b32 s14, 0x2caa000
	s_nop 0
	v_addc_co_u32_e32 v3, vcc, 0, v1, vcc
	global_load_dword v45, v[2:3], off nt
	v_add_co_u32_e32 v2, vcc, s14, v0
	s_mov_b32 s14, 0x2cb0000
	s_nop 0
	v_addc_co_u32_e32 v3, vcc, 0, v1, vcc
	global_load_dword v43, v[2:3], off offset:2048 nt
	v_add_co_u32_e32 v2, vcc, s14, v0
	s_mov_b32 s14, 0x2cb5000
	s_nop 0
	v_addc_co_u32_e32 v3, vcc, 0, v1, vcc
; __device__ __forceinline__ void transpose_item(const float* __restrict__ W, int K, int N, bf16* __restrict__ WT, const float* __restrict__ ksc, int mode, int row_off, int item, int lane) {
;     ...
;     for (int i = 0; i < 64; ++i) v[i] = __builtin_nontemporal_load(src + (size_t)i * N);
	global_load_dword v48, v[2:3], off nt
	v_add_co_u32_e32 v2, vcc, s14, v0
	s_mov_b32 s14, 0x2cbb000
	s_nop 0
	v_addc_co_u32_e32 v3, vcc, 0, v1, vcc
	global_load_dword v46, v[2:3], off offset:2048 nt
	v_add_co_u32_e32 v2, vcc, s14, v0
	s_mov_b32 s14, 0x2cc0000
	s_nop 0
	v_addc_co_u32_e32 v3, vcc, 0, v1, vcc
	global_load_dword v49, v[2:3], off nt
	v_add_co_u32_e32 v2, vcc, s14, v0
	s_mov_b32 s14, 0x2cc6000
	s_nop 0
	v_addc_co_u32_e32 v3, vcc, 0, v1, vcc
	global_load_dword v47, v[2:3], off offset:2048 nt
	v_add_co_u32_e32 v2, vcc, s14, v0
	s_mov_b32 s14, 0x2ccb000
	s_nop 0
	v_addc_co_u32_e32 v3, vcc, 0, v1, vcc
	global_load_dword v52, v[2:3], off nt
	v_add_co_u32_e32 v2, vcc, s14, v0
	s_mov_b32 s14, 0x2cd1000
	s_nop 0
	v_addc_co_u32_e32 v3, vcc, 0, v1, vcc
	global_load_dword v50, v[2:3], off offset:2048 nt
	v_add_co_u32_e32 v2, vcc, s14, v0
	s_mov_b32 s14, 0x2cd6000
	s_nop 0
	v_addc_co_u32_e32 v3, vcc, 0, v1, vcc
	global_load_dword v53, v[2:3], off nt
	v_add_co_u32_e32 v2, vcc, s14, v0
	s_mov_b32 s14, 0x2cdc000
	s_nop 0
	v_addc_co_u32_e32 v3, vcc, 0, v1, vcc
	global_load_dword v51, v[2:3], off offset:2048 nt
	v_add_co_u32_e32 v2, vcc, s14, v0
	s_mov_b32 s14, 0x2ce1000
	s_nop 0
	v_addc_co_u32_e32 v3, vcc, 0, v1, vcc
	global_load_dword v56, v[2:3], off nt
	v_add_co_u32_e32 v2, vcc, s14, v0
	s_mov_b32 s14, 0x2ce7000
	s_nop 0
	v_addc_co_u32_e32 v3, vcc, 0, v1, vcc
	global_load_dword v54, v[2:3], off offset:2048 nt
	v_add_co_u32_e32 v2, vcc, s14, v0
	s_mov_b32 s14, 0x2cec000
	s_nop 0
	v_addc_co_u32_e32 v3, vcc, 0, v1, vcc
	global_load_dword v57, v[2:3], off nt
	v_add_co_u32_e32 v2, vcc, s14, v0
	s_mov_b32 s14, 0x2cf2000
	s_nop 0
	v_addc_co_u32_e32 v3, vcc, 0, v1, vcc
	global_load_dword v55, v[2:3], off offset:2048 nt
	v_add_co_u32_e32 v2, vcc, s14, v0
	s_mov_b32 s14, 0x2cf7000
	s_nop 0
	v_addc_co_u32_e32 v3, vcc, 0, v1, vcc
	global_load_dword v60, v[2:3], off nt
	v_add_co_u32_e32 v2, vcc, s14, v0
	s_mov_b32 s14, 0x2cfd000
	s_nop 0
	v_addc_co_u32_e32 v3, vcc, 0, v1, vcc
	global_load_dword v58, v[2:3], off offset:2048 nt
	v_add_co_u32_e32 v2, vcc, s14, v0
	s_mov_b32 s14, 0x2d02000
	s_nop 0
	v_addc_co_u32_e32 v3, vcc, 0, v1, vcc
	global_load_dword v61, v[2:3], off nt
	v_add_co_u32_e32 v2, vcc, s14, v0
	s_mov_b32 s14, 0x2d08000
	s_nop 0
	v_addc_co_u32_e32 v3, vcc, 0, v1, vcc
	global_load_dword v59, v[2:3], off offset:2048 nt
	v_add_co_u32_e32 v2, vcc, s14, v0
	s_mov_b32 s14, 0x2d0d000
	s_nop 0
	v_addc_co_u32_e32 v3, vcc, 0, v1, vcc
	global_load_dword v64, v[2:3], off nt
	v_add_co_u32_e32 v2, vcc, s14, v0
	s_mov_b32 s14, 0x2d13000
	s_nop 0
	v_addc_co_u32_e32 v3, vcc, 0, v1, vcc
	global_load_dword v62, v[2:3], off offset:2048 nt
	v_add_co_u32_e32 v2, vcc, s14, v0
	s_mov_b32 s14, 0x2d18000
	s_nop 0
	v_addc_co_u32_e32 v3, vcc, 0, v1, vcc
	global_load_dword v65, v[2:3], off nt
	v_add_co_u32_e32 v2, vcc, s14, v0
	s_mov_b32 s14, 0x2d1e000
	s_nop 0
	v_addc_co_u32_e32 v3, vcc, 0, v1, vcc
	global_load_dword v63, v[2:3], off offset:2048 nt
	v_add_co_u32_e32 v2, vcc, s14, v0
	s_mov_b32 s14, 0x2d23000
	s_nop 0
	v_addc_co_u32_e32 v3, vcc, 0, v1, vcc
	global_load_dword v68, v[2:3], off nt
	v_add_co_u32_e32 v2, vcc, s14, v0
	s_mov_b32 s14, 0x2d29000
	s_nop 0
	v_addc_co_u32_e32 v3, vcc, 0, v1, vcc
	global_load_dword v66, v[2:3], off offset:2048 nt
	v_add_co_u32_e32 v2, vcc, s14, v0
	s_mov_b32 s14, 0x2d2e000
	s_nop 0
	v_addc_co_u32_e32 v3, vcc, 0, v1, vcc
	global_load_dword v69, v[2:3], off nt
	v_add_co_u32_e32 v2, vcc, s14, v0
	s_mov_b32 s14, 0x2d34000
	s_nop 0
	v_addc_co_u32_e32 v3, vcc, 0, v1, vcc
	global_load_dword v67, v[2:3], off offset:2048 nt
	v_add_co_u32_e32 v2, vcc, s14, v0
	s_mov_b32 s14, 0x2d39000
	s_nop 0
	v_addc_co_u32_e32 v3, vcc, 0, v1, vcc
	global_load_dword v70, v[2:3], off nt
	v_add_co_u32_e32 v2, vcc, s14, v0
	s_mov_b32 s14, 0x2d3f000
	s_nop 0
	v_addc_co_u32_e32 v3, vcc, 0, v1, vcc
	global_load_dword v72, v[2:3], off offset:2048 nt
	v_add_co_u32_e32 v2, vcc, s14, v0
	s_mov_b32 s14, 0x2d44000
	s_nop 0
	v_addc_co_u32_e32 v3, vcc, 0, v1, vcc
	global_load_dword v71, v[2:3], off nt
	v_add_co_u32_e32 v2, vcc, s14, v0
	s_mov_b32 s14, 0x2d4a000
	s_nop 0
	v_addc_co_u32_e32 v3, vcc, 0, v1, vcc
	global_load_dword v73, v[2:3], off offset:2048 nt
	v_add_co_u32_e32 v2, vcc, s14, v0
	s_mov_b32 s14, 0x2d4f000
	s_nop 0
	v_addc_co_u32_e32 v3, vcc, 0, v1, vcc
	global_load_dword v74, v[2:3], off nt
	v_add_co_u32_e32 v2, vcc, s14, v0
	s_mov_b32 s14, 0x2d55000
	s_nop 0
	v_addc_co_u32_e32 v3, vcc, 0, v1, vcc
	global_load_dword v75, v[2:3], off offset:2048 nt
	v_add_co_u32_e32 v2, vcc, s14, v0
	s_mov_b32 s14, 0x2d5a000
	s_nop 0
	v_addc_co_u32_e32 v3, vcc, 0, v1, vcc
	v_add_co_u32_e32 v0, vcc, s14, v0
	global_load_dword v76, v[2:3], off nt
	s_nop 0
	v_addc_co_u32_e32 v1, vcc, 0, v1, vcc
	global_load_dword v77, v[0:1], off offset:2048 nt
	s_cmp_eq_u64 s[20:21], 0
	s_cbranch_scc1 .Lcx4_688
; __device__ __forceinline__ void transpose_item(const float* __restrict__ W, int K, int N, bf16* __restrict__ WT, const float* __restrict__ ksc, int mode, int row_off, int item, int lane) {
;     ...
;     if (ksc) {
; #pragma unroll
;         for (int i = 0; i < 64; ++i) v[i] *= ksc[k0 + i];
;     }
	s_lshl_b32 s14, s40, 2
	s_add_u32 s22, s20, s14
	s_addc_u32 s23, s21, 0
	s_add_u32 s20, s22, 0x2000
	s_addc_u32 s21, s23, 0
	global_load_dwordx4 v[0:3], v13, s[20:21] offset:48
	global_load_dwordx4 v[4:7], v13, s[20:21] offset:32
	global_load_dwordx4 v[8:11], v13, s[20:21] offset:16
	global_load_dwordx4 v[86:89], v83, s[22:23]
	global_load_dwordx4 v[160:163], v13, s[20:21] offset:112
	global_load_dwordx4 v[164:167], v13, s[20:21] offset:96
	global_load_dwordx4 v[168:171], v13, s[20:21] offset:80
	global_load_dwordx4 v[172:175], v13, s[20:21] offset:64
	global_load_dwordx4 v[176:179], v13, s[20:21] offset:176
	global_load_dwordx4 v[180:183], v13, s[20:21] offset:160
	global_load_dwordx4 v[184:187], v13, s[20:21] offset:144
	global_load_dwordx4 v[188:191], v13, s[20:21] offset:128
	global_load_dwordx4 v[208:211], v13, s[20:21] offset:224
	global_load_dwordx4 v[212:215], v13, s[20:21] offset:208
	global_load_dwordx4 v[216:219], v13, s[20:21] offset:192
	global_load_dwordx4 v[220:223], v13, s[20:21] offset:240
	s_waitcnt vmcnt(0)
	v_mov_b32_e32 v90, v86
	v_mov_b32_e32 v91, v88
	v_mov_b32_e32 v88, v87
	v_mov_b32_e32 v86, v8
	v_mov_b32_e32 v87, v10
	v_mov_b32_e32 v10, v9
	v_mov_b32_e32 v8, v4
	v_mov_b32_e32 v9, v6
	v_mov_b32_e32 v6, v5
	v_mov_b32_e32 v4, v0
	v_mov_b32_e32 v5, v2
	v_mov_b32_e32 v2, v1
	v_pk_mul_f32 v[14:15], v[14:15], v[88:89]
	v_pk_mul_f32 v[20:21], v[20:21], v[86:87]
	v_pk_mul_f32 v[18:19], v[18:19], v[10:11]
	v_pk_mul_f32 v[24:25], v[24:25], v[8:9]
	v_pk_mul_f32 v[22:23], v[22:23], v[6:7]
	v_pk_mul_f32 v[28:29], v[28:29], v[4:5]
	v_pk_mul_f32 v[26:27], v[26:27], v[2:3]
	v_mov_b32_e32 v0, v160
	v_mov_b32_e32 v1, v161
	v_mov_b32_e32 v2, v162
	v_mov_b32_e32 v3, v163
	v_mov_b32_e32 v4, v164
	v_mov_b32_e32 v5, v165
	v_mov_b32_e32 v6, v166
	v_mov_b32_e32 v7, v167
	v_mov_b32_e32 v8, v168
	v_mov_b32_e32 v9, v169
	v_mov_b32_e32 v10, v170
	v_mov_b32_e32 v11, v171
	v_mov_b32_e32 v86, v172
	v_mov_b32_e32 v87, v173
	v_mov_b32_e32 v88, v174
	v_mov_b32_e32 v89, v175
	v_pk_mul_f32 v[16:17], v[16:17], v[90:91]
	s_waitcnt vmcnt(0)
	v_mov_b32_e32 v90, v86
	v_mov_b32_e32 v91, v88
	v_mov_b32_e32 v88, v87
	v_mov_b32_e32 v86, v8
	v_mov_b32_e32 v87, v10
	v_mov_b32_e32 v10, v9
	v_mov_b32_e32 v8, v4
	v_mov_b32_e32 v9, v6
	v_mov_b32_e32 v6, v5
	v_mov_b32_e32 v4, v0
	v_mov_b32_e32 v5, v2
	v_mov_b32_e32 v2, v1
	v_pk_mul_f32 v[30:31], v[30:31], v[88:89]
	v_pk_mul_f32 v[36:37], v[36:37], v[86:87]
	v_pk_mul_f32 v[34:35], v[34:35], v[10:11]
	v_pk_mul_f32 v[40:41], v[40:41], v[8:9]
	v_pk_mul_f32 v[38:39], v[38:39], v[6:7]
	v_pk_mul_f32 v[44:45], v[44:45], v[4:5]
	v_pk_mul_f32 v[42:43], v[42:43], v[2:3]
	v_mov_b32_e32 v0, v176
	v_mov_b32_e32 v1, v177
	v_mov_b32_e32 v2, v178
	v_mov_b32_e32 v3, v179
	v_mov_b32_e32 v4, v180
	v_mov_b32_e32 v5, v181
	v_mov_b32_e32 v6, v182
	v_mov_b32_e32 v7, v183
	v_mov_b32_e32 v8, v184
	v_mov_b32_e32 v9, v185
	v_mov_b32_e32 v10, v186
	v_mov_b32_e32 v11, v187
	v_mov_b32_e32 v86, v188
	v_mov_b32_e32 v87, v189
	v_mov_b32_e32 v88, v190
	v_mov_b32_e32 v89, v191
	v_pk_mul_f32 v[32:33], v[32:33], v[90:91]
	s_waitcnt vmcnt(0)
	v_mov_b32_e32 v90, v86
	v_mov_b32_e32 v91, v88
	v_mov_b32_e32 v88, v87
	v_mov_b32_e32 v86, v8
	v_mov_b32_e32 v87, v10
	v_mov_b32_e32 v10, v9
	v_mov_b32_e32 v8, v4
	v_mov_b32_e32 v9, v6
	v_mov_b32_e32 v6, v5
	v_mov_b32_e32 v4, v0
	v_mov_b32_e32 v5, v2
	v_mov_b32_e32 v2, v1
	v_pk_mul_f32 v[46:47], v[46:47], v[88:89]
	v_pk_mul_f32 v[52:53], v[52:53], v[86:87]
	v_pk_mul_f32 v[50:51], v[50:51], v[10:11]
	v_pk_mul_f32 v[56:57], v[56:57], v[8:9]
	v_pk_mul_f32 v[54:55], v[54:55], v[6:7]
	v_pk_mul_f32 v[60:61], v[60:61], v[4:5]
	v_pk_mul_f32 v[58:59], v[58:59], v[2:3]
	v_mov_b32_e32 v0, v208
	v_mov_b32_e32 v1, v209
	v_mov_b32_e32 v2, v210
	v_mov_b32_e32 v3, v211
	v_mov_b32_e32 v4, v212
	v_mov_b32_e32 v5, v213
	v_mov_b32_e32 v6, v214
	v_mov_b32_e32 v7, v215
	v_mov_b32_e32 v86, v216
	v_mov_b32_e32 v87, v217
	v_mov_b32_e32 v88, v218
	v_mov_b32_e32 v89, v219
	v_mov_b32_e32 v8, v220
	v_mov_b32_e32 v9, v221
	v_mov_b32_e32 v10, v222
	v_mov_b32_e32 v11, v223
	v_pk_mul_f32 v[48:49], v[48:49], v[90:91]
	s_waitcnt vmcnt(1)
	v_mov_b32_e32 v90, v86
	v_mov_b32_e32 v91, v88
	v_mov_b32_e32 v88, v87
	v_mov_b32_e32 v86, v4
	v_mov_b32_e32 v87, v6
	v_mov_b32_e32 v6, v5
	v_mov_b32_e32 v4, v0
	v_mov_b32_e32 v5, v2
	v_mov_b32_e32 v2, v1
	v_pk_mul_f32 v[64:65], v[64:65], v[90:91]
	v_pk_mul_f32 v[62:63], v[62:63], v[88:89]
	v_pk_mul_f32 v[68:69], v[68:69], v[86:87]
	v_pk_mul_f32 v[66:67], v[66:67], v[6:7]
	v_pk_mul_f32 v[70:71], v[70:71], v[4:5]
	v_pk_mul_f32 v[72:73], v[72:73], v[2:3]
	s_waitcnt vmcnt(0)
	v_pk_mul_f32 v[74:75], v[74:75], v[8:9]
	v_pk_mul_f32 v[76:77], v[76:77], v[10:11]

; __device__ __forceinline__ void transpose_item(const float* __restrict__ W, int K, int N, bf16* __restrict__ WT, const float* __restrict__ ksc, int mode, int row_off, int item, int lane) {
;     const int nblk = N / 64, kb = item / nblk, nb = item % nblk, k0 = 64 * kb, n = 64 * nb + lane;
;     const float* src = W + (size_t)k0 * N + n;
;     float v[64];
; #pragma unroll
;     for (int i = 0; i < 64; ++i) v[i] = __builtin_nontemporal_load(src + (size_t)i * N);
; __device__ __forceinline__ void convert_layer(ArgsP a, int L, int first, int stride, int lane) {
;     ...
;         if (r < I_IN) transpose_item(a->in[3] + (size_t)L * D * INW, D, INW, WIN + (size_t)L * INW * D, a->in[2] + L * D, 1, 0, r, lane);
.Lcx4_697:
	s_andn2_b64 vcc, exec, s[20:21]
	s_cbranch_vccnz .Lcx4_680
	s_load_dwordx4 s[20:23], s[24:25], 0x10
	s_mul_hi_u32 s14, s1, 0xcccccccd
	s_lshr_b32 s14, s14, 5
	s_mul_i32 s15, s14, 0xa00
	s_lshl_b32 s40, s14, 6
	s_mul_i32 s14, s14, 0xa0000
	v_subrev_u32_e32 v12, s15, v82
	s_mul_hi_u32 s15, s40, 0x2800
	s_waitcnt lgkmcnt(0)
	s_add_u32 s22, s22, s14
	s_addc_u32 s23, s23, s15
	v_lshl_add_u64 v[66:67], v[12:13], 2, s[22:23]
	s_mov_b32 s14, 0x1400000
	v_add_co_u32_e32 v0, vcc, s14, v66
	s_mov_b32 s14, 0x1402000
	s_nop 0
	v_addc_co_u32_e32 v1, vcc, 0, v67, vcc
	v_add_co_u32_e32 v2, vcc, s14, v66
	s_mov_b32 s14, 0x1405000
	s_nop 0
	v_addc_co_u32_e32 v3, vcc, 0, v67, vcc
	global_load_dword v0, v[0:1], off nt
	s_cmp_eq_u64 s[20:21], 0
	global_load_dword v1, v[2:3], off offset:2048 nt
	v_add_co_u32_e32 v2, vcc, s14, v66
	s_mov_b32 s14, 0x1407000
	s_nop 0
	v_addc_co_u32_e32 v3, vcc, 0, v67, vcc
	v_add_co_u32_e32 v4, vcc, s14, v66
	s_mov_b32 s14, 0x140a000
	s_nop 0
	v_addc_co_u32_e32 v5, vcc, 0, v67, vcc
	global_load_dword v2, v[2:3], off nt
	s_nop 0
	global_load_dword v3, v[4:5], off offset:2048 nt
	v_add_co_u32_e32 v4, vcc, s14, v66
	s_mov_b32 s14, 0x140c000
	s_nop 0
	v_addc_co_u32_e32 v5, vcc, 0, v67, vcc
	v_add_co_u32_e32 v6, vcc, s14, v66
	s_mov_b32 s14, 0x140f000
	s_nop 0
	v_addc_co_u32_e32 v7, vcc, 0, v67, vcc
	global_load_dword v4, v[4:5], off nt
	s_nop 0
	global_load_dword v5, v[6:7], off offset:2048 nt
	v_add_co_u32_e32 v6, vcc, s14, v66
	s_mov_b32 s14, 0x1411000
	s_nop 0
	v_addc_co_u32_e32 v7, vcc, 0, v67, vcc
	v_add_co_u32_e32 v8, vcc, s14, v66
	s_mov_b32 s14, 0x1414000
	s_nop 0
	v_addc_co_u32_e32 v9, vcc, 0, v67, vcc
	global_load_dword v6, v[6:7], off nt
	s_nop 0
	global_load_dword v7, v[8:9], off offset:2048 nt
	v_add_co_u32_e32 v8, vcc, s14, v66
	s_mov_b32 s14, 0x1416000
	s_nop 0
	v_addc_co_u32_e32 v9, vcc, 0, v67, vcc
	v_add_co_u32_e32 v10, vcc, s14, v66
	s_mov_b32 s14, 0x1419000
	s_nop 0
	v_addc_co_u32_e32 v11, vcc, 0, v67, vcc
	global_load_dword v8, v[8:9], off nt
	s_nop 0
	global_load_dword v9, v[10:11], off offset:2048 nt
	v_add_co_u32_e32 v10, vcc, s14, v66
	s_mov_b32 s14, 0x141b000
	s_nop 0
	v_addc_co_u32_e32 v11, vcc, 0, v67, vcc
	v_add_co_u32_e32 v14, vcc, s14, v66
	s_mov_b32 s14, 0x141e000
	s_nop 0
	v_addc_co_u32_e32 v15, vcc, 0, v67, vcc
	global_load_dword v10, v[10:11], off nt
	s_nop 0
	global_load_dword v11, v[14:15], off offset:2048 nt
	v_add_co_u32_e32 v14, vcc, s14, v66
	s_mov_b32 s14, 0x1420000
	s_nop 0
	v_addc_co_u32_e32 v15, vcc, 0, v67, vcc
	v_add_co_u32_e32 v16, vcc, s14, v66
	s_mov_b32 s14, 0x1423000
	s_nop 0
	v_addc_co_u32_e32 v17, vcc, 0, v67, vcc
	global_load_dword v14, v[14:15], off nt
	s_nop 0
	global_load_dword v15, v[16:17], off offset:2048 nt
	v_add_co_u32_e32 v16, vcc, s14, v66
	s_mov_b32 s14, 0x1425000
	s_nop 0
	v_addc_co_u32_e32 v17, vcc, 0, v67, vcc
	v_add_co_u32_e32 v18, vcc, s14, v66
	s_mov_b32 s14, 0x1428000
	s_nop 0
	v_addc_co_u32_e32 v19, vcc, 0, v67, vcc
	global_load_dword v16, v[16:17], off nt
	s_nop 0
	global_load_dword v17, v[18:19], off offset:2048 nt
	v_add_co_u32_e32 v18, vcc, s14, v66
	s_mov_b32 s14, 0x142a000
	s_nop 0
	v_addc_co_u32_e32 v19, vcc, 0, v67, vcc
	v_add_co_u32_e32 v20, vcc, s14, v66
	s_mov_b32 s14, 0x142d000
	s_nop 0
	v_addc_co_u32_e32 v21, vcc, 0, v67, vcc
	global_load_dword v18, v[18:19], off nt
	s_nop 0
	global_load_dword v19, v[20:21], off offset:2048 nt
	v_add_co_u32_e32 v20, vcc, s14, v66
	s_mov_b32 s14, 0x142f000
	s_nop 0
	v_addc_co_u32_e32 v21, vcc, 0, v67, vcc
	v_add_co_u32_e32 v22, vcc, s14, v66
	s_mov_b32 s14, 0x1432000
	s_nop 0
	v_addc_co_u32_e32 v23, vcc, 0, v67, vcc
	global_load_dword v20, v[20:21], off nt
	s_nop 0
	global_load_dword v21, v[22:23], off offset:2048 nt
	v_add_co_u32_e32 v22, vcc, s14, v66
	s_mov_b32 s14, 0x1434000
	s_nop 0
	v_addc_co_u32_e32 v23, vcc, 0, v67, vcc
	v_add_co_u32_e32 v24, vcc, s14, v66
	s_mov_b32 s14, 0x1437000
	s_nop 0
	v_addc_co_u32_e32 v25, vcc, 0, v67, vcc
	global_load_dword v22, v[22:23], off nt
	s_nop 0
	global_load_dword v23, v[24:25], off offset:2048 nt
	v_add_co_u32_e32 v24, vcc, s14, v66
	s_nop 1
	v_addc_co_u32_e32 v25, vcc, 0, v67, vcc
	v_add_co_u32_e32 v26, vcc, s33, v66
	global_load_dword v24, v[24:25], off nt
	s_nop 0
	v_addc_co_u32_e32 v27, vcc, 0, v67, vcc
	global_load_dword v25, v[26:27], off offset:2048 nt
	v_add_co_u32_e32 v26, vcc, s44, v66
	s_nop 1
	v_addc_co_u32_e32 v27, vcc, 0, v67, vcc
	v_add_co_u32_e32 v28, vcc, s45, v66
	global_load_dword v26, v[26:27], off nt
	s_nop 0
	v_addc_co_u32_e32 v29, vcc, 0, v67, vcc
	global_load_dword v27, v[28:29], off offset:2048 nt
	v_add_co_u32_e32 v28, vcc, s46, v66
	s_nop 1
	v_addc_co_u32_e32 v29, vcc, 0, v67, vcc
	v_add_co_u32_e32 v30, vcc, s47, v66
	global_load_dword v28, v[28:29], off nt
	s_nop 0
	v_addc_co_u32_e32 v31, vcc, 0, v67, vcc
	global_load_dword v29, v[30:31], off offset:2048 nt
	v_add_co_u32_e32 v30, vcc, s48, v66
	s_nop 1
	v_addc_co_u32_e32 v31, vcc, 0, v67, vcc
	v_add_co_u32_e32 v32, vcc, s49, v66
	global_load_dword v30, v[30:31], off nt
	s_nop 0
	v_addc_co_u32_e32 v33, vcc, 0, v67, vcc
	global_load_dword v31, v[32:33], off offset:2048 nt
	v_add_co_u32_e32 v32, vcc, s50, v66
	s_nop 1
	v_addc_co_u32_e32 v33, vcc, 0, v67, vcc
	v_add_co_u32_e32 v34, vcc, s51, v66
	global_load_dword v32, v[32:33], off nt
	s_nop 0
	v_addc_co_u32_e32 v35, vcc, 0, v67, vcc
	global_load_dword v33, v[34:35], off offset:2048 nt
	v_add_co_u32_e32 v34, vcc, s52, v66
	s_nop 1
	v_addc_co_u32_e32 v35, vcc, 0, v67, vcc
	v_add_co_u32_e32 v36, vcc, s53, v66
	global_load_dword v34, v[34:35], off nt
	s_nop 0
	v_addc_co_u32_e32 v37, vcc, 0, v67, vcc
	global_load_dword v35, v[36:37], off offset:2048 nt
; __device__ __forceinline__ void transpose_item(const float* __restrict__ W, int K, int N, bf16* __restrict__ WT, const float* __restrict__ ksc, int mode, int row_off, int item, int lane) {
;     ...
;     for (int i = 0; i < 64; ++i) v[i] = __builtin_nontemporal_load(src + (size_t)i * N);
	v_add_co_u32_e32 v36, vcc, s54, v66
	s_nop 1
	v_addc_co_u32_e32 v37, vcc, 0, v67, vcc
	v_add_co_u32_e32 v38, vcc, s55, v66
	global_load_dword v36, v[36:37], off nt
	s_nop 0
	v_addc_co_u32_e32 v39, vcc, 0, v67, vcc
	global_load_dword v37, v[38:39], off offset:2048 nt
	v_add_co_u32_e32 v38, vcc, s56, v66
	s_nop 1
	v_addc_co_u32_e32 v39, vcc, 0, v67, vcc
	v_add_co_u32_e32 v40, vcc, s57, v66
	global_load_dword v38, v[38:39], off nt
	s_nop 0
	v_addc_co_u32_e32 v41, vcc, 0, v67, vcc
	global_load_dword v39, v[40:41], off offset:2048 nt
	v_add_co_u32_e32 v40, vcc, s58, v66
	s_nop 1
	v_addc_co_u32_e32 v41, vcc, 0, v67, vcc
	v_add_co_u32_e32 v42, vcc, s59, v66
	global_load_dword v40, v[40:41], off nt
	s_nop 0
	v_addc_co_u32_e32 v43, vcc, 0, v67, vcc
	global_load_dword v41, v[42:43], off offset:2048 nt
	v_add_co_u32_e32 v42, vcc, s60, v66
	s_nop 1
	v_addc_co_u32_e32 v43, vcc, 0, v67, vcc
	v_add_co_u32_e32 v44, vcc, s61, v66
	global_load_dword v42, v[42:43], off nt
	s_nop 0
	v_addc_co_u32_e32 v45, vcc, 0, v67, vcc
	global_load_dword v43, v[44:45], off offset:2048 nt
	v_add_co_u32_e32 v44, vcc, s62, v66
	s_nop 1
	v_addc_co_u32_e32 v45, vcc, 0, v67, vcc
	v_add_co_u32_e32 v46, vcc, s63, v66
	global_load_dword v44, v[44:45], off nt
	s_nop 0
	v_addc_co_u32_e32 v47, vcc, 0, v67, vcc
	global_load_dword v45, v[46:47], off offset:2048 nt
	v_add_co_u32_e32 v46, vcc, s64, v66
	s_nop 1
	v_addc_co_u32_e32 v47, vcc, 0, v67, vcc
	v_add_co_u32_e32 v48, vcc, s65, v66
	global_load_dword v46, v[46:47], off nt
	s_nop 0
	v_addc_co_u32_e32 v49, vcc, 0, v67, vcc
	global_load_dword v47, v[48:49], off offset:2048 nt
	v_add_co_u32_e32 v48, vcc, s66, v66
	s_nop 1
	v_addc_co_u32_e32 v49, vcc, 0, v67, vcc
	v_add_co_u32_e32 v50, vcc, s67, v66
	global_load_dword v48, v[48:49], off nt
	s_nop 0
	v_addc_co_u32_e32 v51, vcc, 0, v67, vcc
	global_load_dword v49, v[50:51], off offset:2048 nt
	v_add_co_u32_e32 v50, vcc, s68, v66
	s_nop 1
	v_addc_co_u32_e32 v51, vcc, 0, v67, vcc
	v_add_co_u32_e32 v52, vcc, s69, v66
	global_load_dword v50, v[50:51], off nt
	s_nop 0
	v_addc_co_u32_e32 v53, vcc, 0, v67, vcc
	global_load_dword v51, v[52:53], off offset:2048 nt
	v_add_co_u32_e32 v52, vcc, s70, v66
	s_nop 1
	v_addc_co_u32_e32 v53, vcc, 0, v67, vcc
	v_add_co_u32_e32 v54, vcc, s71, v66
	global_load_dword v52, v[52:53], off nt
	s_nop 0
	v_addc_co_u32_e32 v55, vcc, 0, v67, vcc
	global_load_dword v53, v[54:55], off offset:2048 nt
	v_add_co_u32_e32 v54, vcc, s72, v66
	s_nop 1
	v_addc_co_u32_e32 v55, vcc, 0, v67, vcc
	v_add_co_u32_e32 v56, vcc, s73, v66
	global_load_dword v54, v[54:55], off nt
	s_nop 0
	v_addc_co_u32_e32 v57, vcc, 0, v67, vcc
	global_load_dword v55, v[56:57], off offset:2048 nt
	v_add_co_u32_e32 v56, vcc, s74, v66
	s_nop 1
	v_addc_co_u32_e32 v57, vcc, 0, v67, vcc
	v_add_co_u32_e32 v58, vcc, s75, v66
	global_load_dword v56, v[56:57], off nt
	s_nop 0
	v_addc_co_u32_e32 v59, vcc, 0, v67, vcc
	global_load_dword v57, v[58:59], off offset:2048 nt
	v_add_co_u32_e32 v58, vcc, s76, v66
	s_nop 1
	v_addc_co_u32_e32 v59, vcc, 0, v67, vcc
	v_add_co_u32_e32 v60, vcc, s77, v66
	global_load_dword v58, v[58:59], off nt
	s_nop 0
	v_addc_co_u32_e32 v61, vcc, 0, v67, vcc
	global_load_dword v59, v[60:61], off offset:2048 nt
	v_add_co_u32_e32 v60, vcc, s78, v66
	s_nop 1
	v_addc_co_u32_e32 v61, vcc, 0, v67, vcc
	v_add_co_u32_e32 v62, vcc, s79, v66
	global_load_dword v60, v[60:61], off nt
	s_nop 0
	v_addc_co_u32_e32 v63, vcc, 0, v67, vcc
	global_load_dword v61, v[62:63], off offset:2048 nt
	v_add_co_u32_e32 v62, vcc, s80, v66
	s_nop 1
	v_addc_co_u32_e32 v63, vcc, 0, v67, vcc
	v_add_co_u32_e32 v64, vcc, s81, v66
	global_load_dword v62, v[62:63], off nt
	s_nop 0
	v_addc_co_u32_e32 v65, vcc, 0, v67, vcc
	global_load_dword v63, v[64:65], off offset:2048 nt
	v_add_co_u32_e32 v64, vcc, s82, v66
	s_nop 1
	v_addc_co_u32_e32 v65, vcc, 0, v67, vcc
	v_add_co_u32_e32 v66, vcc, s83, v66
	global_load_dword v64, v[64:65], off nt
	s_nop 0
	v_addc_co_u32_e32 v67, vcc, 0, v67, vcc
	global_load_dword v65, v[66:67], off offset:2048 nt
	s_cbranch_scc1 .Lcx4_679
; __device__ __forceinline__ void transpose_item(const float* __restrict__ W, int K, int N, bf16* __restrict__ WT, const float* __restrict__ ksc, int mode, int row_off, int item, int lane) {
;     ...
;     if (ksc) {
; #pragma unroll
;         for (int i = 0; i < 64; ++i) v[i] *= ksc[k0 + i];
;     }
	s_lshl_b64 s[22:23], s[40:41], 2
	s_add_u32 s22, s20, s22
	s_addc_u32 s23, s21, s23
	s_add_u32 s20, s22, 0x2000
	s_addc_u32 s21, s23, 0
	global_load_dwordx4 v[66:69], v13, s[20:21] offset:48
	global_load_dwordx4 v[70:73], v13, s[20:21] offset:32
	global_load_dwordx4 v[74:77], v13, s[20:21] offset:16
	global_load_dwordx4 v[86:89], v83, s[22:23]
	global_load_dwordx4 v[160:163], v13, s[20:21] offset:112
	global_load_dwordx4 v[164:167], v13, s[20:21] offset:96
	global_load_dwordx4 v[168:171], v13, s[20:21] offset:80
	global_load_dwordx4 v[172:175], v13, s[20:21] offset:64
	global_load_dwordx4 v[176:179], v13, s[20:21] offset:176
	global_load_dwordx4 v[180:183], v13, s[20:21] offset:160
	global_load_dwordx4 v[184:187], v13, s[20:21] offset:144
	global_load_dwordx4 v[188:191], v13, s[20:21] offset:128
	global_load_dwordx4 v[208:211], v13, s[20:21] offset:240
	global_load_dwordx4 v[212:215], v13, s[20:21] offset:224
	global_load_dwordx4 v[216:219], v13, s[20:21] offset:208
	global_load_dwordx4 v[220:223], v13, s[20:21] offset:192
	s_waitcnt vmcnt(0)
	v_pk_mul_f32 v[14:15], v[14:15], v[66:67]
	s_waitcnt vmcnt(2)
	v_pk_mul_f32 v[8:9], v[8:9], v[70:71]
	s_waitcnt vmcnt(1)
	v_pk_mul_f32 v[4:5], v[4:5], v[74:75]
	s_waitcnt vmcnt(0)
	v_pk_mul_f32 v[0:1], v[0:1], v[86:87]
	v_pk_mul_f32 v[2:3], v[2:3], v[88:89]
	v_pk_mul_f32 v[6:7], v[6:7], v[76:77]
	v_pk_mul_f32 v[10:11], v[10:11], v[72:73]
	v_pk_mul_f32 v[16:17], v[16:17], v[68:69]
	v_mov_b32_e32 v66, v160
	v_mov_b32_e32 v67, v161
	v_mov_b32_e32 v68, v162
	v_mov_b32_e32 v69, v163
	v_mov_b32_e32 v70, v164
	v_mov_b32_e32 v71, v165
	v_mov_b32_e32 v72, v166
	v_mov_b32_e32 v73, v167
	v_mov_b32_e32 v74, v168
	v_mov_b32_e32 v75, v169
	v_mov_b32_e32 v76, v170
	v_mov_b32_e32 v77, v171
	v_mov_b32_e32 v86, v172
	v_mov_b32_e32 v87, v173
	v_mov_b32_e32 v88, v174
	v_mov_b32_e32 v89, v175
	s_waitcnt vmcnt(3)
	v_pk_mul_f32 v[30:31], v[30:31], v[66:67]
	s_waitcnt vmcnt(2)
	v_pk_mul_f32 v[26:27], v[26:27], v[70:71]
	s_waitcnt vmcnt(1)
	v_pk_mul_f32 v[22:23], v[22:23], v[74:75]
	s_waitcnt vmcnt(0)
	v_pk_mul_f32 v[18:19], v[18:19], v[86:87]
	v_pk_mul_f32 v[20:21], v[20:21], v[88:89]
	v_pk_mul_f32 v[24:25], v[24:25], v[76:77]
	v_pk_mul_f32 v[28:29], v[28:29], v[72:73]
	v_pk_mul_f32 v[32:33], v[32:33], v[68:69]
	v_mov_b32_e32 v66, v176
	v_mov_b32_e32 v67, v177
	v_mov_b32_e32 v68, v178
	v_mov_b32_e32 v69, v179
	v_mov_b32_e32 v70, v180
	v_mov_b32_e32 v71, v181
	v_mov_b32_e32 v72, v182
	v_mov_b32_e32 v73, v183
	v_mov_b32_e32 v74, v184
	v_mov_b32_e32 v75, v185
	v_mov_b32_e32 v76, v186
	v_mov_b32_e32 v77, v187
	v_mov_b32_e32 v86, v188
	v_mov_b32_e32 v87, v189
	v_mov_b32_e32 v88, v190
	v_mov_b32_e32 v89, v191
	s_waitcnt vmcnt(3)
	v_pk_mul_f32 v[46:47], v[46:47], v[66:67]
	s_waitcnt vmcnt(2)
	v_pk_mul_f32 v[42:43], v[42:43], v[70:71]
	s_waitcnt vmcnt(1)
	v_pk_mul_f32 v[38:39], v[38:39], v[74:75]
	s_waitcnt vmcnt(0)
	v_pk_mul_f32 v[34:35], v[34:35], v[86:87]
	v_pk_mul_f32 v[36:37], v[36:37], v[88:89]
	v_pk_mul_f32 v[40:41], v[40:41], v[76:77]
	v_pk_mul_f32 v[44:45], v[44:45], v[72:73]
	v_pk_mul_f32 v[48:49], v[48:49], v[68:69]
	v_mov_b32_e32 v66, v208
	v_mov_b32_e32 v67, v209
	v_mov_b32_e32 v68, v210
	v_mov_b32_e32 v69, v211
	v_mov_b32_e32 v70, v212
	v_mov_b32_e32 v71, v213
	v_mov_b32_e32 v72, v214
	v_mov_b32_e32 v73, v215
	v_mov_b32_e32 v74, v216
	v_mov_b32_e32 v75, v217
	v_mov_b32_e32 v76, v218
	v_mov_b32_e32 v77, v219
	v_mov_b32_e32 v86, v220
	v_mov_b32_e32 v87, v221
	v_mov_b32_e32 v88, v222
	v_mov_b32_e32 v89, v223
	s_waitcnt vmcnt(3)
	v_pk_mul_f32 v[62:63], v[62:63], v[66:67]
	s_waitcnt vmcnt(2)
	v_pk_mul_f32 v[58:59], v[58:59], v[70:71]
	s_waitcnt vmcnt(1)
	v_pk_mul_f32 v[54:55], v[54:55], v[74:75]
	s_waitcnt vmcnt(0)
	v_pk_mul_f32 v[50:51], v[50:51], v[86:87]
	v_pk_mul_f32 v[52:53], v[52:53], v[88:89]
	v_pk_mul_f32 v[56:57], v[56:57], v[76:77]
	v_pk_mul_f32 v[60:61], v[60:61], v[72:73]
	v_pk_mul_f32 v[64:65], v[64:65], v[68:69]
	s_branch .Lcx4_679

; __device__ __forceinline__ void transpose_item(const float* __restrict__ W, int K, int N, bf16* __restrict__ WT, const float* __restrict__ ksc, int mode, int row_off, int item, int lane) {
;     const int nblk = N / 64, kb = item / nblk, nb = item % nblk, k0 = 64 * kb, n = 64 * nb + lane;
;     const float* src = W + (size_t)k0 * N + n;
;     float v[64];
; #pragma unroll
;     for (int i = 0; i < 64; ++i) v[i] = __builtin_nontemporal_load(src + (size_t)i * N);
; __device__ __forceinline__ void convert_layer(ArgsP a, int L, int first, int stride, int lane) {
;     ...
;         else if (r < I_IN + I_OUT + I_GU) transpose_item(a->in[18] + (size_t)L * D * GU, D, GU, WGU + (size_t)L * GU * D, a->in[17] + L * D, 2, 0, r - I_IN - I_OUT, lane);
.LBB0_1161:
	s_andn2_b64 vcc, exec, s[16:17]
	s_cbranch_vccnz .LBB0_1169
	s_add_i32 s0, s3, 0xfc80
	s_and_b32 s4, s0, 0xffff
	s_mul_i32 s4, s4, 0xba2f
	s_load_dwordx4 s[16:19], s[14:15], 0x88
	s_lshr_b32 s5, s4, 16
	s_lshr_b32 s4, s4, 22
	s_mulk_i32 s4, 0x58
	s_sub_i32 s0, s0, s4
	s_and_b32 s46, s0, 0xffff
	s_and_b32 s0, s5, 0xffc0
	s_lshl_b32 s33, s46, 6
	s_mul_i32 s4, s0, 0x5800
	v_or_b32_e32 v78, s33, v80
	s_waitcnt lgkmcnt(0)
	s_add_u32 s18, s18, s4
	s_addc_u32 s19, s19, 0
	v_lshlrev_b32_e32 v12, 2, v78
	v_lshl_add_u64 v[0:1], s[18:19], 0, v[12:13]
	s_mov_b32 s4, 0x4200000
	v_add_co_u32_e32 v2, vcc, s4, v0
	s_mov_b32 s4, 0x4205000
	s_nop 0
	v_addc_co_u32_e32 v3, vcc, 0, v1, vcc
	global_load_dword v16, v[2:3], off nt
	v_add_co_u32_e32 v2, vcc, s4, v0
	s_mov_b32 s4, 0x420b000
	s_nop 0
	v_addc_co_u32_e32 v3, vcc, 0, v1, vcc
	global_load_dword v14, v[2:3], off offset:2048 nt
	v_add_co_u32_e32 v2, vcc, s4, v0
	s_mov_b32 s4, 0x4210000
	s_nop 0
	v_addc_co_u32_e32 v3, vcc, 0, v1, vcc
	global_load_dword v17, v[2:3], off nt
	v_add_co_u32_e32 v2, vcc, s4, v0
	s_mov_b32 s4, 0x4216000
	s_nop 0
	v_addc_co_u32_e32 v3, vcc, 0, v1, vcc
	global_load_dword v15, v[2:3], off offset:2048 nt
	v_add_co_u32_e32 v2, vcc, s4, v0
	s_mov_b32 s4, 0x421b000
	s_nop 0
	v_addc_co_u32_e32 v3, vcc, 0, v1, vcc
	global_load_dword v20, v[2:3], off nt
	v_add_co_u32_e32 v2, vcc, s4, v0
	s_mov_b32 s4, 0x4221000
	s_nop 0
	v_addc_co_u32_e32 v3, vcc, 0, v1, vcc
	global_load_dword v18, v[2:3], off offset:2048 nt
	v_add_co_u32_e32 v2, vcc, s4, v0
	s_mov_b32 s4, 0x4226000
	s_nop 0
	v_addc_co_u32_e32 v3, vcc, 0, v1, vcc
	global_load_dword v21, v[2:3], off nt
	v_add_co_u32_e32 v2, vcc, s4, v0
	s_mov_b32 s4, 0x422c000
	s_nop 0
	v_addc_co_u32_e32 v3, vcc, 0, v1, vcc
	global_load_dword v19, v[2:3], off offset:2048 nt
	v_add_co_u32_e32 v2, vcc, s4, v0
	s_mov_b32 s4, 0x4231000
	s_nop 0
	v_addc_co_u32_e32 v3, vcc, 0, v1, vcc
	global_load_dword v24, v[2:3], off nt
	v_add_co_u32_e32 v2, vcc, s4, v0
	s_mov_b32 s4, 0x4237000
	s_nop 0
	v_addc_co_u32_e32 v3, vcc, 0, v1, vcc
	global_load_dword v22, v[2:3], off offset:2048 nt
	v_add_co_u32_e32 v2, vcc, s4, v0
	s_mov_b32 s4, 0x423c000
	s_nop 0
	v_addc_co_u32_e32 v3, vcc, 0, v1, vcc
	global_load_dword v25, v[2:3], off nt
	v_add_co_u32_e32 v2, vcc, s4, v0
	s_mov_b32 s4, 0x4242000
	s_nop 0
	v_addc_co_u32_e32 v3, vcc, 0, v1, vcc
	global_load_dword v23, v[2:3], off offset:2048 nt
	v_add_co_u32_e32 v2, vcc, s4, v0
	s_mov_b32 s4, 0x4247000
	s_nop 0
	v_addc_co_u32_e32 v3, vcc, 0, v1, vcc
	global_load_dword v28, v[2:3], off nt
	v_add_co_u32_e32 v2, vcc, s4, v0
	s_mov_b32 s4, 0x424d000
	s_nop 0
	v_addc_co_u32_e32 v3, vcc, 0, v1, vcc
	global_load_dword v26, v[2:3], off offset:2048 nt
	v_add_co_u32_e32 v2, vcc, s4, v0
	s_mov_b32 s4, 0x4252000
	s_nop 0
	v_addc_co_u32_e32 v3, vcc, 0, v1, vcc
	global_load_dword v29, v[2:3], off nt
	v_add_co_u32_e32 v2, vcc, s4, v0
	s_mov_b32 s4, 0x4258000
	s_nop 0
	v_addc_co_u32_e32 v3, vcc, 0, v1, vcc
	global_load_dword v27, v[2:3], off offset:2048 nt
	v_add_co_u32_e32 v2, vcc, s4, v0
	s_mov_b32 s4, 0x425d000
	s_nop 0
	v_addc_co_u32_e32 v3, vcc, 0, v1, vcc
	global_load_dword v32, v[2:3], off nt
	v_add_co_u32_e32 v2, vcc, s4, v0
	s_mov_b32 s4, 0x4263000
	s_nop 0
	v_addc_co_u32_e32 v3, vcc, 0, v1, vcc
	global_load_dword v30, v[2:3], off offset:2048 nt
	v_add_co_u32_e32 v2, vcc, s4, v0
	s_mov_b32 s4, 0x4268000
	s_nop 0
	v_addc_co_u32_e32 v3, vcc, 0, v1, vcc
	global_load_dword v33, v[2:3], off nt
	v_add_co_u32_e32 v2, vcc, s4, v0
	s_mov_b32 s4, 0x426e000
	s_nop 0
	v_addc_co_u32_e32 v3, vcc, 0, v1, vcc
	global_load_dword v31, v[2:3], off offset:2048 nt
	v_add_co_u32_e32 v2, vcc, s4, v0
	s_mov_b32 s4, 0x4273000
	s_nop 0
	v_addc_co_u32_e32 v3, vcc, 0, v1, vcc
	global_load_dword v36, v[2:3], off nt
	v_add_co_u32_e32 v2, vcc, s4, v0
	s_mov_b32 s4, 0x4279000
	s_nop 0
	v_addc_co_u32_e32 v3, vcc, 0, v1, vcc
	global_load_dword v34, v[2:3], off offset:2048 nt
	v_add_co_u32_e32 v2, vcc, s4, v0
	s_mov_b32 s4, 0x427e000
	s_nop 0
	v_addc_co_u32_e32 v3, vcc, 0, v1, vcc
	global_load_dword v37, v[2:3], off nt
	v_add_co_u32_e32 v2, vcc, s4, v0
	s_mov_b32 s4, 0x4284000
	s_nop 0
	v_addc_co_u32_e32 v3, vcc, 0, v1, vcc
	global_load_dword v35, v[2:3], off offset:2048 nt
	v_add_co_u32_e32 v2, vcc, s4, v0
	s_mov_b32 s4, 0x4289000
	s_nop 0
	v_addc_co_u32_e32 v3, vcc, 0, v1, vcc
	global_load_dword v40, v[2:3], off nt
	v_add_co_u32_e32 v2, vcc, s4, v0
	s_mov_b32 s4, 0x428f000
	s_nop 0
	v_addc_co_u32_e32 v3, vcc, 0, v1, vcc
	global_load_dword v38, v[2:3], off offset:2048 nt
	v_add_co_u32_e32 v2, vcc, s4, v0
	s_mov_b32 s4, 0x4294000
	s_nop 0
	v_addc_co_u32_e32 v3, vcc, 0, v1, vcc
	global_load_dword v41, v[2:3], off nt
	v_add_co_u32_e32 v2, vcc, s4, v0
	s_mov_b32 s4, 0x429a000
	s_nop 0
	v_addc_co_u32_e32 v3, vcc, 0, v1, vcc
	global_load_dword v39, v[2:3], off offset:2048 nt
	v_add_co_u32_e32 v2, vcc, s4, v0
	s_mov_b32 s4, 0x429f000
	s_nop 0
	v_addc_co_u32_e32 v3, vcc, 0, v1, vcc
	global_load_dword v44, v[2:3], off nt
	v_add_co_u32_e32 v2, vcc, s4, v0
	s_mov_b32 s4, 0x42a5000
	s_nop 0
	v_addc_co_u32_e32 v3, vcc, 0, v1, vcc
	global_load_dword v42, v[2:3], off offset:2048 nt
	v_add_co_u32_e32 v2, vcc, s4, v0
	s_mov_b32 s4, 0x42aa000
	s_nop 0
	v_addc_co_u32_e32 v3, vcc, 0, v1, vcc
	global_load_dword v45, v[2:3], off nt
	v_add_co_u32_e32 v2, vcc, s4, v0
	s_mov_b32 s4, 0x42b0000
	s_nop 0
	v_addc_co_u32_e32 v3, vcc, 0, v1, vcc
	global_load_dword v43, v[2:3], off offset:2048 nt
	v_add_co_u32_e32 v2, vcc, s4, v0
	s_mov_b32 s4, 0x42b5000
	s_nop 0
	v_addc_co_u32_e32 v3, vcc, 0, v1, vcc
	global_load_dword v48, v[2:3], off nt
	v_add_co_u32_e32 v2, vcc, s4, v0
; __device__ __forceinline__ void transpose_item(const float* __restrict__ W, int K, int N, bf16* __restrict__ WT, const float* __restrict__ ksc, int mode, int row_off, int item, int lane) {
;     ...
;     for (int i = 0; i < 64; ++i) v[i] = __builtin_nontemporal_load(src + (size_t)i * N);
	s_mov_b32 s4, 0x42bb000
	s_nop 0
	v_addc_co_u32_e32 v3, vcc, 0, v1, vcc
	global_load_dword v46, v[2:3], off offset:2048 nt
	v_add_co_u32_e32 v2, vcc, s4, v0
	s_mov_b32 s4, 0x42c0000
	s_nop 0
	v_addc_co_u32_e32 v3, vcc, 0, v1, vcc
	global_load_dword v49, v[2:3], off nt
	v_add_co_u32_e32 v2, vcc, s4, v0
	s_mov_b32 s4, 0x42c6000
	s_nop 0
	v_addc_co_u32_e32 v3, vcc, 0, v1, vcc
	global_load_dword v47, v[2:3], off offset:2048 nt
	v_add_co_u32_e32 v2, vcc, s4, v0
	s_mov_b32 s4, 0x42cb000
	s_nop 0
	v_addc_co_u32_e32 v3, vcc, 0, v1, vcc
	global_load_dword v52, v[2:3], off nt
	v_add_co_u32_e32 v2, vcc, s4, v0
	s_mov_b32 s4, 0x42d1000
	s_nop 0
	v_addc_co_u32_e32 v3, vcc, 0, v1, vcc
	global_load_dword v50, v[2:3], off offset:2048 nt
	v_add_co_u32_e32 v2, vcc, s4, v0
	s_mov_b32 s4, 0x42d6000
	s_nop 0
	v_addc_co_u32_e32 v3, vcc, 0, v1, vcc
	global_load_dword v53, v[2:3], off nt
	v_add_co_u32_e32 v2, vcc, s4, v0
	s_mov_b32 s4, 0x42dc000
	s_nop 0
	v_addc_co_u32_e32 v3, vcc, 0, v1, vcc
	global_load_dword v51, v[2:3], off offset:2048 nt
	v_add_co_u32_e32 v2, vcc, s4, v0
	s_mov_b32 s4, 0x42e1000
	s_nop 0
	v_addc_co_u32_e32 v3, vcc, 0, v1, vcc
	global_load_dword v56, v[2:3], off nt
	v_add_co_u32_e32 v2, vcc, s4, v0
	s_mov_b32 s4, 0x42e7000
	s_nop 0
	v_addc_co_u32_e32 v3, vcc, 0, v1, vcc
	global_load_dword v54, v[2:3], off offset:2048 nt
	v_add_co_u32_e32 v2, vcc, s4, v0
	s_mov_b32 s4, 0x42ec000
	s_nop 0
	v_addc_co_u32_e32 v3, vcc, 0, v1, vcc
	global_load_dword v57, v[2:3], off nt
	v_add_co_u32_e32 v2, vcc, s4, v0
	s_mov_b32 s4, 0x42f2000
	s_nop 0
	v_addc_co_u32_e32 v3, vcc, 0, v1, vcc
	global_load_dword v55, v[2:3], off offset:2048 nt
	v_add_co_u32_e32 v2, vcc, s4, v0
	s_mov_b32 s4, 0x42f7000
	s_nop 0
	v_addc_co_u32_e32 v3, vcc, 0, v1, vcc
	global_load_dword v60, v[2:3], off nt
	v_add_co_u32_e32 v2, vcc, s4, v0
	s_mov_b32 s4, 0x42fd000
	s_nop 0
	v_addc_co_u32_e32 v3, vcc, 0, v1, vcc
	global_load_dword v58, v[2:3], off offset:2048 nt
	v_add_co_u32_e32 v2, vcc, s4, v0
	s_mov_b32 s4, 0x4302000
	s_nop 0
	v_addc_co_u32_e32 v3, vcc, 0, v1, vcc
	global_load_dword v61, v[2:3], off nt
	v_add_co_u32_e32 v2, vcc, s4, v0
	s_mov_b32 s4, 0x4308000
	s_nop 0
	v_addc_co_u32_e32 v3, vcc, 0, v1, vcc
	global_load_dword v59, v[2:3], off offset:2048 nt
	v_add_co_u32_e32 v2, vcc, s4, v0
	s_mov_b32 s4, 0x430d000
	s_nop 0
	v_addc_co_u32_e32 v3, vcc, 0, v1, vcc
	global_load_dword v64, v[2:3], off nt
	v_add_co_u32_e32 v2, vcc, s4, v0
	s_mov_b32 s4, 0x4313000
	s_nop 0
	v_addc_co_u32_e32 v3, vcc, 0, v1, vcc
	global_load_dword v62, v[2:3], off offset:2048 nt
	v_add_co_u32_e32 v2, vcc, s4, v0
	s_mov_b32 s4, 0x4318000
	s_nop 0
	v_addc_co_u32_e32 v3, vcc, 0, v1, vcc
	global_load_dword v65, v[2:3], off nt
	v_add_co_u32_e32 v2, vcc, s4, v0
	s_mov_b32 s4, 0x431e000
	s_nop 0
	v_addc_co_u32_e32 v3, vcc, 0, v1, vcc
	global_load_dword v63, v[2:3], off offset:2048 nt
	v_add_co_u32_e32 v2, vcc, s4, v0
	s_mov_b32 s4, 0x4323000
	s_nop 0
	v_addc_co_u32_e32 v3, vcc, 0, v1, vcc
	global_load_dword v68, v[2:3], off nt
	v_add_co_u32_e32 v2, vcc, s4, v0
	s_mov_b32 s4, 0x4329000
	s_nop 0
	v_addc_co_u32_e32 v3, vcc, 0, v1, vcc
	global_load_dword v66, v[2:3], off offset:2048 nt
	v_add_co_u32_e32 v2, vcc, s4, v0
	s_mov_b32 s4, 0x432e000
	s_nop 0
	v_addc_co_u32_e32 v3, vcc, 0, v1, vcc
	global_load_dword v69, v[2:3], off nt
	v_add_co_u32_e32 v2, vcc, s4, v0
	s_mov_b32 s4, 0x4334000
	s_nop 0
	v_addc_co_u32_e32 v3, vcc, 0, v1, vcc
	global_load_dword v67, v[2:3], off offset:2048 nt
	v_add_co_u32_e32 v2, vcc, s4, v0
	s_mov_b32 s4, 0x4339000
	s_nop 0
	v_addc_co_u32_e32 v3, vcc, 0, v1, vcc
	global_load_dword v70, v[2:3], off nt
	v_add_co_u32_e32 v2, vcc, s4, v0
	s_mov_b32 s4, 0x433f000
	s_nop 0
	v_addc_co_u32_e32 v3, vcc, 0, v1, vcc
	global_load_dword v72, v[2:3], off offset:2048 nt
	v_add_co_u32_e32 v2, vcc, s4, v0
	s_mov_b32 s4, 0x4344000
	s_nop 0
	v_addc_co_u32_e32 v3, vcc, 0, v1, vcc
	global_load_dword v71, v[2:3], off nt
	v_add_co_u32_e32 v2, vcc, s4, v0
	s_mov_b32 s4, 0x434a000
	s_nop 0
	v_addc_co_u32_e32 v3, vcc, 0, v1, vcc
	global_load_dword v73, v[2:3], off offset:2048 nt
	v_add_co_u32_e32 v2, vcc, s4, v0
	s_mov_b32 s4, 0x434f000
	s_nop 0
	v_addc_co_u32_e32 v3, vcc, 0, v1, vcc
	global_load_dword v74, v[2:3], off nt
	v_add_co_u32_e32 v2, vcc, s4, v0
	s_mov_b32 s4, 0x4355000
	s_nop 0
	v_addc_co_u32_e32 v3, vcc, 0, v1, vcc
	global_load_dword v75, v[2:3], off offset:2048 nt
	v_add_co_u32_e32 v2, vcc, s4, v0
	s_mov_b32 s4, 0x435a000
	s_nop 0
	v_addc_co_u32_e32 v3, vcc, 0, v1, vcc
	v_add_co_u32_e32 v0, vcc, s4, v0
	global_load_dword v76, v[2:3], off nt
	s_nop 0
	v_addc_co_u32_e32 v1, vcc, 0, v1, vcc
	global_load_dword v77, v[0:1], off offset:2048 nt
	s_cmp_eq_u64 s[16:17], 0
	s_cbranch_scc1 .LBB0_1164
; __device__ __forceinline__ void transpose_item(const float* __restrict__ W, int K, int N, bf16* __restrict__ WT, const float* __restrict__ ksc, int mode, int row_off, int item, int lane) {
;     ...
;     if (ksc) {
; #pragma unroll
;         for (int i = 0; i < 64; ++i) v[i] *= ksc[k0 + i];
;     }
	s_lshl_b32 s4, s0, 2
	s_add_u32 s18, s16, s4
	s_addc_u32 s19, s17, 0
	s_add_u32 s16, s18, 0x3000
	s_addc_u32 s17, s19, 0
	global_load_dwordx4 v[0:3], v13, s[16:17] offset:48
	global_load_dwordx4 v[4:7], v13, s[16:17] offset:32
	global_load_dwordx4 v[8:11], v13, s[16:17] offset:16
	global_load_dwordx4 v[86:89], v83, s[18:19]
	global_load_dwordx4 v[160:163], v13, s[16:17] offset:112
	global_load_dwordx4 v[164:167], v13, s[16:17] offset:96
	global_load_dwordx4 v[168:171], v13, s[16:17] offset:80
	global_load_dwordx4 v[172:175], v13, s[16:17] offset:64
	global_load_dwordx4 v[176:179], v13, s[16:17] offset:176
	global_load_dwordx4 v[180:183], v13, s[16:17] offset:160
	global_load_dwordx4 v[184:187], v13, s[16:17] offset:144
	global_load_dwordx4 v[188:191], v13, s[16:17] offset:128
	global_load_dwordx4 v[208:211], v13, s[16:17] offset:224
	global_load_dwordx4 v[212:215], v13, s[16:17] offset:208
	global_load_dwordx4 v[216:219], v13, s[16:17] offset:192
	global_load_dwordx4 v[220:223], v13, s[16:17] offset:240
	s_waitcnt vmcnt(0)
	v_mov_b32_e32 v90, v86
	v_mov_b32_e32 v91, v88
	v_mov_b32_e32 v88, v87
	v_mov_b32_e32 v86, v8
	v_mov_b32_e32 v87, v10
	v_mov_b32_e32 v10, v9
	v_mov_b32_e32 v8, v4
	v_mov_b32_e32 v9, v6
	v_mov_b32_e32 v6, v5
	v_mov_b32_e32 v4, v0
	v_mov_b32_e32 v5, v2
	v_mov_b32_e32 v2, v1
	v_pk_mul_f32 v[14:15], v[14:15], v[88:89]
	v_pk_mul_f32 v[20:21], v[20:21], v[86:87]
	v_pk_mul_f32 v[18:19], v[18:19], v[10:11]
	v_pk_mul_f32 v[24:25], v[24:25], v[8:9]
	v_pk_mul_f32 v[22:23], v[22:23], v[6:7]
	v_pk_mul_f32 v[28:29], v[28:29], v[4:5]
	v_pk_mul_f32 v[26:27], v[26:27], v[2:3]
	v_mov_b32_e32 v0, v160
	v_mov_b32_e32 v1, v161
	v_mov_b32_e32 v2, v162
	v_mov_b32_e32 v3, v163
	v_mov_b32_e32 v4, v164
	v_mov_b32_e32 v5, v165
	v_mov_b32_e32 v6, v166
	v_mov_b32_e32 v7, v167
	v_mov_b32_e32 v8, v168
	v_mov_b32_e32 v9, v169
	v_mov_b32_e32 v10, v170
	v_mov_b32_e32 v11, v171
	v_mov_b32_e32 v86, v172
	v_mov_b32_e32 v87, v173
	v_mov_b32_e32 v88, v174
	v_mov_b32_e32 v89, v175
	v_pk_mul_f32 v[16:17], v[16:17], v[90:91]
	s_waitcnt vmcnt(0)
	v_mov_b32_e32 v90, v86
	v_mov_b32_e32 v91, v88
	v_mov_b32_e32 v88, v87
	v_mov_b32_e32 v86, v8
	v_mov_b32_e32 v87, v10
	v_mov_b32_e32 v10, v9
	v_mov_b32_e32 v8, v4
	v_mov_b32_e32 v9, v6
	v_mov_b32_e32 v6, v5
	v_mov_b32_e32 v4, v0
	v_mov_b32_e32 v5, v2
	v_mov_b32_e32 v2, v1
	v_pk_mul_f32 v[30:31], v[30:31], v[88:89]
	v_pk_mul_f32 v[36:37], v[36:37], v[86:87]
	v_pk_mul_f32 v[34:35], v[34:35], v[10:11]
	v_pk_mul_f32 v[40:41], v[40:41], v[8:9]
	v_pk_mul_f32 v[38:39], v[38:39], v[6:7]
	v_pk_mul_f32 v[44:45], v[44:45], v[4:5]
	v_pk_mul_f32 v[42:43], v[42:43], v[2:3]
	v_mov_b32_e32 v0, v176
	v_mov_b32_e32 v1, v177
	v_mov_b32_e32 v2, v178
	v_mov_b32_e32 v3, v179
	v_mov_b32_e32 v4, v180
	v_mov_b32_e32 v5, v181
	v_mov_b32_e32 v6, v182
	v_mov_b32_e32 v7, v183
	v_mov_b32_e32 v8, v184
	v_mov_b32_e32 v9, v185
	v_mov_b32_e32 v10, v186
	v_mov_b32_e32 v11, v187
	v_mov_b32_e32 v86, v188
	v_mov_b32_e32 v87, v189
	v_mov_b32_e32 v88, v190
	v_mov_b32_e32 v89, v191
	v_pk_mul_f32 v[32:33], v[32:33], v[90:91]
	s_waitcnt vmcnt(0)
	v_mov_b32_e32 v90, v86
	v_mov_b32_e32 v91, v88
	v_mov_b32_e32 v88, v87
	v_mov_b32_e32 v86, v8
	v_mov_b32_e32 v87, v10
	v_mov_b32_e32 v10, v9
	v_mov_b32_e32 v8, v4
	v_mov_b32_e32 v9, v6
	v_mov_b32_e32 v6, v5
	v_mov_b32_e32 v4, v0
	v_mov_b32_e32 v5, v2
	v_mov_b32_e32 v2, v1
	v_pk_mul_f32 v[46:47], v[46:47], v[88:89]
	v_pk_mul_f32 v[52:53], v[52:53], v[86:87]
	v_pk_mul_f32 v[50:51], v[50:51], v[10:11]
	v_pk_mul_f32 v[56:57], v[56:57], v[8:9]
	v_pk_mul_f32 v[54:55], v[54:55], v[6:7]
	v_pk_mul_f32 v[60:61], v[60:61], v[4:5]
	v_pk_mul_f32 v[58:59], v[58:59], v[2:3]
	v_mov_b32_e32 v0, v208
	v_mov_b32_e32 v1, v209
	v_mov_b32_e32 v2, v210
	v_mov_b32_e32 v3, v211
	v_mov_b32_e32 v4, v212
	v_mov_b32_e32 v5, v213
	v_mov_b32_e32 v6, v214
	v_mov_b32_e32 v7, v215
	v_mov_b32_e32 v86, v216
	v_mov_b32_e32 v87, v217
	v_mov_b32_e32 v88, v218
	v_mov_b32_e32 v89, v219
	v_mov_b32_e32 v8, v220
	v_mov_b32_e32 v9, v221
	v_mov_b32_e32 v10, v222
	v_mov_b32_e32 v11, v223
	v_pk_mul_f32 v[48:49], v[48:49], v[90:91]
	s_waitcnt vmcnt(1)
	v_mov_b32_e32 v90, v86
	v_mov_b32_e32 v91, v88
	v_mov_b32_e32 v88, v87
	v_mov_b32_e32 v86, v4
	v_mov_b32_e32 v87, v6
	v_mov_b32_e32 v6, v5
	v_mov_b32_e32 v4, v0
	v_mov_b32_e32 v5, v2
	v_mov_b32_e32 v2, v1
	v_pk_mul_f32 v[64:65], v[64:65], v[90:91]
	v_pk_mul_f32 v[62:63], v[62:63], v[88:89]
	v_pk_mul_f32 v[68:69], v[68:69], v[86:87]
	v_pk_mul_f32 v[66:67], v[66:67], v[6:7]
	v_pk_mul_f32 v[70:71], v[70:71], v[4:5]
	v_pk_mul_f32 v[72:73], v[72:73], v[2:3]
	s_waitcnt vmcnt(0)
	v_pk_mul_f32 v[74:75], v[74:75], v[8:9]
	v_pk_mul_f32 v[76:77], v[76:77], v[10:11]

; __device__ __forceinline__ void transpose_item(const float* __restrict__ W, int K, int N, bf16* __restrict__ WT, const float* __restrict__ ksc, int mode, int row_off, int item, int lane) {
;     const int nblk = N / 64, kb = item / nblk, nb = item % nblk, k0 = 64 * kb, n = 64 * nb + lane;
;     const float* src = W + (size_t)k0 * N + n;
;     float v[64];
; #pragma unroll
;     for (int i = 0; i < 64; ++i) v[i] = __builtin_nontemporal_load(src + (size_t)i * N);
; __device__ __forceinline__ void convert_layer(ArgsP a, int L, int first, int stride, int lane) {
;     ...
;         if (r < I_IN) transpose_item(a->in[3] + (size_t)L * D * INW, D, INW, WIN + (size_t)L * INW * D, a->in[2] + L * D, 1, 0, r, lane);
.LBB0_1173:
	s_andn2_b64 vcc, exec, s[16:17]
	s_cbranch_vccnz .LBB0_1156
	s_load_dwordx4 s[16:19], s[14:15], 0x10
	s_mul_hi_u32 s0, s3, 0xcccccccd
	s_lshr_b32 s0, s0, 5
	s_mul_i32 s4, s0, 0xa00
	s_lshl_b32 s46, s0, 6
	s_mul_i32 s0, s0, 0xa0000
	v_subrev_u32_e32 v12, s4, v82
	s_mul_hi_u32 s4, s46, 0x2800
	s_waitcnt lgkmcnt(0)
	s_add_u32 s18, s18, s0
	s_addc_u32 s19, s19, s4
	v_lshl_add_u64 v[66:67], v[12:13], 2, s[18:19]
	s_mov_b32 s0, 0x1e00000
	v_add_co_u32_e32 v0, vcc, s0, v66
	s_mov_b32 s0, 0x1e02000
	s_nop 0
	v_addc_co_u32_e32 v1, vcc, 0, v67, vcc
	v_add_co_u32_e32 v2, vcc, s0, v66
	s_mov_b32 s0, 0x1e05000
	s_nop 0
	v_addc_co_u32_e32 v3, vcc, 0, v67, vcc
	global_load_dword v0, v[0:1], off nt
	s_cmp_eq_u64 s[16:17], 0
	global_load_dword v1, v[2:3], off offset:2048 nt
	v_add_co_u32_e32 v2, vcc, s0, v66
	s_mov_b32 s0, 0x1e07000
	s_nop 0
	v_addc_co_u32_e32 v3, vcc, 0, v67, vcc
	v_add_co_u32_e32 v4, vcc, s0, v66
	s_mov_b32 s0, 0x1e0a000
	s_nop 0
	v_addc_co_u32_e32 v5, vcc, 0, v67, vcc
	global_load_dword v2, v[2:3], off nt
	s_nop 0
	global_load_dword v3, v[4:5], off offset:2048 nt
	v_add_co_u32_e32 v4, vcc, s0, v66
	s_mov_b32 s0, 0x1e0c000
	s_nop 0
	v_addc_co_u32_e32 v5, vcc, 0, v67, vcc
	v_add_co_u32_e32 v6, vcc, s0, v66
	s_mov_b32 s0, 0x1e0f000
	s_nop 0
	v_addc_co_u32_e32 v7, vcc, 0, v67, vcc
	global_load_dword v4, v[4:5], off nt
	s_nop 0
	global_load_dword v5, v[6:7], off offset:2048 nt
	v_add_co_u32_e32 v6, vcc, s0, v66
	s_mov_b32 s0, 0x1e11000
	s_nop 0
	v_addc_co_u32_e32 v7, vcc, 0, v67, vcc
	v_add_co_u32_e32 v8, vcc, s0, v66
	s_mov_b32 s0, 0x1e14000
	s_nop 0
	v_addc_co_u32_e32 v9, vcc, 0, v67, vcc
	global_load_dword v6, v[6:7], off nt
	s_nop 0
	global_load_dword v7, v[8:9], off offset:2048 nt
	v_add_co_u32_e32 v8, vcc, s0, v66
	s_mov_b32 s0, 0x1e16000
	s_nop 0
	v_addc_co_u32_e32 v9, vcc, 0, v67, vcc
	v_add_co_u32_e32 v10, vcc, s0, v66
	s_mov_b32 s0, 0x1e19000
	s_nop 0
	v_addc_co_u32_e32 v11, vcc, 0, v67, vcc
	global_load_dword v8, v[8:9], off nt
	s_nop 0
	global_load_dword v9, v[10:11], off offset:2048 nt
	v_add_co_u32_e32 v10, vcc, s0, v66
	s_mov_b32 s0, 0x1e1b000
	s_nop 0
	v_addc_co_u32_e32 v11, vcc, 0, v67, vcc
	v_add_co_u32_e32 v14, vcc, s0, v66
	s_mov_b32 s0, 0x1e1e000
	s_nop 0
	v_addc_co_u32_e32 v15, vcc, 0, v67, vcc
	global_load_dword v10, v[10:11], off nt
	s_nop 0
	global_load_dword v11, v[14:15], off offset:2048 nt
	v_add_co_u32_e32 v14, vcc, s0, v66
	s_mov_b32 s0, 0x1e20000
	s_nop 0
	v_addc_co_u32_e32 v15, vcc, 0, v67, vcc
	v_add_co_u32_e32 v16, vcc, s0, v66
	s_mov_b32 s0, 0x1e23000
	s_nop 0
	v_addc_co_u32_e32 v17, vcc, 0, v67, vcc
	global_load_dword v14, v[14:15], off nt
	s_nop 0
	global_load_dword v15, v[16:17], off offset:2048 nt
	v_add_co_u32_e32 v16, vcc, s0, v66
	s_mov_b32 s0, 0x1e25000
	s_nop 0
	v_addc_co_u32_e32 v17, vcc, 0, v67, vcc
	v_add_co_u32_e32 v18, vcc, s0, v66
	s_mov_b32 s0, 0x1e28000
	s_nop 0
	v_addc_co_u32_e32 v19, vcc, 0, v67, vcc
	global_load_dword v16, v[16:17], off nt
	s_nop 0
	global_load_dword v17, v[18:19], off offset:2048 nt
	v_add_co_u32_e32 v18, vcc, s0, v66
	s_mov_b32 s0, 0x1e2a000
	s_nop 0
	v_addc_co_u32_e32 v19, vcc, 0, v67, vcc
	v_add_co_u32_e32 v20, vcc, s0, v66
	s_mov_b32 s0, 0x1e2d000
	s_nop 0
	v_addc_co_u32_e32 v21, vcc, 0, v67, vcc
	global_load_dword v18, v[18:19], off nt
	s_nop 0
	global_load_dword v19, v[20:21], off offset:2048 nt
	v_add_co_u32_e32 v20, vcc, s0, v66
	s_mov_b32 s0, 0x1e2f000
	s_nop 0
	v_addc_co_u32_e32 v21, vcc, 0, v67, vcc
	v_add_co_u32_e32 v22, vcc, s0, v66
	s_mov_b32 s0, 0x1e32000
	s_nop 0
	v_addc_co_u32_e32 v23, vcc, 0, v67, vcc
	global_load_dword v20, v[20:21], off nt
	s_nop 0
	global_load_dword v21, v[22:23], off offset:2048 nt
	v_add_co_u32_e32 v22, vcc, s0, v66
	s_mov_b32 s0, 0x1e34000
	s_nop 0
	v_addc_co_u32_e32 v23, vcc, 0, v67, vcc
	v_add_co_u32_e32 v24, vcc, s0, v66
	s_mov_b32 s0, 0x1e37000
	s_nop 0
	v_addc_co_u32_e32 v25, vcc, 0, v67, vcc
	global_load_dword v22, v[22:23], off nt
	s_nop 0
	global_load_dword v23, v[24:25], off offset:2048 nt
	v_add_co_u32_e32 v24, vcc, s0, v66
	s_mov_b32 s0, 0x1e39000
	s_nop 0
	v_addc_co_u32_e32 v25, vcc, 0, v67, vcc
	v_add_co_u32_e32 v26, vcc, s0, v66
	s_mov_b32 s0, 0x1e3c000
	s_nop 0
	v_addc_co_u32_e32 v27, vcc, 0, v67, vcc
	global_load_dword v24, v[24:25], off nt
	s_nop 0
	global_load_dword v25, v[26:27], off offset:2048 nt
	v_add_co_u32_e32 v26, vcc, s0, v66
	s_mov_b32 s0, 0x1e3e000
	s_nop 0
	v_addc_co_u32_e32 v27, vcc, 0, v67, vcc
	v_add_co_u32_e32 v28, vcc, s0, v66
	s_mov_b32 s0, 0x1e41000
	s_nop 0
	v_addc_co_u32_e32 v29, vcc, 0, v67, vcc
	global_load_dword v26, v[26:27], off nt
	s_nop 0
	global_load_dword v27, v[28:29], off offset:2048 nt
	v_add_co_u32_e32 v28, vcc, s0, v66
	s_mov_b32 s0, 0x1e43000
	s_nop 0
	v_addc_co_u32_e32 v29, vcc, 0, v67, vcc
	v_add_co_u32_e32 v30, vcc, s0, v66
	s_mov_b32 s0, 0x1e46000
	s_nop 0
	v_addc_co_u32_e32 v31, vcc, 0, v67, vcc
	global_load_dword v28, v[28:29], off nt
	s_nop 0
	global_load_dword v29, v[30:31], off offset:2048 nt
	v_add_co_u32_e32 v30, vcc, s0, v66
	s_mov_b32 s0, 0x1e48000
	s_nop 0
	v_addc_co_u32_e32 v31, vcc, 0, v67, vcc
	v_add_co_u32_e32 v32, vcc, s0, v66
	s_mov_b32 s0, 0x1e4b000
	s_nop 0
	v_addc_co_u32_e32 v33, vcc, 0, v67, vcc
	global_load_dword v30, v[30:31], off nt
	s_nop 0
	global_load_dword v31, v[32:33], off offset:2048 nt
	v_add_co_u32_e32 v32, vcc, s0, v66
	s_mov_b32 s0, 0x1e4d000
	s_nop 0
	v_addc_co_u32_e32 v33, vcc, 0, v67, vcc
	v_add_co_u32_e32 v34, vcc, s0, v66
	s_mov_b32 s0, 0x1e50000
	s_nop 0
	v_addc_co_u32_e32 v35, vcc, 0, v67, vcc
	global_load_dword v32, v[32:33], off nt
	s_nop 0
	global_load_dword v33, v[34:35], off offset:2048 nt
	v_add_co_u32_e32 v34, vcc, s0, v66
; __device__ __forceinline__ void transpose_item(const float* __restrict__ W, int K, int N, bf16* __restrict__ WT, const float* __restrict__ ksc, int mode, int row_off, int item, int lane) {
;     ...
;     for (int i = 0; i < 64; ++i) v[i] = __builtin_nontemporal_load(src + (size_t)i * N);
	s_mov_b32 s0, 0x1e52000
	s_nop 0
	v_addc_co_u32_e32 v35, vcc, 0, v67, vcc
	v_add_co_u32_e32 v36, vcc, s0, v66
	s_mov_b32 s0, 0x1e55000
	s_nop 0
	v_addc_co_u32_e32 v37, vcc, 0, v67, vcc
	global_load_dword v34, v[34:35], off nt
	s_nop 0
	global_load_dword v35, v[36:37], off offset:2048 nt
	v_add_co_u32_e32 v36, vcc, s0, v66
	s_mov_b32 s0, 0x1e57000
	s_nop 0
	v_addc_co_u32_e32 v37, vcc, 0, v67, vcc
	v_add_co_u32_e32 v38, vcc, s0, v66
	s_mov_b32 s0, 0x1e5a000
	s_nop 0
	v_addc_co_u32_e32 v39, vcc, 0, v67, vcc
	global_load_dword v36, v[36:37], off nt
	s_nop 0
	global_load_dword v37, v[38:39], off offset:2048 nt
	v_add_co_u32_e32 v38, vcc, s0, v66
	s_mov_b32 s0, 0x1e5c000
	s_nop 0
	v_addc_co_u32_e32 v39, vcc, 0, v67, vcc
	v_add_co_u32_e32 v40, vcc, s0, v66
	s_mov_b32 s0, 0x1e5f000
	s_nop 0
	v_addc_co_u32_e32 v41, vcc, 0, v67, vcc
	global_load_dword v38, v[38:39], off nt
	s_nop 0
	global_load_dword v39, v[40:41], off offset:2048 nt
	v_add_co_u32_e32 v40, vcc, s0, v66
	s_mov_b32 s0, 0x1e61000
	s_nop 0
	v_addc_co_u32_e32 v41, vcc, 0, v67, vcc
	v_add_co_u32_e32 v42, vcc, s0, v66
	s_mov_b32 s0, 0x1e64000
	s_nop 0
	v_addc_co_u32_e32 v43, vcc, 0, v67, vcc
	global_load_dword v40, v[40:41], off nt
	s_nop 0
	global_load_dword v41, v[42:43], off offset:2048 nt
	v_add_co_u32_e32 v42, vcc, s0, v66
	s_mov_b32 s0, 0x1e66000
	s_nop 0
	v_addc_co_u32_e32 v43, vcc, 0, v67, vcc
	v_add_co_u32_e32 v44, vcc, s0, v66
	s_mov_b32 s0, 0x1e69000
	s_nop 0
	v_addc_co_u32_e32 v45, vcc, 0, v67, vcc
	global_load_dword v42, v[42:43], off nt
	s_nop 0
	global_load_dword v43, v[44:45], off offset:2048 nt
	v_add_co_u32_e32 v44, vcc, s0, v66
	s_mov_b32 s0, 0x1e6b000
	s_nop 0
	v_addc_co_u32_e32 v45, vcc, 0, v67, vcc
	v_add_co_u32_e32 v46, vcc, s0, v66
	s_mov_b32 s0, 0x1e6e000
	s_nop 0
	v_addc_co_u32_e32 v47, vcc, 0, v67, vcc
	global_load_dword v44, v[44:45], off nt
	s_nop 0
	global_load_dword v45, v[46:47], off offset:2048 nt
	v_add_co_u32_e32 v46, vcc, s0, v66
	s_mov_b32 s0, 0x1e70000
	s_nop 0
	v_addc_co_u32_e32 v47, vcc, 0, v67, vcc
	v_add_co_u32_e32 v48, vcc, s0, v66
	s_mov_b32 s0, 0x1e73000
	s_nop 0
	v_addc_co_u32_e32 v49, vcc, 0, v67, vcc
	global_load_dword v46, v[46:47], off nt
	s_nop 0
	global_load_dword v47, v[48:49], off offset:2048 nt
	v_add_co_u32_e32 v48, vcc, s0, v66
	s_mov_b32 s0, 0x1e75000
	s_nop 0
	v_addc_co_u32_e32 v49, vcc, 0, v67, vcc
	v_add_co_u32_e32 v50, vcc, s0, v66
	s_mov_b32 s0, 0x1e78000
	s_nop 0
	v_addc_co_u32_e32 v51, vcc, 0, v67, vcc
	global_load_dword v48, v[48:49], off nt
	s_nop 0
	global_load_dword v49, v[50:51], off offset:2048 nt
	v_add_co_u32_e32 v50, vcc, s0, v66
	s_mov_b32 s0, 0x1e7a000
	s_nop 0
	v_addc_co_u32_e32 v51, vcc, 0, v67, vcc
	v_add_co_u32_e32 v52, vcc, s0, v66
	s_mov_b32 s0, 0x1e7d000
	s_nop 0
	v_addc_co_u32_e32 v53, vcc, 0, v67, vcc
	global_load_dword v50, v[50:51], off nt
	s_nop 0
	global_load_dword v51, v[52:53], off offset:2048 nt
	v_add_co_u32_e32 v52, vcc, s0, v66
	s_mov_b32 s0, 0x1e7f000
	s_nop 0
	v_addc_co_u32_e32 v53, vcc, 0, v67, vcc
	v_add_co_u32_e32 v54, vcc, s0, v66
	s_mov_b32 s0, 0x1e82000
	s_nop 0
	v_addc_co_u32_e32 v55, vcc, 0, v67, vcc
	global_load_dword v52, v[52:53], off nt
	s_nop 0
	global_load_dword v53, v[54:55], off offset:2048 nt
	v_add_co_u32_e32 v54, vcc, s0, v66
	s_mov_b32 s0, 0x1e84000
	s_nop 0
	v_addc_co_u32_e32 v55, vcc, 0, v67, vcc
	v_add_co_u32_e32 v56, vcc, s0, v66
	s_mov_b32 s0, 0x1e87000
	s_nop 0
	v_addc_co_u32_e32 v57, vcc, 0, v67, vcc
	global_load_dword v54, v[54:55], off nt
	s_nop 0
	global_load_dword v55, v[56:57], off offset:2048 nt
	v_add_co_u32_e32 v56, vcc, s0, v66
	s_mov_b32 s0, 0x1e89000
	s_nop 0
	v_addc_co_u32_e32 v57, vcc, 0, v67, vcc
	v_add_co_u32_e32 v58, vcc, s0, v66
	s_mov_b32 s0, 0x1e8c000
	s_nop 0
	v_addc_co_u32_e32 v59, vcc, 0, v67, vcc
	global_load_dword v56, v[56:57], off nt
	s_nop 0
	global_load_dword v57, v[58:59], off offset:2048 nt
	v_add_co_u32_e32 v58, vcc, s0, v66
	s_mov_b32 s0, 0x1e8e000
	s_nop 0
	v_addc_co_u32_e32 v59, vcc, 0, v67, vcc
	v_add_co_u32_e32 v60, vcc, s0, v66
	s_mov_b32 s0, 0x1e91000
	s_nop 0
	v_addc_co_u32_e32 v61, vcc, 0, v67, vcc
	global_load_dword v58, v[58:59], off nt
	s_nop 0
	global_load_dword v59, v[60:61], off offset:2048 nt
	v_add_co_u32_e32 v60, vcc, s0, v66
	s_mov_b32 s0, 0x1e93000
	s_nop 0
	v_addc_co_u32_e32 v61, vcc, 0, v67, vcc
	v_add_co_u32_e32 v62, vcc, s0, v66
	s_mov_b32 s0, 0x1e96000
	s_nop 0
	v_addc_co_u32_e32 v63, vcc, 0, v67, vcc
	global_load_dword v60, v[60:61], off nt
	s_nop 0
	global_load_dword v61, v[62:63], off offset:2048 nt
	v_add_co_u32_e32 v62, vcc, s0, v66
	s_mov_b32 s0, 0x1e98000
	s_nop 0
	v_addc_co_u32_e32 v63, vcc, 0, v67, vcc
	v_add_co_u32_e32 v64, vcc, s0, v66
	global_load_dword v62, v[62:63], off nt
	s_nop 0
	v_addc_co_u32_e32 v65, vcc, 0, v67, vcc
	global_load_dword v63, v[64:65], off offset:2048 nt
	v_add_co_u32_e32 v64, vcc, s50, v66
	s_nop 1
	v_addc_co_u32_e32 v65, vcc, 0, v67, vcc
	v_add_co_u32_e32 v66, vcc, s51, v66
	global_load_dword v64, v[64:65], off nt
	s_nop 0
	v_addc_co_u32_e32 v67, vcc, 0, v67, vcc
	global_load_dword v65, v[66:67], off offset:2048 nt
	s_cbranch_scc1 .LBB0_1155
; __device__ __forceinline__ void transpose_item(const float* __restrict__ W, int K, int N, bf16* __restrict__ WT, const float* __restrict__ ksc, int mode, int row_off, int item, int lane) {
;     ...
;     if (ksc) {
; #pragma unroll
;         for (int i = 0; i < 64; ++i) v[i] *= ksc[k0 + i];
;     }
	s_lshl_b64 s[18:19], s[46:47], 2
	s_add_u32 s18, s16, s18
	s_addc_u32 s19, s17, s19
	s_add_u32 s16, s18, 0x3000
	s_addc_u32 s17, s19, 0
	global_load_dwordx4 v[66:69], v13, s[16:17] offset:48
	global_load_dwordx4 v[70:73], v13, s[16:17] offset:32
	global_load_dwordx4 v[74:77], v13, s[16:17] offset:16
	global_load_dwordx4 v[86:89], v83, s[18:19]
	global_load_dwordx4 v[160:163], v13, s[16:17] offset:112
	global_load_dwordx4 v[164:167], v13, s[16:17] offset:96
	global_load_dwordx4 v[168:171], v13, s[16:17] offset:80
	global_load_dwordx4 v[172:175], v13, s[16:17] offset:64
	global_load_dwordx4 v[176:179], v13, s[16:17] offset:176
	global_load_dwordx4 v[180:183], v13, s[16:17] offset:160
	global_load_dwordx4 v[184:187], v13, s[16:17] offset:144
	global_load_dwordx4 v[188:191], v13, s[16:17] offset:128
	global_load_dwordx4 v[208:211], v13, s[16:17] offset:240
	global_load_dwordx4 v[212:215], v13, s[16:17] offset:224
	global_load_dwordx4 v[216:219], v13, s[16:17] offset:208
	global_load_dwordx4 v[220:223], v13, s[16:17] offset:192
	s_waitcnt vmcnt(0)
	v_pk_mul_f32 v[14:15], v[14:15], v[66:67]
	s_waitcnt vmcnt(2)
	v_pk_mul_f32 v[8:9], v[8:9], v[70:71]
	s_waitcnt vmcnt(1)
	v_pk_mul_f32 v[4:5], v[4:5], v[74:75]
	s_waitcnt vmcnt(0)
	v_pk_mul_f32 v[0:1], v[0:1], v[86:87]
	v_pk_mul_f32 v[2:3], v[2:3], v[88:89]
	v_pk_mul_f32 v[6:7], v[6:7], v[76:77]
	v_pk_mul_f32 v[10:11], v[10:11], v[72:73]
	v_pk_mul_f32 v[16:17], v[16:17], v[68:69]
	v_mov_b32_e32 v66, v160
	v_mov_b32_e32 v67, v161
	v_mov_b32_e32 v68, v162
	v_mov_b32_e32 v69, v163
	v_mov_b32_e32 v70, v164
	v_mov_b32_e32 v71, v165
	v_mov_b32_e32 v72, v166
	v_mov_b32_e32 v73, v167
	v_mov_b32_e32 v74, v168
	v_mov_b32_e32 v75, v169
	v_mov_b32_e32 v76, v170
	v_mov_b32_e32 v77, v171
	v_mov_b32_e32 v86, v172
	v_mov_b32_e32 v87, v173
	v_mov_b32_e32 v88, v174
	v_mov_b32_e32 v89, v175
	s_waitcnt vmcnt(3)
	v_pk_mul_f32 v[30:31], v[30:31], v[66:67]
	s_waitcnt vmcnt(2)
	v_pk_mul_f32 v[26:27], v[26:27], v[70:71]
	s_waitcnt vmcnt(1)
	v_pk_mul_f32 v[22:23], v[22:23], v[74:75]
	s_waitcnt vmcnt(0)
	v_pk_mul_f32 v[18:19], v[18:19], v[86:87]
	v_pk_mul_f32 v[20:21], v[20:21], v[88:89]
	v_pk_mul_f32 v[24:25], v[24:25], v[76:77]
	v_pk_mul_f32 v[28:29], v[28:29], v[72:73]
	v_pk_mul_f32 v[32:33], v[32:33], v[68:69]
	v_mov_b32_e32 v66, v176
	v_mov_b32_e32 v67, v177
	v_mov_b32_e32 v68, v178
	v_mov_b32_e32 v69, v179
	v_mov_b32_e32 v70, v180
	v_mov_b32_e32 v71, v181
	v_mov_b32_e32 v72, v182
	v_mov_b32_e32 v73, v183
	v_mov_b32_e32 v74, v184
	v_mov_b32_e32 v75, v185
	v_mov_b32_e32 v76, v186
	v_mov_b32_e32 v77, v187
	v_mov_b32_e32 v86, v188
	v_mov_b32_e32 v87, v189
	v_mov_b32_e32 v88, v190
	v_mov_b32_e32 v89, v191
	s_waitcnt vmcnt(3)
	v_pk_mul_f32 v[46:47], v[46:47], v[66:67]
	s_waitcnt vmcnt(2)
	v_pk_mul_f32 v[42:43], v[42:43], v[70:71]
	s_waitcnt vmcnt(1)
	v_pk_mul_f32 v[38:39], v[38:39], v[74:75]
	s_waitcnt vmcnt(0)
	v_pk_mul_f32 v[34:35], v[34:35], v[86:87]
	v_pk_mul_f32 v[36:37], v[36:37], v[88:89]
	v_pk_mul_f32 v[40:41], v[40:41], v[76:77]
	v_pk_mul_f32 v[44:45], v[44:45], v[72:73]
	v_pk_mul_f32 v[48:49], v[48:49], v[68:69]
	v_mov_b32_e32 v66, v208
	v_mov_b32_e32 v67, v209
	v_mov_b32_e32 v68, v210
	v_mov_b32_e32 v69, v211
	v_mov_b32_e32 v70, v212
	v_mov_b32_e32 v71, v213
	v_mov_b32_e32 v72, v214
	v_mov_b32_e32 v73, v215
	v_mov_b32_e32 v74, v216
	v_mov_b32_e32 v75, v217
	v_mov_b32_e32 v76, v218
	v_mov_b32_e32 v77, v219
	v_mov_b32_e32 v86, v220
	v_mov_b32_e32 v87, v221
	v_mov_b32_e32 v88, v222
	v_mov_b32_e32 v89, v223
	s_waitcnt vmcnt(3)
	v_pk_mul_f32 v[62:63], v[62:63], v[66:67]
	s_waitcnt vmcnt(2)
	v_pk_mul_f32 v[58:59], v[58:59], v[70:71]
	s_waitcnt vmcnt(1)
	v_pk_mul_f32 v[54:55], v[54:55], v[74:75]
	s_waitcnt vmcnt(0)
	v_pk_mul_f32 v[50:51], v[50:51], v[86:87]
	v_pk_mul_f32 v[52:53], v[52:53], v[88:89]
	v_pk_mul_f32 v[56:57], v[56:57], v[76:77]
	v_pk_mul_f32 v[60:61], v[60:61], v[72:73]
	v_pk_mul_f32 v[64:65], v[64:65], v[68:69]
	s_branch .LBB0_1155

; __device__ __forceinline__ void transpose_item(const float* __restrict__ W, int K, int N, bf16* __restrict__ WT, const float* __restrict__ ksc, int mode, int row_off, int item, int lane) {
;     const int nblk = N / 64, kb = item / nblk, nb = item % nblk, k0 = 64 * kb, n = 64 * nb + lane;
;     const float* src = W + (size_t)k0 * N + n;
;     float v[64];
; #pragma unroll
;     for (int i = 0; i < 64; ++i) v[i] = __builtin_nontemporal_load(src + (size_t)i * N);
; __device__ __forceinline__ void convert_layer(ArgsP a, int L, int first, int stride, int lane) {
;     ...
;         else if (r < I_IN + I_OUT + I_GU) transpose_item(a->in[18] + (size_t)L * D * GU, D, GU, WGU + (size_t)L * GU * D, a->in[17] + L * D, 2, 0, r - I_IN - I_OUT, lane);
.Lcx5_1161:
	s_andn2_b64 vcc, exec, s[16:17]
	s_cbranch_vccnz .Lcx5_1169
	s_add_i32 s0, s3, 0xfc80
	s_and_b32 s4, s0, 0xffff
	s_mul_i32 s4, s4, 0xba2f
	s_load_dwordx4 s[16:19], s[14:15], 0x88
	s_lshr_b32 s5, s4, 16
	s_lshr_b32 s4, s4, 22
	s_mulk_i32 s4, 0x58
	s_sub_i32 s0, s0, s4
	s_and_b32 s46, s0, 0xffff
	s_and_b32 s0, s5, 0xffc0
	s_lshl_b32 s33, s46, 6
	s_mul_i32 s4, s0, 0x5800
	v_or_b32_e32 v78, s33, v80
	s_waitcnt lgkmcnt(0)
	s_add_u32 s18, s18, s4
	s_addc_u32 s19, s19, 0
	v_lshlrev_b32_e32 v12, 2, v78
	v_lshl_add_u64 v[0:1], s[18:19], 0, v[12:13]
	s_mov_b32 s4, 0x4200000
	v_add_co_u32_e32 v2, vcc, s4, v0
	s_mov_b32 s4, 0x4205000
	s_nop 0
	v_addc_co_u32_e32 v3, vcc, 0, v1, vcc
	global_load_dword v16, v[2:3], off nt
	v_add_co_u32_e32 v2, vcc, s4, v0
	s_mov_b32 s4, 0x420b000
	s_nop 0
	v_addc_co_u32_e32 v3, vcc, 0, v1, vcc
	global_load_dword v14, v[2:3], off offset:2048 nt
	v_add_co_u32_e32 v2, vcc, s4, v0
	s_mov_b32 s4, 0x4210000
	s_nop 0
	v_addc_co_u32_e32 v3, vcc, 0, v1, vcc
	global_load_dword v17, v[2:3], off nt
	v_add_co_u32_e32 v2, vcc, s4, v0
	s_mov_b32 s4, 0x4216000
	s_nop 0
	v_addc_co_u32_e32 v3, vcc, 0, v1, vcc
	global_load_dword v15, v[2:3], off offset:2048 nt
	v_add_co_u32_e32 v2, vcc, s4, v0
	s_mov_b32 s4, 0x421b000
	s_nop 0
	v_addc_co_u32_e32 v3, vcc, 0, v1, vcc
	global_load_dword v20, v[2:3], off nt
	v_add_co_u32_e32 v2, vcc, s4, v0
	s_mov_b32 s4, 0x4221000
	s_nop 0
	v_addc_co_u32_e32 v3, vcc, 0, v1, vcc
	global_load_dword v18, v[2:3], off offset:2048 nt
	v_add_co_u32_e32 v2, vcc, s4, v0
	s_mov_b32 s4, 0x4226000
	s_nop 0
	v_addc_co_u32_e32 v3, vcc, 0, v1, vcc
	global_load_dword v21, v[2:3], off nt
	v_add_co_u32_e32 v2, vcc, s4, v0
	s_mov_b32 s4, 0x422c000
	s_nop 0
	v_addc_co_u32_e32 v3, vcc, 0, v1, vcc
	global_load_dword v19, v[2:3], off offset:2048 nt
	v_add_co_u32_e32 v2, vcc, s4, v0
	s_mov_b32 s4, 0x4231000
	s_nop 0
	v_addc_co_u32_e32 v3, vcc, 0, v1, vcc
	global_load_dword v24, v[2:3], off nt
	v_add_co_u32_e32 v2, vcc, s4, v0
	s_mov_b32 s4, 0x4237000
	s_nop 0
	v_addc_co_u32_e32 v3, vcc, 0, v1, vcc
	global_load_dword v22, v[2:3], off offset:2048 nt
	v_add_co_u32_e32 v2, vcc, s4, v0
	s_mov_b32 s4, 0x423c000
	s_nop 0
	v_addc_co_u32_e32 v3, vcc, 0, v1, vcc
	global_load_dword v25, v[2:3], off nt
	v_add_co_u32_e32 v2, vcc, s4, v0
	s_mov_b32 s4, 0x4242000
	s_nop 0
	v_addc_co_u32_e32 v3, vcc, 0, v1, vcc
	global_load_dword v23, v[2:3], off offset:2048 nt
	v_add_co_u32_e32 v2, vcc, s4, v0
	s_mov_b32 s4, 0x4247000
	s_nop 0
	v_addc_co_u32_e32 v3, vcc, 0, v1, vcc
	global_load_dword v28, v[2:3], off nt
	v_add_co_u32_e32 v2, vcc, s4, v0
	s_mov_b32 s4, 0x424d000
	s_nop 0
	v_addc_co_u32_e32 v3, vcc, 0, v1, vcc
	global_load_dword v26, v[2:3], off offset:2048 nt
	v_add_co_u32_e32 v2, vcc, s4, v0
	s_mov_b32 s4, 0x4252000
	s_nop 0
	v_addc_co_u32_e32 v3, vcc, 0, v1, vcc
	global_load_dword v29, v[2:3], off nt
	v_add_co_u32_e32 v2, vcc, s4, v0
	s_mov_b32 s4, 0x4258000
	s_nop 0
	v_addc_co_u32_e32 v3, vcc, 0, v1, vcc
	global_load_dword v27, v[2:3], off offset:2048 nt
	v_add_co_u32_e32 v2, vcc, s4, v0
	s_mov_b32 s4, 0x425d000
	s_nop 0
	v_addc_co_u32_e32 v3, vcc, 0, v1, vcc
	global_load_dword v32, v[2:3], off nt
	v_add_co_u32_e32 v2, vcc, s4, v0
	s_mov_b32 s4, 0x4263000
	s_nop 0
	v_addc_co_u32_e32 v3, vcc, 0, v1, vcc
	global_load_dword v30, v[2:3], off offset:2048 nt
	v_add_co_u32_e32 v2, vcc, s4, v0
	s_mov_b32 s4, 0x4268000
	s_nop 0
	v_addc_co_u32_e32 v3, vcc, 0, v1, vcc
	global_load_dword v33, v[2:3], off nt
	v_add_co_u32_e32 v2, vcc, s4, v0
	s_mov_b32 s4, 0x426e000
	s_nop 0
	v_addc_co_u32_e32 v3, vcc, 0, v1, vcc
	global_load_dword v31, v[2:3], off offset:2048 nt
	v_add_co_u32_e32 v2, vcc, s4, v0
	s_mov_b32 s4, 0x4273000
	s_nop 0
	v_addc_co_u32_e32 v3, vcc, 0, v1, vcc
	global_load_dword v36, v[2:3], off nt
	v_add_co_u32_e32 v2, vcc, s4, v0
	s_mov_b32 s4, 0x4279000
	s_nop 0
	v_addc_co_u32_e32 v3, vcc, 0, v1, vcc
	global_load_dword v34, v[2:3], off offset:2048 nt
	v_add_co_u32_e32 v2, vcc, s4, v0
	s_mov_b32 s4, 0x427e000
	s_nop 0
	v_addc_co_u32_e32 v3, vcc, 0, v1, vcc
	global_load_dword v37, v[2:3], off nt
	v_add_co_u32_e32 v2, vcc, s4, v0
	s_mov_b32 s4, 0x4284000
	s_nop 0
	v_addc_co_u32_e32 v3, vcc, 0, v1, vcc
	global_load_dword v35, v[2:3], off offset:2048 nt
	v_add_co_u32_e32 v2, vcc, s4, v0
	s_mov_b32 s4, 0x4289000
	s_nop 0
	v_addc_co_u32_e32 v3, vcc, 0, v1, vcc
	global_load_dword v40, v[2:3], off nt
	v_add_co_u32_e32 v2, vcc, s4, v0
	s_mov_b32 s4, 0x428f000
	s_nop 0
	v_addc_co_u32_e32 v3, vcc, 0, v1, vcc
	global_load_dword v38, v[2:3], off offset:2048 nt
	v_add_co_u32_e32 v2, vcc, s4, v0
	s_mov_b32 s4, 0x4294000
	s_nop 0
	v_addc_co_u32_e32 v3, vcc, 0, v1, vcc
	global_load_dword v41, v[2:3], off nt
	v_add_co_u32_e32 v2, vcc, s4, v0
	s_mov_b32 s4, 0x429a000
	s_nop 0
	v_addc_co_u32_e32 v3, vcc, 0, v1, vcc
	global_load_dword v39, v[2:3], off offset:2048 nt
	v_add_co_u32_e32 v2, vcc, s4, v0
	s_mov_b32 s4, 0x429f000
	s_nop 0
	v_addc_co_u32_e32 v3, vcc, 0, v1, vcc
	global_load_dword v44, v[2:3], off nt
	v_add_co_u32_e32 v2, vcc, s4, v0
	s_mov_b32 s4, 0x42a5000
	s_nop 0
	v_addc_co_u32_e32 v3, vcc, 0, v1, vcc
	global_load_dword v42, v[2:3], off offset:2048 nt
	v_add_co_u32_e32 v2, vcc, s4, v0
	s_mov_b32 s4, 0x42aa000
	s_nop 0
	v_addc_co_u32_e32 v3, vcc, 0, v1, vcc
	global_load_dword v45, v[2:3], off nt
	v_add_co_u32_e32 v2, vcc, s4, v0
	s_mov_b32 s4, 0x42b0000
	s_nop 0
	v_addc_co_u32_e32 v3, vcc, 0, v1, vcc
	global_load_dword v43, v[2:3], off offset:2048 nt
	v_add_co_u32_e32 v2, vcc, s4, v0
	s_mov_b32 s4, 0x42b5000
	s_nop 0
	v_addc_co_u32_e32 v3, vcc, 0, v1, vcc
	global_load_dword v48, v[2:3], off nt
	v_add_co_u32_e32 v2, vcc, s4, v0
; __device__ __forceinline__ void transpose_item(const float* __restrict__ W, int K, int N, bf16* __restrict__ WT, const float* __restrict__ ksc, int mode, int row_off, int item, int lane) {
;     ...
;     for (int i = 0; i < 64; ++i) v[i] = __builtin_nontemporal_load(src + (size_t)i * N);
	s_mov_b32 s4, 0x42bb000
	s_nop 0
	v_addc_co_u32_e32 v3, vcc, 0, v1, vcc
	global_load_dword v46, v[2:3], off offset:2048 nt
	v_add_co_u32_e32 v2, vcc, s4, v0
	s_mov_b32 s4, 0x42c0000
	s_nop 0
	v_addc_co_u32_e32 v3, vcc, 0, v1, vcc
	global_load_dword v49, v[2:3], off nt
	v_add_co_u32_e32 v2, vcc, s4, v0
	s_mov_b32 s4, 0x42c6000
	s_nop 0
	v_addc_co_u32_e32 v3, vcc, 0, v1, vcc
	global_load_dword v47, v[2:3], off offset:2048 nt
	v_add_co_u32_e32 v2, vcc, s4, v0
	s_mov_b32 s4, 0x42cb000
	s_nop 0
	v_addc_co_u32_e32 v3, vcc, 0, v1, vcc
	global_load_dword v52, v[2:3], off nt
	v_add_co_u32_e32 v2, vcc, s4, v0
	s_mov_b32 s4, 0x42d1000
	s_nop 0
	v_addc_co_u32_e32 v3, vcc, 0, v1, vcc
	global_load_dword v50, v[2:3], off offset:2048 nt
	v_add_co_u32_e32 v2, vcc, s4, v0
	s_mov_b32 s4, 0x42d6000
	s_nop 0
	v_addc_co_u32_e32 v3, vcc, 0, v1, vcc
	global_load_dword v53, v[2:3], off nt
	v_add_co_u32_e32 v2, vcc, s4, v0
	s_mov_b32 s4, 0x42dc000
	s_nop 0
	v_addc_co_u32_e32 v3, vcc, 0, v1, vcc
	global_load_dword v51, v[2:3], off offset:2048 nt
	v_add_co_u32_e32 v2, vcc, s4, v0
	s_mov_b32 s4, 0x42e1000
	s_nop 0
	v_addc_co_u32_e32 v3, vcc, 0, v1, vcc
	global_load_dword v56, v[2:3], off nt
	v_add_co_u32_e32 v2, vcc, s4, v0
	s_mov_b32 s4, 0x42e7000
	s_nop 0
	v_addc_co_u32_e32 v3, vcc, 0, v1, vcc
	global_load_dword v54, v[2:3], off offset:2048 nt
	v_add_co_u32_e32 v2, vcc, s4, v0
	s_mov_b32 s4, 0x42ec000
	s_nop 0
	v_addc_co_u32_e32 v3, vcc, 0, v1, vcc
	global_load_dword v57, v[2:3], off nt
	v_add_co_u32_e32 v2, vcc, s4, v0
	s_mov_b32 s4, 0x42f2000
	s_nop 0
	v_addc_co_u32_e32 v3, vcc, 0, v1, vcc
	global_load_dword v55, v[2:3], off offset:2048 nt
	v_add_co_u32_e32 v2, vcc, s4, v0
	s_mov_b32 s4, 0x42f7000
	s_nop 0
	v_addc_co_u32_e32 v3, vcc, 0, v1, vcc
	global_load_dword v60, v[2:3], off nt
	v_add_co_u32_e32 v2, vcc, s4, v0
	s_mov_b32 s4, 0x42fd000
	s_nop 0
	v_addc_co_u32_e32 v3, vcc, 0, v1, vcc
	global_load_dword v58, v[2:3], off offset:2048 nt
	v_add_co_u32_e32 v2, vcc, s4, v0
	s_mov_b32 s4, 0x4302000
	s_nop 0
	v_addc_co_u32_e32 v3, vcc, 0, v1, vcc
	global_load_dword v61, v[2:3], off nt
	v_add_co_u32_e32 v2, vcc, s4, v0
	s_mov_b32 s4, 0x4308000
	s_nop 0
	v_addc_co_u32_e32 v3, vcc, 0, v1, vcc
	global_load_dword v59, v[2:3], off offset:2048 nt
	v_add_co_u32_e32 v2, vcc, s4, v0
	s_mov_b32 s4, 0x430d000
	s_nop 0
	v_addc_co_u32_e32 v3, vcc, 0, v1, vcc
	global_load_dword v64, v[2:3], off nt
	v_add_co_u32_e32 v2, vcc, s4, v0
	s_mov_b32 s4, 0x4313000
	s_nop 0
	v_addc_co_u32_e32 v3, vcc, 0, v1, vcc
	global_load_dword v62, v[2:3], off offset:2048 nt
	v_add_co_u32_e32 v2, vcc, s4, v0
	s_mov_b32 s4, 0x4318000
	s_nop 0
	v_addc_co_u32_e32 v3, vcc, 0, v1, vcc
	global_load_dword v65, v[2:3], off nt
	v_add_co_u32_e32 v2, vcc, s4, v0
	s_mov_b32 s4, 0x431e000
	s_nop 0
	v_addc_co_u32_e32 v3, vcc, 0, v1, vcc
	global_load_dword v63, v[2:3], off offset:2048 nt
	v_add_co_u32_e32 v2, vcc, s4, v0
	s_mov_b32 s4, 0x4323000
	s_nop 0
	v_addc_co_u32_e32 v3, vcc, 0, v1, vcc
	global_load_dword v68, v[2:3], off nt
	v_add_co_u32_e32 v2, vcc, s4, v0
	s_mov_b32 s4, 0x4329000
	s_nop 0
	v_addc_co_u32_e32 v3, vcc, 0, v1, vcc
	global_load_dword v66, v[2:3], off offset:2048 nt
	v_add_co_u32_e32 v2, vcc, s4, v0
	s_mov_b32 s4, 0x432e000
	s_nop 0
	v_addc_co_u32_e32 v3, vcc, 0, v1, vcc
	global_load_dword v69, v[2:3], off nt
	v_add_co_u32_e32 v2, vcc, s4, v0
	s_mov_b32 s4, 0x4334000
	s_nop 0
	v_addc_co_u32_e32 v3, vcc, 0, v1, vcc
	global_load_dword v67, v[2:3], off offset:2048 nt
	v_add_co_u32_e32 v2, vcc, s4, v0
	s_mov_b32 s4, 0x4339000
	s_nop 0
	v_addc_co_u32_e32 v3, vcc, 0, v1, vcc
	global_load_dword v70, v[2:3], off nt
	v_add_co_u32_e32 v2, vcc, s4, v0
	s_mov_b32 s4, 0x433f000
	s_nop 0
	v_addc_co_u32_e32 v3, vcc, 0, v1, vcc
	global_load_dword v72, v[2:3], off offset:2048 nt
	v_add_co_u32_e32 v2, vcc, s4, v0
	s_mov_b32 s4, 0x4344000
	s_nop 0
	v_addc_co_u32_e32 v3, vcc, 0, v1, vcc
	global_load_dword v71, v[2:3], off nt
	v_add_co_u32_e32 v2, vcc, s4, v0
	s_mov_b32 s4, 0x434a000
	s_nop 0
	v_addc_co_u32_e32 v3, vcc, 0, v1, vcc
	global_load_dword v73, v[2:3], off offset:2048 nt
	v_add_co_u32_e32 v2, vcc, s4, v0
	s_mov_b32 s4, 0x434f000
	s_nop 0
	v_addc_co_u32_e32 v3, vcc, 0, v1, vcc
	global_load_dword v74, v[2:3], off nt
	v_add_co_u32_e32 v2, vcc, s4, v0
	s_mov_b32 s4, 0x4355000
	s_nop 0
	v_addc_co_u32_e32 v3, vcc, 0, v1, vcc
	global_load_dword v75, v[2:3], off offset:2048 nt
	v_add_co_u32_e32 v2, vcc, s4, v0
	s_mov_b32 s4, 0x435a000
	s_nop 0
	v_addc_co_u32_e32 v3, vcc, 0, v1, vcc
	v_add_co_u32_e32 v0, vcc, s4, v0
	global_load_dword v76, v[2:3], off nt
	s_nop 0
	v_addc_co_u32_e32 v1, vcc, 0, v1, vcc
	global_load_dword v77, v[0:1], off offset:2048 nt
	s_cmp_eq_u64 s[16:17], 0
	s_cbranch_scc1 .Lcx5_1164
; __device__ __forceinline__ void transpose_item(const float* __restrict__ W, int K, int N, bf16* __restrict__ WT, const float* __restrict__ ksc, int mode, int row_off, int item, int lane) {
;     ...
;     if (ksc) {
; #pragma unroll
;         for (int i = 0; i < 64; ++i) v[i] *= ksc[k0 + i];
;     }
	s_lshl_b32 s4, s0, 2
	s_add_u32 s18, s16, s4
	s_addc_u32 s19, s17, 0
	s_add_u32 s16, s18, 0x3000
	s_addc_u32 s17, s19, 0
	global_load_dwordx4 v[0:3], v13, s[16:17] offset:48
	global_load_dwordx4 v[4:7], v13, s[16:17] offset:32
	global_load_dwordx4 v[8:11], v13, s[16:17] offset:16
	global_load_dwordx4 v[86:89], v83, s[18:19]
	global_load_dwordx4 v[184:187], v13, s[16:17] offset:112
	global_load_dwordx4 v[188:191], v13, s[16:17] offset:96
	global_load_dwordx4 v[192:195], v13, s[16:17] offset:80
	global_load_dwordx4 v[196:199], v13, s[16:17] offset:64
	global_load_dwordx4 v[204:207], v13, s[16:17] offset:176
	global_load_dwordx4 v[208:211], v13, s[16:17] offset:160
	global_load_dwordx4 v[212:215], v13, s[16:17] offset:144
	global_load_dwordx4 v[216:219], v13, s[16:17] offset:128
	global_load_dwordx4 v[220:223], v13, s[16:17] offset:224
	global_load_dwordx4 v[224:227], v13, s[16:17] offset:208
	global_load_dwordx4 v[228:231], v13, s[16:17] offset:192
	global_load_dwordx4 v[232:235], v13, s[16:17] offset:240
	s_waitcnt vmcnt(0)
	v_mov_b32_e32 v90, v86
	v_mov_b32_e32 v91, v88
	v_mov_b32_e32 v88, v87
	v_mov_b32_e32 v86, v8
	v_mov_b32_e32 v87, v10
	v_mov_b32_e32 v10, v9
	v_mov_b32_e32 v8, v4
	v_mov_b32_e32 v9, v6
	v_mov_b32_e32 v6, v5
	v_mov_b32_e32 v4, v0
	v_mov_b32_e32 v5, v2
	v_mov_b32_e32 v2, v1
	v_pk_mul_f32 v[14:15], v[14:15], v[88:89]
	v_pk_mul_f32 v[20:21], v[20:21], v[86:87]
	v_pk_mul_f32 v[18:19], v[18:19], v[10:11]
	v_pk_mul_f32 v[24:25], v[24:25], v[8:9]
	v_pk_mul_f32 v[22:23], v[22:23], v[6:7]
	v_pk_mul_f32 v[28:29], v[28:29], v[4:5]
	v_pk_mul_f32 v[26:27], v[26:27], v[2:3]
	v_mov_b32_e32 v0, v184
	v_mov_b32_e32 v1, v185
	v_mov_b32_e32 v2, v186
	v_mov_b32_e32 v3, v187
	v_mov_b32_e32 v4, v188
	v_mov_b32_e32 v5, v189
	v_mov_b32_e32 v6, v190
	v_mov_b32_e32 v7, v191
	v_mov_b32_e32 v8, v192
	v_mov_b32_e32 v9, v193
	v_mov_b32_e32 v10, v194
	v_mov_b32_e32 v11, v195
	v_mov_b32_e32 v86, v196
	v_mov_b32_e32 v87, v197
	v_mov_b32_e32 v88, v198
	v_mov_b32_e32 v89, v199
	v_pk_mul_f32 v[16:17], v[16:17], v[90:91]
	s_waitcnt vmcnt(0)
	v_mov_b32_e32 v90, v86
	v_mov_b32_e32 v91, v88
	v_mov_b32_e32 v88, v87
	v_mov_b32_e32 v86, v8
	v_mov_b32_e32 v87, v10
	v_mov_b32_e32 v10, v9
	v_mov_b32_e32 v8, v4
	v_mov_b32_e32 v9, v6
	v_mov_b32_e32 v6, v5
	v_mov_b32_e32 v4, v0
	v_mov_b32_e32 v5, v2
	v_mov_b32_e32 v2, v1
	v_pk_mul_f32 v[30:31], v[30:31], v[88:89]
	v_pk_mul_f32 v[36:37], v[36:37], v[86:87]
	v_pk_mul_f32 v[34:35], v[34:35], v[10:11]
	v_pk_mul_f32 v[40:41], v[40:41], v[8:9]
	v_pk_mul_f32 v[38:39], v[38:39], v[6:7]
	v_pk_mul_f32 v[44:45], v[44:45], v[4:5]
	v_pk_mul_f32 v[42:43], v[42:43], v[2:3]
	v_mov_b32_e32 v0, v204
	v_mov_b32_e32 v1, v205
	v_mov_b32_e32 v2, v206
	v_mov_b32_e32 v3, v207
	v_mov_b32_e32 v4, v208
	v_mov_b32_e32 v5, v209
	v_mov_b32_e32 v6, v210
	v_mov_b32_e32 v7, v211
	v_mov_b32_e32 v8, v212
	v_mov_b32_e32 v9, v213
	v_mov_b32_e32 v10, v214
	v_mov_b32_e32 v11, v215
	v_mov_b32_e32 v86, v216
	v_mov_b32_e32 v87, v217
	v_mov_b32_e32 v88, v218
	v_mov_b32_e32 v89, v219
	v_pk_mul_f32 v[32:33], v[32:33], v[90:91]
	s_waitcnt vmcnt(0)
	v_mov_b32_e32 v90, v86
	v_mov_b32_e32 v91, v88
	v_mov_b32_e32 v88, v87
	v_mov_b32_e32 v86, v8
	v_mov_b32_e32 v87, v10
	v_mov_b32_e32 v10, v9
	v_mov_b32_e32 v8, v4
	v_mov_b32_e32 v9, v6
	v_mov_b32_e32 v6, v5
	v_mov_b32_e32 v4, v0
	v_mov_b32_e32 v5, v2
	v_mov_b32_e32 v2, v1
	v_pk_mul_f32 v[46:47], v[46:47], v[88:89]
	v_pk_mul_f32 v[52:53], v[52:53], v[86:87]
	v_pk_mul_f32 v[50:51], v[50:51], v[10:11]
	v_pk_mul_f32 v[56:57], v[56:57], v[8:9]
	v_pk_mul_f32 v[54:55], v[54:55], v[6:7]
	v_pk_mul_f32 v[60:61], v[60:61], v[4:5]
	v_pk_mul_f32 v[58:59], v[58:59], v[2:3]
	v_mov_b32_e32 v0, v220
	v_mov_b32_e32 v1, v221
	v_mov_b32_e32 v2, v222
	v_mov_b32_e32 v3, v223
	v_mov_b32_e32 v4, v224
	v_mov_b32_e32 v5, v225
	v_mov_b32_e32 v6, v226
	v_mov_b32_e32 v7, v227
	v_mov_b32_e32 v86, v228
	v_mov_b32_e32 v87, v229
	v_mov_b32_e32 v88, v230
	v_mov_b32_e32 v89, v231
	v_mov_b32_e32 v8, v232
	v_mov_b32_e32 v9, v233
	v_mov_b32_e32 v10, v234
	v_mov_b32_e32 v11, v235
	v_pk_mul_f32 v[48:49], v[48:49], v[90:91]
	s_waitcnt vmcnt(1)
	v_mov_b32_e32 v90, v86
	v_mov_b32_e32 v91, v88
	v_mov_b32_e32 v88, v87
	v_mov_b32_e32 v86, v4
	v_mov_b32_e32 v87, v6
	v_mov_b32_e32 v6, v5
	v_mov_b32_e32 v4, v0
	v_mov_b32_e32 v5, v2
	v_mov_b32_e32 v2, v1
	v_pk_mul_f32 v[64:65], v[64:65], v[90:91]
	v_pk_mul_f32 v[62:63], v[62:63], v[88:89]
	v_pk_mul_f32 v[68:69], v[68:69], v[86:87]
	v_pk_mul_f32 v[66:67], v[66:67], v[6:7]
	v_pk_mul_f32 v[70:71], v[70:71], v[4:5]
	v_pk_mul_f32 v[72:73], v[72:73], v[2:3]
	s_waitcnt vmcnt(0)
	v_pk_mul_f32 v[74:75], v[74:75], v[8:9]
	v_pk_mul_f32 v[76:77], v[76:77], v[10:11]

; __device__ __forceinline__ void transpose_item(const float* __restrict__ W, int K, int N, bf16* __restrict__ WT, const float* __restrict__ ksc, int mode, int row_off, int item, int lane) {
;     const int nblk = N / 64, kb = item / nblk, nb = item % nblk, k0 = 64 * kb, n = 64 * nb + lane;
;     const float* src = W + (size_t)k0 * N + n;
;     float v[64];
; #pragma unroll
;     for (int i = 0; i < 64; ++i) v[i] = __builtin_nontemporal_load(src + (size_t)i * N);
; __device__ __forceinline__ void convert_layer(ArgsP a, int L, int first, int stride, int lane) {
;     ...
;         if (r < I_IN) transpose_item(a->in[3] + (size_t)L * D * INW, D, INW, WIN + (size_t)L * INW * D, a->in[2] + L * D, 1, 0, r, lane);
.Lcx5_1173:
	s_andn2_b64 vcc, exec, s[16:17]
	s_cbranch_vccnz .Lcx5_1156
	s_load_dwordx4 s[16:19], s[14:15], 0x10
	s_mul_hi_u32 s0, s3, 0xcccccccd
	s_lshr_b32 s0, s0, 5
	s_mul_i32 s4, s0, 0xa00
	s_lshl_b32 s46, s0, 6
	s_mul_i32 s0, s0, 0xa0000
	v_subrev_u32_e32 v12, s4, v82
	s_mul_hi_u32 s4, s46, 0x2800
	s_waitcnt lgkmcnt(0)
	s_add_u32 s18, s18, s0
	s_addc_u32 s19, s19, s4
	v_lshl_add_u64 v[66:67], v[12:13], 2, s[18:19]
	s_mov_b32 s0, 0x1e00000
	v_add_co_u32_e32 v0, vcc, s0, v66
	s_mov_b32 s0, 0x1e02000
	s_nop 0
	v_addc_co_u32_e32 v1, vcc, 0, v67, vcc
	v_add_co_u32_e32 v2, vcc, s0, v66
	s_mov_b32 s0, 0x1e05000
	s_nop 0
	v_addc_co_u32_e32 v3, vcc, 0, v67, vcc
	global_load_dword v0, v[0:1], off nt
	s_cmp_eq_u64 s[16:17], 0
	global_load_dword v1, v[2:3], off offset:2048 nt
	v_add_co_u32_e32 v2, vcc, s0, v66
	s_mov_b32 s0, 0x1e07000
	s_nop 0
	v_addc_co_u32_e32 v3, vcc, 0, v67, vcc
	v_add_co_u32_e32 v4, vcc, s0, v66
	s_mov_b32 s0, 0x1e0a000
	s_nop 0
	v_addc_co_u32_e32 v5, vcc, 0, v67, vcc
	global_load_dword v2, v[2:3], off nt
	s_nop 0
	global_load_dword v3, v[4:5], off offset:2048 nt
	v_add_co_u32_e32 v4, vcc, s0, v66
	s_mov_b32 s0, 0x1e0c000
	s_nop 0
	v_addc_co_u32_e32 v5, vcc, 0, v67, vcc
	v_add_co_u32_e32 v6, vcc, s0, v66
	s_mov_b32 s0, 0x1e0f000
	s_nop 0
	v_addc_co_u32_e32 v7, vcc, 0, v67, vcc
	global_load_dword v4, v[4:5], off nt
	s_nop 0
	global_load_dword v5, v[6:7], off offset:2048 nt
	v_add_co_u32_e32 v6, vcc, s0, v66
	s_mov_b32 s0, 0x1e11000
	s_nop 0
	v_addc_co_u32_e32 v7, vcc, 0, v67, vcc
	v_add_co_u32_e32 v8, vcc, s0, v66
	s_mov_b32 s0, 0x1e14000
	s_nop 0
	v_addc_co_u32_e32 v9, vcc, 0, v67, vcc
	global_load_dword v6, v[6:7], off nt
	s_nop 0
	global_load_dword v7, v[8:9], off offset:2048 nt
	v_add_co_u32_e32 v8, vcc, s0, v66
	s_mov_b32 s0, 0x1e16000
	s_nop 0
	v_addc_co_u32_e32 v9, vcc, 0, v67, vcc
	v_add_co_u32_e32 v10, vcc, s0, v66
	s_mov_b32 s0, 0x1e19000
	s_nop 0
	v_addc_co_u32_e32 v11, vcc, 0, v67, vcc
	global_load_dword v8, v[8:9], off nt
	s_nop 0
	global_load_dword v9, v[10:11], off offset:2048 nt
	v_add_co_u32_e32 v10, vcc, s0, v66
	s_mov_b32 s0, 0x1e1b000
	s_nop 0
	v_addc_co_u32_e32 v11, vcc, 0, v67, vcc
	v_add_co_u32_e32 v14, vcc, s0, v66
	s_mov_b32 s0, 0x1e1e000
	s_nop 0
	v_addc_co_u32_e32 v15, vcc, 0, v67, vcc
	global_load_dword v10, v[10:11], off nt
	s_nop 0
	global_load_dword v11, v[14:15], off offset:2048 nt
	v_add_co_u32_e32 v14, vcc, s0, v66
	s_mov_b32 s0, 0x1e20000
	s_nop 0
	v_addc_co_u32_e32 v15, vcc, 0, v67, vcc
	v_add_co_u32_e32 v16, vcc, s0, v66
	s_mov_b32 s0, 0x1e23000
	s_nop 0
	v_addc_co_u32_e32 v17, vcc, 0, v67, vcc
	global_load_dword v14, v[14:15], off nt
	s_nop 0
	global_load_dword v15, v[16:17], off offset:2048 nt
	v_add_co_u32_e32 v16, vcc, s0, v66
	s_mov_b32 s0, 0x1e25000
	s_nop 0
	v_addc_co_u32_e32 v17, vcc, 0, v67, vcc
	v_add_co_u32_e32 v18, vcc, s0, v66
	s_mov_b32 s0, 0x1e28000
	s_nop 0
	v_addc_co_u32_e32 v19, vcc, 0, v67, vcc
	global_load_dword v16, v[16:17], off nt
	s_nop 0
	global_load_dword v17, v[18:19], off offset:2048 nt
	v_add_co_u32_e32 v18, vcc, s0, v66
	s_mov_b32 s0, 0x1e2a000
	s_nop 0
	v_addc_co_u32_e32 v19, vcc, 0, v67, vcc
	v_add_co_u32_e32 v20, vcc, s0, v66
	s_mov_b32 s0, 0x1e2d000
	s_nop 0
	v_addc_co_u32_e32 v21, vcc, 0, v67, vcc
	global_load_dword v18, v[18:19], off nt
	s_nop 0
	global_load_dword v19, v[20:21], off offset:2048 nt
	v_add_co_u32_e32 v20, vcc, s0, v66
	s_mov_b32 s0, 0x1e2f000
	s_nop 0
	v_addc_co_u32_e32 v21, vcc, 0, v67, vcc
	v_add_co_u32_e32 v22, vcc, s0, v66
	s_mov_b32 s0, 0x1e32000
	s_nop 0
	v_addc_co_u32_e32 v23, vcc, 0, v67, vcc
	global_load_dword v20, v[20:21], off nt
	s_nop 0
	global_load_dword v21, v[22:23], off offset:2048 nt
	v_add_co_u32_e32 v22, vcc, s0, v66
	s_mov_b32 s0, 0x1e34000
	s_nop 0
	v_addc_co_u32_e32 v23, vcc, 0, v67, vcc
	v_add_co_u32_e32 v24, vcc, s0, v66
	s_mov_b32 s0, 0x1e37000
	s_nop 0
	v_addc_co_u32_e32 v25, vcc, 0, v67, vcc
	global_load_dword v22, v[22:23], off nt
	s_nop 0
	global_load_dword v23, v[24:25], off offset:2048 nt
	v_add_co_u32_e32 v24, vcc, s0, v66
	s_mov_b32 s0, 0x1e39000
	s_nop 0
	v_addc_co_u32_e32 v25, vcc, 0, v67, vcc
	v_add_co_u32_e32 v26, vcc, s0, v66
	s_mov_b32 s0, 0x1e3c000
	s_nop 0
	v_addc_co_u32_e32 v27, vcc, 0, v67, vcc
	global_load_dword v24, v[24:25], off nt
	s_nop 0
	global_load_dword v25, v[26:27], off offset:2048 nt
	v_add_co_u32_e32 v26, vcc, s0, v66
	s_mov_b32 s0, 0x1e3e000
	s_nop 0
	v_addc_co_u32_e32 v27, vcc, 0, v67, vcc
	v_add_co_u32_e32 v28, vcc, s0, v66
	s_mov_b32 s0, 0x1e41000
	s_nop 0
	v_addc_co_u32_e32 v29, vcc, 0, v67, vcc
	global_load_dword v26, v[26:27], off nt
	s_nop 0
	global_load_dword v27, v[28:29], off offset:2048 nt
	v_add_co_u32_e32 v28, vcc, s0, v66
	s_mov_b32 s0, 0x1e43000
	s_nop 0
	v_addc_co_u32_e32 v29, vcc, 0, v67, vcc
	v_add_co_u32_e32 v30, vcc, s0, v66
	s_mov_b32 s0, 0x1e46000
	s_nop 0
	v_addc_co_u32_e32 v31, vcc, 0, v67, vcc
	global_load_dword v28, v[28:29], off nt
	s_nop 0
	global_load_dword v29, v[30:31], off offset:2048 nt
	v_add_co_u32_e32 v30, vcc, s0, v66
	s_mov_b32 s0, 0x1e48000
	s_nop 0
	v_addc_co_u32_e32 v31, vcc, 0, v67, vcc
	v_add_co_u32_e32 v32, vcc, s0, v66
	s_mov_b32 s0, 0x1e4b000
	s_nop 0
	v_addc_co_u32_e32 v33, vcc, 0, v67, vcc
	global_load_dword v30, v[30:31], off nt
	s_nop 0
	global_load_dword v31, v[32:33], off offset:2048 nt
	v_add_co_u32_e32 v32, vcc, s0, v66
	s_mov_b32 s0, 0x1e4d000
	s_nop 0
	v_addc_co_u32_e32 v33, vcc, 0, v67, vcc
	v_add_co_u32_e32 v34, vcc, s0, v66
	s_mov_b32 s0, 0x1e50000
	s_nop 0
	v_addc_co_u32_e32 v35, vcc, 0, v67, vcc
	global_load_dword v32, v[32:33], off nt
	s_nop 0
	global_load_dword v33, v[34:35], off offset:2048 nt
	v_add_co_u32_e32 v34, vcc, s0, v66
; __device__ __forceinline__ void transpose_item(const float* __restrict__ W, int K, int N, bf16* __restrict__ WT, const float* __restrict__ ksc, int mode, int row_off, int item, int lane) {
;     ...
;     const float* src = W + (size_t)k0 * N + n;
;     float v[64];
; #pragma unroll
;     for (int i = 0; i < 64; ++i) v[i] = __builtin_nontemporal_load(src + (size_t)i * N);
	s_mov_b32 s0, 0x1e52000
	s_nop 0
	v_addc_co_u32_e32 v35, vcc, 0, v67, vcc
	v_add_co_u32_e32 v36, vcc, s0, v66
	s_mov_b32 s0, 0x1e55000
	s_nop 0
	v_addc_co_u32_e32 v37, vcc, 0, v67, vcc
	global_load_dword v34, v[34:35], off nt
	s_nop 0
	global_load_dword v35, v[36:37], off offset:2048 nt
	v_add_co_u32_e32 v36, vcc, s0, v66
	s_mov_b32 s0, 0x1e57000
	s_nop 0
	v_addc_co_u32_e32 v37, vcc, 0, v67, vcc
	v_add_co_u32_e32 v38, vcc, s0, v66
	s_mov_b32 s0, 0x1e5a000
	s_nop 0
	v_addc_co_u32_e32 v39, vcc, 0, v67, vcc
	global_load_dword v36, v[36:37], off nt
	s_nop 0
	global_load_dword v37, v[38:39], off offset:2048 nt
	v_add_co_u32_e32 v38, vcc, s0, v66
	s_mov_b32 s0, 0x1e5c000
	s_nop 0
	v_addc_co_u32_e32 v39, vcc, 0, v67, vcc
	v_add_co_u32_e32 v40, vcc, s0, v66
	s_mov_b32 s0, 0x1e5f000
	s_nop 0
	v_addc_co_u32_e32 v41, vcc, 0, v67, vcc
	global_load_dword v38, v[38:39], off nt
	s_nop 0
	global_load_dword v39, v[40:41], off offset:2048 nt
	v_add_co_u32_e32 v40, vcc, s0, v66
	s_mov_b32 s0, 0x1e61000
	s_nop 0
	v_addc_co_u32_e32 v41, vcc, 0, v67, vcc
	v_add_co_u32_e32 v42, vcc, s0, v66
	s_mov_b32 s0, 0x1e64000
	s_nop 0
	v_addc_co_u32_e32 v43, vcc, 0, v67, vcc
	global_load_dword v40, v[40:41], off nt
	s_nop 0
	global_load_dword v41, v[42:43], off offset:2048 nt
	v_add_co_u32_e32 v42, vcc, s0, v66
	s_mov_b32 s0, 0x1e66000
	s_nop 0
	v_addc_co_u32_e32 v43, vcc, 0, v67, vcc
	v_add_co_u32_e32 v44, vcc, s0, v66
	s_mov_b32 s0, 0x1e69000
	s_nop 0
	v_addc_co_u32_e32 v45, vcc, 0, v67, vcc
	global_load_dword v42, v[42:43], off nt
	s_nop 0
	global_load_dword v43, v[44:45], off offset:2048 nt
	v_add_co_u32_e32 v44, vcc, s0, v66
	s_mov_b32 s0, 0x1e6b000
	s_nop 0
	v_addc_co_u32_e32 v45, vcc, 0, v67, vcc
	v_add_co_u32_e32 v46, vcc, s0, v66
	s_mov_b32 s0, 0x1e6e000
	s_nop 0
	v_addc_co_u32_e32 v47, vcc, 0, v67, vcc
	global_load_dword v44, v[44:45], off nt
	s_nop 0
	global_load_dword v45, v[46:47], off offset:2048 nt
	v_add_co_u32_e32 v46, vcc, s0, v66
	s_mov_b32 s0, 0x1e70000
	s_nop 0
	v_addc_co_u32_e32 v47, vcc, 0, v67, vcc
	v_add_co_u32_e32 v48, vcc, s0, v66
	s_mov_b32 s0, 0x1e73000
	s_nop 0
	v_addc_co_u32_e32 v49, vcc, 0, v67, vcc
	global_load_dword v46, v[46:47], off nt
	s_nop 0
	global_load_dword v47, v[48:49], off offset:2048 nt
	v_add_co_u32_e32 v48, vcc, s0, v66
	s_mov_b32 s0, 0x1e75000
	s_nop 0
	v_addc_co_u32_e32 v49, vcc, 0, v67, vcc
	v_add_co_u32_e32 v50, vcc, s0, v66
	s_mov_b32 s0, 0x1e78000
	s_nop 0
	v_addc_co_u32_e32 v51, vcc, 0, v67, vcc
	global_load_dword v48, v[48:49], off nt
	s_nop 0
	global_load_dword v49, v[50:51], off offset:2048 nt
	v_add_co_u32_e32 v50, vcc, s0, v66
	s_mov_b32 s0, 0x1e7a000
	s_nop 0
	v_addc_co_u32_e32 v51, vcc, 0, v67, vcc
	v_add_co_u32_e32 v52, vcc, s0, v66
	s_mov_b32 s0, 0x1e7d000
	s_nop 0
	v_addc_co_u32_e32 v53, vcc, 0, v67, vcc
	global_load_dword v50, v[50:51], off nt
	s_nop 0
	global_load_dword v51, v[52:53], off offset:2048 nt
	v_add_co_u32_e32 v52, vcc, s0, v66
	s_mov_b32 s0, 0x1e7f000
	s_nop 0
	v_addc_co_u32_e32 v53, vcc, 0, v67, vcc
	v_add_co_u32_e32 v54, vcc, s0, v66
	s_mov_b32 s0, 0x1e82000
	s_nop 0
	v_addc_co_u32_e32 v55, vcc, 0, v67, vcc
	global_load_dword v52, v[52:53], off nt
	s_nop 0
	global_load_dword v53, v[54:55], off offset:2048 nt
	v_add_co_u32_e32 v54, vcc, s0, v66
	s_mov_b32 s0, 0x1e84000
	s_nop 0
	v_addc_co_u32_e32 v55, vcc, 0, v67, vcc
	v_add_co_u32_e32 v56, vcc, s0, v66
	s_mov_b32 s0, 0x1e87000
	s_nop 0
	v_addc_co_u32_e32 v57, vcc, 0, v67, vcc
	global_load_dword v54, v[54:55], off nt
	s_nop 0
	global_load_dword v55, v[56:57], off offset:2048 nt
	v_add_co_u32_e32 v56, vcc, s0, v66
	s_mov_b32 s0, 0x1e89000
	s_nop 0
	v_addc_co_u32_e32 v57, vcc, 0, v67, vcc
	v_add_co_u32_e32 v58, vcc, s0, v66
	s_mov_b32 s0, 0x1e8c000
	s_nop 0
	v_addc_co_u32_e32 v59, vcc, 0, v67, vcc
	global_load_dword v56, v[56:57], off nt
	s_nop 0
	global_load_dword v57, v[58:59], off offset:2048 nt
	v_add_co_u32_e32 v58, vcc, s0, v66
	s_mov_b32 s0, 0x1e8e000
	s_nop 0
	v_addc_co_u32_e32 v59, vcc, 0, v67, vcc
	v_add_co_u32_e32 v60, vcc, s0, v66
	s_mov_b32 s0, 0x1e91000
	s_nop 0
	v_addc_co_u32_e32 v61, vcc, 0, v67, vcc
	global_load_dword v58, v[58:59], off nt
	s_nop 0
	global_load_dword v59, v[60:61], off offset:2048 nt
	v_add_co_u32_e32 v60, vcc, s0, v66
	s_mov_b32 s0, 0x1e93000
	s_nop 0
	v_addc_co_u32_e32 v61, vcc, 0, v67, vcc
	v_add_co_u32_e32 v62, vcc, s0, v66
	s_mov_b32 s0, 0x1e96000
	s_nop 0
	v_addc_co_u32_e32 v63, vcc, 0, v67, vcc
	global_load_dword v60, v[60:61], off nt
	s_nop 0
	global_load_dword v61, v[62:63], off offset:2048 nt
	v_add_co_u32_e32 v62, vcc, s0, v66
	s_mov_b32 s0, 0x1e98000
	s_nop 0
	v_addc_co_u32_e32 v63, vcc, 0, v67, vcc
	v_add_co_u32_e32 v64, vcc, s0, v66
	global_load_dword v62, v[62:63], off nt
	s_nop 0
	v_addc_co_u32_e32 v65, vcc, 0, v67, vcc
	global_load_dword v63, v[64:65], off offset:2048 nt
	v_add_co_u32_e32 v64, vcc, s50, v66
	s_nop 1
	v_addc_co_u32_e32 v65, vcc, 0, v67, vcc
	v_add_co_u32_e32 v66, vcc, s51, v66
	global_load_dword v64, v[64:65], off nt
	s_nop 0
	v_addc_co_u32_e32 v67, vcc, 0, v67, vcc
	global_load_dword v65, v[66:67], off offset:2048 nt
	s_cbranch_scc1 .Lcx5_1155
; __device__ __forceinline__ void transpose_item(const float* __restrict__ W, int K, int N, bf16* __restrict__ WT, const float* __restrict__ ksc, int mode, int row_off, int item, int lane) {
;     ...
;     if (ksc) {
; #pragma unroll
;         for (int i = 0; i < 64; ++i) v[i] *= ksc[k0 + i];
;     }
	s_lshl_b64 s[18:19], s[46:47], 2
	s_add_u32 s18, s16, s18
	s_addc_u32 s19, s17, s19
	s_add_u32 s16, s18, 0x3000
	s_addc_u32 s17, s19, 0
	global_load_dwordx4 v[66:69], v13, s[16:17] offset:48
	global_load_dwordx4 v[70:73], v13, s[16:17] offset:32
	global_load_dwordx4 v[74:77], v13, s[16:17] offset:16
	global_load_dwordx4 v[86:89], v83, s[18:19]
	global_load_dwordx4 v[184:187], v13, s[16:17] offset:112
	global_load_dwordx4 v[188:191], v13, s[16:17] offset:96
	global_load_dwordx4 v[192:195], v13, s[16:17] offset:80
	global_load_dwordx4 v[196:199], v13, s[16:17] offset:64
	global_load_dwordx4 v[204:207], v13, s[16:17] offset:176
	global_load_dwordx4 v[208:211], v13, s[16:17] offset:160
	global_load_dwordx4 v[212:215], v13, s[16:17] offset:144
	global_load_dwordx4 v[216:219], v13, s[16:17] offset:128
	global_load_dwordx4 v[220:223], v13, s[16:17] offset:240
	global_load_dwordx4 v[224:227], v13, s[16:17] offset:224
	global_load_dwordx4 v[228:231], v13, s[16:17] offset:208
	global_load_dwordx4 v[232:235], v13, s[16:17] offset:192
	s_waitcnt vmcnt(0)
	v_pk_mul_f32 v[14:15], v[14:15], v[66:67]
	s_waitcnt vmcnt(2)
	v_pk_mul_f32 v[8:9], v[8:9], v[70:71]
	s_waitcnt vmcnt(1)
	v_pk_mul_f32 v[4:5], v[4:5], v[74:75]
	s_waitcnt vmcnt(0)
	v_pk_mul_f32 v[0:1], v[0:1], v[86:87]
	v_pk_mul_f32 v[2:3], v[2:3], v[88:89]
	v_pk_mul_f32 v[6:7], v[6:7], v[76:77]
	v_pk_mul_f32 v[10:11], v[10:11], v[72:73]
	v_pk_mul_f32 v[16:17], v[16:17], v[68:69]
	v_mov_b32_e32 v66, v184
	v_mov_b32_e32 v67, v185
	v_mov_b32_e32 v68, v186
	v_mov_b32_e32 v69, v187
	v_mov_b32_e32 v70, v188
	v_mov_b32_e32 v71, v189
	v_mov_b32_e32 v72, v190
	v_mov_b32_e32 v73, v191
	v_mov_b32_e32 v74, v192
	v_mov_b32_e32 v75, v193
	v_mov_b32_e32 v76, v194
	v_mov_b32_e32 v77, v195
	v_mov_b32_e32 v86, v196
	v_mov_b32_e32 v87, v197
	v_mov_b32_e32 v88, v198
	v_mov_b32_e32 v89, v199
	s_waitcnt vmcnt(3)
	v_pk_mul_f32 v[30:31], v[30:31], v[66:67]
	s_waitcnt vmcnt(2)
	v_pk_mul_f32 v[26:27], v[26:27], v[70:71]
	s_waitcnt vmcnt(1)
	v_pk_mul_f32 v[22:23], v[22:23], v[74:75]
	s_waitcnt vmcnt(0)
	v_pk_mul_f32 v[18:19], v[18:19], v[86:87]
	v_pk_mul_f32 v[20:21], v[20:21], v[88:89]
	v_pk_mul_f32 v[24:25], v[24:25], v[76:77]
	v_pk_mul_f32 v[28:29], v[28:29], v[72:73]
	v_pk_mul_f32 v[32:33], v[32:33], v[68:69]
	v_mov_b32_e32 v66, v204
	v_mov_b32_e32 v67, v205
	v_mov_b32_e32 v68, v206
	v_mov_b32_e32 v69, v207
	v_mov_b32_e32 v70, v208
	v_mov_b32_e32 v71, v209
	v_mov_b32_e32 v72, v210
	v_mov_b32_e32 v73, v211
	v_mov_b32_e32 v74, v212
	v_mov_b32_e32 v75, v213
	v_mov_b32_e32 v76, v214
	v_mov_b32_e32 v77, v215
	v_mov_b32_e32 v86, v216
	v_mov_b32_e32 v87, v217
	v_mov_b32_e32 v88, v218
	v_mov_b32_e32 v89, v219
	s_waitcnt vmcnt(3)
	v_pk_mul_f32 v[46:47], v[46:47], v[66:67]
	s_waitcnt vmcnt(2)
	v_pk_mul_f32 v[42:43], v[42:43], v[70:71]
	s_waitcnt vmcnt(1)
	v_pk_mul_f32 v[38:39], v[38:39], v[74:75]
	s_waitcnt vmcnt(0)
	v_pk_mul_f32 v[34:35], v[34:35], v[86:87]
	v_pk_mul_f32 v[36:37], v[36:37], v[88:89]
	v_pk_mul_f32 v[40:41], v[40:41], v[76:77]
	v_pk_mul_f32 v[44:45], v[44:45], v[72:73]
	v_pk_mul_f32 v[48:49], v[48:49], v[68:69]
	v_mov_b32_e32 v66, v220
	v_mov_b32_e32 v67, v221
	v_mov_b32_e32 v68, v222
	v_mov_b32_e32 v69, v223
	v_mov_b32_e32 v70, v224
	v_mov_b32_e32 v71, v225
	v_mov_b32_e32 v72, v226
	v_mov_b32_e32 v73, v227
	v_mov_b32_e32 v74, v228
	v_mov_b32_e32 v75, v229
	v_mov_b32_e32 v76, v230
	v_mov_b32_e32 v77, v231
	v_mov_b32_e32 v86, v232
	v_mov_b32_e32 v87, v233
	v_mov_b32_e32 v88, v234
	v_mov_b32_e32 v89, v235
	s_waitcnt vmcnt(3)
	v_pk_mul_f32 v[62:63], v[62:63], v[66:67]
	s_waitcnt vmcnt(2)
	v_pk_mul_f32 v[58:59], v[58:59], v[70:71]
	s_waitcnt vmcnt(1)
	v_pk_mul_f32 v[54:55], v[54:55], v[74:75]
	s_waitcnt vmcnt(0)
	v_pk_mul_f32 v[50:51], v[50:51], v[86:87]
	v_pk_mul_f32 v[52:53], v[52:53], v[88:89]
	v_pk_mul_f32 v[56:57], v[56:57], v[76:77]
	v_pk_mul_f32 v[60:61], v[60:61], v[72:73]
	v_pk_mul_f32 v[64:65], v[64:65], v[68:69]
	s_branch .Lcx5_1155
